# stack: scan LDS reads double-buffered one group ahead + sgemm_resid u=1 loads hoisted/counted waits + EpiSwiglu ss rows prefetched
# speedup vs baseline: 1.0121x; 1.0121x over previous
; #define EPI_LOOP_ROWS for (int am_ = 0; am_ < 8; ++am_)
; __device__ __forceinline__ float ss_rstd(const float* ssrow) { const f32x4 a = *(const f32x4*)ssrow, b = *(const f32x4*)(ssrow + 4), c = *(const f32x4*)(ssrow + 8), d = *(const f32x4*)(ssrow + 12);
;     const float s = ((a[0] + a[1]) + (a[2] + a[3])) + ((b[0] + b[1]) + (b[2] + b[3])) + ((c[0] + c[1]) + (c[2] + c[3])) + ((d[0] + d[1]) + (d[2] + d[3])); return rsqrtf(s * (1.f / D) + 1e-6f); }
;     __device__ __forceinline__ void operator()(const f32x4 (&acc)[2][2][4][2], const pg8::Unit& u, int wr, int wc, int fr, int fq) const { asm volatile("" : "+v"(fr), "+v"(fq));
;     ...
;         EPI_LOOP_ROWS { EPI_AM const int row = u.pm * 256 + ai * 128 + wr * 64 + m * 16 + fr; const float rstd = ss_rstd(ss + (size_t)row * 16);
; #pragma unroll
;             for (int bj = 0; bj < 2; ++bj) { const int col0 = u.pn * 256 + bj * 128 + wc * 32 + 8 * fq; const f32x4 g = acc[ai][bj][m][0] * rstd, up = acc[ai][bj][m][1] * rstd; f32x4 o;
.LBB0_191:
	v_mov_b32_e32 v139, v148
	v_mov_b32_e32 v142, v149
	s_lshl_b32 s33, s33, 8
	s_add_i32 s33, s33, s71
	v_add_u32_e32 v142, s33, v142
	v_ashrrev_i32_e32 v143, 31, v142
	s_lshl_b32 s33, s80, 8
	s_or_b32 s33, s33, s74
	v_lshl_add_u32 v139, v139, 3, s33
	v_lshlrev_b64 v[228:229], 6, v[142:143]
	v_lshl_add_u64 v[228:229], s[16:17], 0, v[228:229]
	v_add_co_u32_e32 v172, vcc, 0x2000, v228
	s_nop 1
	v_addc_co_u32_e32 v173, vcc, 0, v229, vcc
	global_load_dwordx4 v[176:179], v[228:229], off offset:0
	global_load_dwordx4 v[180:183], v[228:229], off offset:16
	global_load_dwordx4 v[184:187], v[228:229], off offset:32
	global_load_dwordx4 v[188:191], v[228:229], off offset:48
	global_load_dwordx4 v[192:195], v[228:229], off offset:1024
	global_load_dwordx4 v[196:199], v[228:229], off offset:1040
	global_load_dwordx4 v[200:203], v[228:229], off offset:1056
	global_load_dwordx4 v[204:207], v[228:229], off offset:1072
	global_load_dwordx4 v[208:211], v[228:229], off offset:2048
	global_load_dwordx4 v[212:215], v[228:229], off offset:2064
	global_load_dwordx4 v[216:219], v[228:229], off offset:2080
	global_load_dwordx4 v[220:223], v[228:229], off offset:2096
	global_load_dwordx4 v[224:227], v[228:229], off offset:3072
	global_load_dwordx4 v[234:237], v[228:229], off offset:3088
	global_load_dwordx4 v[238:241], v[228:229], off offset:3104
	global_load_dwordx4 v[242:245], v[228:229], off offset:3120
	s_waitcnt vmcnt(12)
	v_add_f32_e32 v176, v176, v177
	v_add_f32_e32 v178, v178, v179
	v_add_f32_e32 v180, v180, v181
	v_add_f32_e32 v182, v182, v183
	v_add_f32_e32 v184, v184, v185
	v_add_f32_e32 v186, v186, v187
	v_add_f32_e32 v188, v188, v189
	v_add_f32_e32 v190, v190, v191
	v_add_f32_e32 v176, v176, v178
	v_add_f32_e32 v180, v180, v182
	v_add_f32_e32 v184, v184, v186
	v_add_f32_e32 v188, v188, v190
	v_add_f32_e32 v176, v176, v180
	v_add_f32_e32 v176, v176, v184
	v_add_f32_e32 v176, v176, v188
	v_fmamk_f32 v176, v176, 0x3a800000, v138
	v_cmp_gt_f32_e32 vcc, s64, v176
	v_mul_f32_e32 v174, 0x4b800000, v176
	s_nop 0
	v_cndmask_b32_e32 v176, v176, v174, vcc
	v_rsq_f32_e32 v176, v176
	s_nop 0
	v_mul_f32_e32 v174, 0x45800000, v176
	v_cndmask_b32_e32 v246, v176, v174, vcc
	global_load_dwordx4 v[176:179], v[172:173], off offset:0
	global_load_dwordx4 v[180:183], v[172:173], off offset:16
	global_load_dwordx4 v[184:187], v[172:173], off offset:32
	global_load_dwordx4 v[188:191], v[172:173], off offset:48
	s_waitcnt vmcnt(12)
	v_add_f32_e32 v192, v192, v193
	v_add_f32_e32 v194, v194, v195
	v_add_f32_e32 v196, v196, v197
	v_add_f32_e32 v198, v198, v199
	v_add_f32_e32 v200, v200, v201
	v_add_f32_e32 v202, v202, v203
	v_add_f32_e32 v204, v204, v205
	v_add_f32_e32 v206, v206, v207
	v_add_f32_e32 v192, v192, v194
	v_add_f32_e32 v196, v196, v198
	v_add_f32_e32 v200, v200, v202
	v_add_f32_e32 v204, v204, v206
	v_add_f32_e32 v192, v192, v196
	v_add_f32_e32 v192, v192, v200
	v_add_f32_e32 v192, v192, v204
	v_fmamk_f32 v192, v192, 0x3a800000, v138
	v_cmp_gt_f32_e32 vcc, s64, v192
	v_mul_f32_e32 v174, 0x4b800000, v192
	s_nop 0
	v_cndmask_b32_e32 v192, v192, v174, vcc
	v_rsq_f32_e32 v192, v192
	s_nop 0
	v_mul_f32_e32 v174, 0x45800000, v192
	v_cndmask_b32_e32 v247, v192, v174, vcc
	global_load_dwordx4 v[192:195], v[172:173], off offset:1024
	global_load_dwordx4 v[196:199], v[172:173], off offset:1040
	global_load_dwordx4 v[200:203], v[172:173], off offset:1056
	global_load_dwordx4 v[204:207], v[172:173], off offset:1072
	s_waitcnt vmcnt(12)
	v_add_f32_e32 v208, v208, v209
	v_add_f32_e32 v210, v210, v211
	v_add_f32_e32 v212, v212, v213
	v_add_f32_e32 v214, v214, v215
	v_add_f32_e32 v216, v216, v217
	v_add_f32_e32 v218, v218, v219
	v_add_f32_e32 v220, v220, v221
	v_add_f32_e32 v222, v222, v223
	v_add_f32_e32 v208, v208, v210
	v_add_f32_e32 v212, v212, v214
	v_add_f32_e32 v216, v216, v218
	v_add_f32_e32 v220, v220, v222
	v_add_f32_e32 v208, v208, v212
	v_add_f32_e32 v208, v208, v216
	v_add_f32_e32 v208, v208, v220
	v_fmamk_f32 v208, v208, 0x3a800000, v138
	v_cmp_gt_f32_e32 vcc, s64, v208
	v_mul_f32_e32 v174, 0x4b800000, v208
	s_nop 0
	v_cndmask_b32_e32 v208, v208, v174, vcc
	v_rsq_f32_e32 v208, v208
	s_nop 0
	v_mul_f32_e32 v174, 0x45800000, v208
	v_cndmask_b32_e32 v248, v208, v174, vcc
	global_load_dwordx4 v[208:211], v[172:173], off offset:2048
	global_load_dwordx4 v[212:215], v[172:173], off offset:2064
	global_load_dwordx4 v[216:219], v[172:173], off offset:2080
	global_load_dwordx4 v[220:223], v[172:173], off offset:2096
	s_waitcnt vmcnt(12)
	v_add_f32_e32 v224, v224, v225
	v_add_f32_e32 v226, v226, v227
	v_add_f32_e32 v234, v234, v235
	v_add_f32_e32 v236, v236, v237
	v_add_f32_e32 v238, v238, v239
	v_add_f32_e32 v240, v240, v241
	v_add_f32_e32 v242, v242, v243
	v_add_f32_e32 v244, v244, v245
	v_add_f32_e32 v224, v224, v226
	v_add_f32_e32 v234, v234, v236
	v_add_f32_e32 v238, v238, v240
	v_add_f32_e32 v242, v242, v244
	v_add_f32_e32 v224, v224, v234
	v_add_f32_e32 v224, v224, v238
	v_add_f32_e32 v224, v224, v242
	v_fmamk_f32 v224, v224, 0x3a800000, v138
	v_cmp_gt_f32_e32 vcc, s64, v224
	v_mul_f32_e32 v174, 0x4b800000, v224
	s_nop 0
	v_cndmask_b32_e32 v224, v224, v174, vcc
	v_rsq_f32_e32 v224, v224
	s_nop 0
	v_mul_f32_e32 v174, 0x45800000, v224
	v_cndmask_b32_e32 v249, v224, v174, vcc
	global_load_dwordx4 v[224:227], v[172:173], off offset:3072
	global_load_dwordx4 v[234:237], v[172:173], off offset:3088
	global_load_dwordx4 v[238:241], v[172:173], off offset:3104
	global_load_dwordx4 v[242:245], v[172:173], off offset:3120
	s_waitcnt vmcnt(12)
; __device__ __forceinline__ float sigmoidf_(float x) { return __builtin_amdgcn_rcpf(1.f + __expf(-x)); }
; __device__ __forceinline__ u32x2 pack4(const f32x4& a) { u32x2 w; w.x = pk2(a[0], a[1]); w.y = pk2(a[2], a[3]); return w; }
; #define EPI_LOOP_ROWS for (int am_ = 0; am_ < 8; ++am_)
; __device__ __forceinline__ float ss_rstd(const float* ssrow) { const f32x4 a = *(const f32x4*)ssrow, b = *(const f32x4*)(ssrow + 4), c = *(const f32x4*)(ssrow + 8), d = *(const f32x4*)(ssrow + 12);
;     const float s = ((a[0] + a[1]) + (a[2] + a[3])) + ((b[0] + b[1]) + (b[2] + b[3])) + ((c[0] + c[1]) + (c[2] + c[3])) + ((d[0] + d[1]) + (d[2] + d[3])); return rsqrtf(s * (1.f / D) + 1e-6f); }
;     __device__ __forceinline__ void operator()(const f32x4 (&acc)[2][2][4][2], const pg8::Unit& u, int wr, int wc, int fr, int fq) const { asm volatile("" : "+v"(fr), "+v"(fq));
;     ...
;         EPI_LOOP_ROWS { EPI_AM const int row = u.pm * 256 + ai * 128 + wr * 64 + m * 16 + fr; const float rstd = ss_rstd(ss + (size_t)row * 16);
; #pragma unroll
;             for (int bj = 0; bj < 2; ++bj) { const int col0 = u.pn * 256 + bj * 128 + wc * 32 + 8 * fq; const f32x4 g = acc[ai][bj][m][0] * rstd, up = acc[ai][bj][m][1] * rstd; f32x4 o;
; #pragma unroll
;                 for (int j = 0; j < 4; ++j) o[j] = g[j] * sigmoidf_(g[j]) * up[j];
;                 *(u32x2*)(act + (size_t)row * FF + (col0 >> 1)) = pack4(o); } }
	v_add_f32_e32 v176, v176, v177
	v_add_f32_e32 v178, v178, v179
	v_add_f32_e32 v180, v180, v181
	v_add_f32_e32 v182, v182, v183
	v_add_f32_e32 v184, v184, v185
	v_add_f32_e32 v186, v186, v187
	v_add_f32_e32 v188, v188, v189
	v_add_f32_e32 v190, v190, v191
	v_add_f32_e32 v176, v176, v178
	v_add_f32_e32 v180, v180, v182
	v_add_f32_e32 v184, v184, v186
	v_add_f32_e32 v188, v188, v190
	v_add_f32_e32 v176, v176, v180
	v_add_f32_e32 v176, v176, v184
	v_add_f32_e32 v176, v176, v188
	v_fmamk_f32 v176, v176, 0x3a800000, v138
	v_cmp_gt_f32_e32 vcc, s64, v176
	v_mul_f32_e32 v174, 0x4b800000, v176
	s_nop 0
	v_cndmask_b32_e32 v176, v176, v174, vcc
	v_rsq_f32_e32 v176, v176
	s_nop 0
	v_mul_f32_e32 v174, 0x45800000, v176
	v_cndmask_b32_e32 v250, v176, v174, vcc
	s_waitcnt vmcnt(8)
	v_add_f32_e32 v192, v192, v193
	v_add_f32_e32 v194, v194, v195
	v_add_f32_e32 v196, v196, v197
	v_add_f32_e32 v198, v198, v199
	v_add_f32_e32 v200, v200, v201
	v_add_f32_e32 v202, v202, v203
	v_add_f32_e32 v204, v204, v205
	v_add_f32_e32 v206, v206, v207
	v_add_f32_e32 v192, v192, v194
	v_add_f32_e32 v196, v196, v198
	v_add_f32_e32 v200, v200, v202
	v_add_f32_e32 v204, v204, v206
	v_add_f32_e32 v192, v192, v196
	v_add_f32_e32 v192, v192, v200
	v_add_f32_e32 v192, v192, v204
	v_fmamk_f32 v192, v192, 0x3a800000, v138
	v_cmp_gt_f32_e32 vcc, s64, v192
	v_mul_f32_e32 v174, 0x4b800000, v192
	s_nop 0
	v_cndmask_b32_e32 v192, v192, v174, vcc
	v_rsq_f32_e32 v192, v192
	s_nop 0
	v_mul_f32_e32 v174, 0x45800000, v192
	v_cndmask_b32_e32 v251, v192, v174, vcc
	s_waitcnt vmcnt(4)
	v_add_f32_e32 v208, v208, v209
	v_add_f32_e32 v210, v210, v211
	v_add_f32_e32 v212, v212, v213
	v_add_f32_e32 v214, v214, v215
	v_add_f32_e32 v216, v216, v217
	v_add_f32_e32 v218, v218, v219
	v_add_f32_e32 v220, v220, v221
	v_add_f32_e32 v222, v222, v223
	v_add_f32_e32 v208, v208, v210
	v_add_f32_e32 v212, v212, v214
	v_add_f32_e32 v216, v216, v218
	v_add_f32_e32 v220, v220, v222
	v_add_f32_e32 v208, v208, v212
	v_add_f32_e32 v208, v208, v216
	v_add_f32_e32 v208, v208, v220
	v_fmamk_f32 v208, v208, 0x3a800000, v138
	v_cmp_gt_f32_e32 vcc, s64, v208
	v_mul_f32_e32 v174, 0x4b800000, v208
	s_nop 0
	v_cndmask_b32_e32 v208, v208, v174, vcc
	v_rsq_f32_e32 v208, v208
	s_nop 0
	v_mul_f32_e32 v174, 0x45800000, v208
	v_cndmask_b32_e32 v252, v208, v174, vcc
	s_waitcnt vmcnt(0)
	v_add_f32_e32 v224, v224, v225
	v_add_f32_e32 v226, v226, v227
	v_add_f32_e32 v234, v234, v235
	v_add_f32_e32 v236, v236, v237
	v_add_f32_e32 v238, v238, v239
	v_add_f32_e32 v240, v240, v241
	v_add_f32_e32 v242, v242, v243
	v_add_f32_e32 v244, v244, v245
	v_add_f32_e32 v224, v224, v226
	v_add_f32_e32 v234, v234, v236
	v_add_f32_e32 v238, v238, v240
	v_add_f32_e32 v242, v242, v244
	v_add_f32_e32 v224, v224, v234
	v_add_f32_e32 v224, v224, v238
	v_add_f32_e32 v224, v224, v242
	v_fmamk_f32 v224, v224, 0x3a800000, v138
	v_cmp_gt_f32_e32 vcc, s64, v224
	v_mul_f32_e32 v174, 0x4b800000, v224
	s_nop 0
	v_cndmask_b32_e32 v224, v224, v174, vcc
	v_rsq_f32_e32 v224, v224
	s_nop 0
	v_mul_f32_e32 v174, 0x45800000, v224
	v_cndmask_b32_e32 v253, v224, v174, vcc
	v_mov_b32_e32 v144, v246
	v_pk_mul_f32 v[124:125], v[124:125], v[144:145] op_sel_hi:[1,0]
	v_pk_mul_f32 v[120:121], v[120:121], v[144:145] op_sel_hi:[1,0]
	v_mul_f32_e32 v143, 0xbfb8aa3b, v124
	v_exp_f32_e32 v143, v143
	v_pk_mul_f32 v[122:123], v[122:123], v[144:145] op_sel_hi:[1,0]
	v_pk_mul_f32 v[116:117], v[116:117], v[144:145] op_sel_hi:[1,0]
	v_pk_mul_f32 v[112:113], v[112:113], v[144:145] op_sel_hi:[1,0]
	v_add_f32_e32 v143, 1.0, v143
	v_rcp_f32_e32 v146, v143
	v_mul_f32_e32 v143, 0xbfb8aa3b, v125
	v_exp_f32_e32 v143, v143
	v_pk_mul_f32 v[114:115], v[114:115], v[144:145] op_sel_hi:[1,0]
	v_add_f32_e32 v143, 1.0, v143
	v_rcp_f32_e32 v147, v143
	s_nop 0
	v_pk_mul_f32 v[124:125], v[124:125], v[146:147]
	s_nop 0
	v_pk_mul_f32 v[120:121], v[120:121], v[124:125]
	v_pk_mul_f32 v[124:125], v[126:127], v[144:145] op_sel_hi:[1,0]
	v_cvt_pk_bf16_f32 v120, v120, v121
	v_mul_f32_e32 v126, 0xbfb8aa3b, v124
	v_mul_f32_e32 v127, 0xbfb8aa3b, v125
	v_exp_f32_e32 v126, v126
	v_exp_f32_e32 v127, v127
	v_add_f32_e32 v126, 1.0, v126
	v_add_f32_e32 v127, 1.0, v127
	v_rcp_f32_e32 v126, v126
	v_rcp_f32_e32 v127, v127
	s_nop 0
	v_pk_mul_f32 v[124:125], v[124:125], v[126:127]
	v_ashrrev_i32_e32 v126, 1, v139
	v_pk_mul_f32 v[122:123], v[122:123], v[124:125]
	v_mov_b64_e32 v[124:125], s[88:89]
	v_ashrrev_i32_e32 v127, 31, v126
	v_cvt_pk_bf16_f32 v121, v122, v123
	v_mad_i64_i32 v[122:123], s[38:39], v142, s59, v[124:125]
	v_lshlrev_b64 v[126:127], 1, v[126:127]
	v_lshl_add_u64 v[146:147], v[122:123], 0, v[126:127]
	global_store_dwordx2 v[146:147], v[120:121], off
	v_mul_f32_e32 v120, 0xbfb8aa3b, v116
	v_mul_f32_e32 v121, 0xbfb8aa3b, v117
	v_exp_f32_e32 v120, v120
	v_exp_f32_e32 v121, v121
	v_add_u32_e32 v146, 16, v142
	v_ashrrev_i32_e32 v147, 31, v146
	v_add_f32_e32 v120, 1.0, v120
	v_add_f32_e32 v121, 1.0, v121
	v_rcp_f32_e32 v120, v120
	v_rcp_f32_e32 v121, v121
	s_nop 0
	v_pk_mul_f32 v[116:117], v[116:117], v[120:121]
	s_nop 0
	v_pk_mul_f32 v[112:113], v[112:113], v[116:117]
	v_pk_mul_f32 v[116:117], v[118:119], v[144:145] op_sel_hi:[1,0]
	v_cvt_pk_bf16_f32 v112, v112, v113
	v_mul_f32_e32 v118, 0xbfb8aa3b, v116
	v_mul_f32_e32 v119, 0xbfb8aa3b, v117
	v_exp_f32_e32 v118, v118
	v_exp_f32_e32 v119, v119
	v_add_f32_e32 v118, 1.0, v118
	v_add_f32_e32 v119, 1.0, v119
	v_rcp_f32_e32 v118, v118
	v_rcp_f32_e32 v119, v119
	s_nop 0
	v_pk_mul_f32 v[116:117], v[116:117], v[118:119]
	s_nop 0
	v_pk_mul_f32 v[114:115], v[114:115], v[116:117]
	v_add_u32_e32 v116, 0x80, v139
	v_cvt_pk_bf16_f32 v113, v114, v115
	v_ashrrev_i32_e32 v114, 1, v116
; __device__ __forceinline__ float sigmoidf_(float x) { return __builtin_amdgcn_rcpf(1.f + __expf(-x)); }
; __device__ __forceinline__ u32x2 pack4(const f32x4& a) { u32x2 w; w.x = pk2(a[0], a[1]); w.y = pk2(a[2], a[3]); return w; }
; #define EPI_LOOP_ROWS for (int am_ = 0; am_ < 8; ++am_)
;     __device__ __forceinline__ void operator()(const f32x4 (&acc)[2][2][4][2], const pg8::Unit& u, int wr, int wc, int fr, int fq) const { asm volatile("" : "+v"(fr), "+v"(fq));
;     ...
;         EPI_LOOP_ROWS { EPI_AM const int row = u.pm * 256 + ai * 128 + wr * 64 + m * 16 + fr; const float rstd = ss_rstd(ss + (size_t)row * 16);
; #pragma unroll
;             for (int bj = 0; bj < 2; ++bj) { const int col0 = u.pn * 256 + bj * 128 + wc * 32 + 8 * fq; const f32x4 g = acc[ai][bj][m][0] * rstd, up = acc[ai][bj][m][1] * rstd; f32x4 o;
; #pragma unroll
;                 for (int j = 0; j < 4; ++j) o[j] = g[j] * sigmoidf_(g[j]) * up[j];
;                 *(u32x2*)(act + (size_t)row * FF + (col0 >> 1)) = pack4(o); } }
	v_ashrrev_i32_e32 v115, 31, v114
	v_lshlrev_b64 v[144:145], 1, v[114:115]
	v_lshl_add_u64 v[114:115], v[122:123], 0, v[144:145]
	global_store_dwordx2 v[114:115], v[112:113], off
	v_mov_b32_e32 v112, v247
	v_pk_mul_f32 v[108:109], v[108:109], v[112:113] op_sel_hi:[1,0]
	s_nop 0
	v_mul_f32_e32 v113, 0xbfb8aa3b, v108
	v_exp_f32_e32 v113, v113
	s_nop 0
	v_add_f32_e32 v113, 1.0, v113
	v_rcp_f32_e32 v114, v113
	v_mul_f32_e32 v113, 0xbfb8aa3b, v109
	v_exp_f32_e32 v113, v113
	s_nop 0
	v_add_f32_e32 v113, 1.0, v113
	v_rcp_f32_e32 v115, v113
	v_pk_mul_f32 v[104:105], v[104:105], v[112:113] op_sel_hi:[1,0]
	v_pk_mul_f32 v[106:107], v[106:107], v[112:113] op_sel_hi:[1,0]
	v_pk_mul_f32 v[100:101], v[100:101], v[112:113] op_sel_hi:[1,0]
	v_pk_mul_f32 v[108:109], v[108:109], v[114:115]
	v_pk_mul_f32 v[96:97], v[96:97], v[112:113] op_sel_hi:[1,0]
	v_pk_mul_f32 v[104:105], v[104:105], v[108:109]
	v_pk_mul_f32 v[108:109], v[110:111], v[112:113] op_sel_hi:[1,0]
	v_cvt_pk_bf16_f32 v104, v104, v105
	v_mul_f32_e32 v110, 0xbfb8aa3b, v108
	v_mul_f32_e32 v111, 0xbfb8aa3b, v109
	v_exp_f32_e32 v110, v110
	v_exp_f32_e32 v111, v111
	v_pk_mul_f32 v[98:99], v[98:99], v[112:113] op_sel_hi:[1,0]
	v_add_f32_e32 v110, 1.0, v110
	v_add_f32_e32 v111, 1.0, v111
	v_rcp_f32_e32 v110, v110
	v_rcp_f32_e32 v111, v111
	s_nop 0
	v_pk_mul_f32 v[108:109], v[108:109], v[110:111]
	s_nop 0
	v_pk_mul_f32 v[106:107], v[106:107], v[108:109]
	s_nop 0
	v_cvt_pk_bf16_f32 v105, v106, v107
	v_mad_i64_i32 v[106:107], s[38:39], v146, s59, v[124:125]
	v_lshl_add_u64 v[108:109], v[106:107], 0, v[126:127]
	global_store_dwordx2 v[108:109], v[104:105], off
	v_mul_f32_e32 v104, 0xbfb8aa3b, v100
	v_mul_f32_e32 v105, 0xbfb8aa3b, v101
	v_exp_f32_e32 v104, v104
	v_exp_f32_e32 v105, v105
	v_add_u32_e32 v108, 32, v142
	v_ashrrev_i32_e32 v109, 31, v108
	v_add_f32_e32 v104, 1.0, v104
	v_add_f32_e32 v105, 1.0, v105
	v_rcp_f32_e32 v104, v104
	v_rcp_f32_e32 v105, v105
	s_nop 0
	v_pk_mul_f32 v[100:101], v[100:101], v[104:105]
	s_nop 0
	v_pk_mul_f32 v[96:97], v[96:97], v[100:101]
	v_pk_mul_f32 v[100:101], v[102:103], v[112:113] op_sel_hi:[1,0]
	v_cvt_pk_bf16_f32 v96, v96, v97
	v_mul_f32_e32 v102, 0xbfb8aa3b, v100
	v_mul_f32_e32 v103, 0xbfb8aa3b, v101
	v_exp_f32_e32 v102, v102
	v_exp_f32_e32 v103, v103
	v_add_f32_e32 v102, 1.0, v102
	v_add_f32_e32 v103, 1.0, v103
	v_rcp_f32_e32 v102, v102
	v_rcp_f32_e32 v103, v103
	s_nop 0
	v_pk_mul_f32 v[100:101], v[100:101], v[102:103]
	s_nop 0
	v_pk_mul_f32 v[98:99], v[98:99], v[100:101]
	s_nop 0
	v_cvt_pk_bf16_f32 v97, v98, v99
	v_lshl_add_u64 v[98:99], v[106:107], 0, v[144:145]
	global_store_dwordx2 v[98:99], v[96:97], off
	v_mov_b32_e32 v96, v248
	v_pk_mul_f32 v[92:93], v[92:93], v[96:97] op_sel_hi:[1,0]
	s_nop 0
	v_mul_f32_e32 v97, 0xbfb8aa3b, v92
	v_exp_f32_e32 v97, v97
	s_nop 0
	v_add_f32_e32 v97, 1.0, v97
	v_rcp_f32_e32 v98, v97
	v_mul_f32_e32 v97, 0xbfb8aa3b, v93
	v_exp_f32_e32 v97, v97
	s_nop 0
	v_add_f32_e32 v97, 1.0, v97
	v_rcp_f32_e32 v99, v97
	v_pk_mul_f32 v[88:89], v[88:89], v[96:97] op_sel_hi:[1,0]
	v_pk_mul_f32 v[90:91], v[90:91], v[96:97] op_sel_hi:[1,0]
	v_pk_mul_f32 v[84:85], v[84:85], v[96:97] op_sel_hi:[1,0]
	v_pk_mul_f32 v[92:93], v[92:93], v[98:99]
	v_pk_mul_f32 v[80:81], v[80:81], v[96:97] op_sel_hi:[1,0]
	v_pk_mul_f32 v[88:89], v[88:89], v[92:93]
	v_pk_mul_f32 v[92:93], v[94:95], v[96:97] op_sel_hi:[1,0]
	v_cvt_pk_bf16_f32 v88, v88, v89
	v_mul_f32_e32 v94, 0xbfb8aa3b, v92
	v_mul_f32_e32 v95, 0xbfb8aa3b, v93
	v_exp_f32_e32 v94, v94
	v_exp_f32_e32 v95, v95
	v_pk_mul_f32 v[82:83], v[82:83], v[96:97] op_sel_hi:[1,0]
	v_add_f32_e32 v94, 1.0, v94
	v_add_f32_e32 v95, 1.0, v95
	v_rcp_f32_e32 v94, v94
	v_rcp_f32_e32 v95, v95
	s_nop 0
	v_pk_mul_f32 v[92:93], v[92:93], v[94:95]
	s_nop 0
	v_pk_mul_f32 v[90:91], v[90:91], v[92:93]
	s_nop 0
	v_cvt_pk_bf16_f32 v89, v90, v91
	v_mad_i64_i32 v[90:91], s[38:39], v108, s59, v[124:125]
	v_lshl_add_u64 v[92:93], v[90:91], 0, v[126:127]
	global_store_dwordx2 v[92:93], v[88:89], off
	v_mul_f32_e32 v88, 0xbfb8aa3b, v84
	v_mul_f32_e32 v89, 0xbfb8aa3b, v85
	v_exp_f32_e32 v88, v88
	v_exp_f32_e32 v89, v89
	v_add_u32_e32 v92, 48, v142
	v_ashrrev_i32_e32 v93, 31, v92
	v_add_f32_e32 v88, 1.0, v88
	v_add_f32_e32 v89, 1.0, v89
	v_rcp_f32_e32 v88, v88
	v_rcp_f32_e32 v89, v89
	s_nop 0
	v_pk_mul_f32 v[84:85], v[84:85], v[88:89]
	s_nop 0
	v_pk_mul_f32 v[80:81], v[80:81], v[84:85]
	v_pk_mul_f32 v[84:85], v[86:87], v[96:97] op_sel_hi:[1,0]
	v_cvt_pk_bf16_f32 v80, v80, v81
	v_mul_f32_e32 v86, 0xbfb8aa3b, v84
	v_mul_f32_e32 v87, 0xbfb8aa3b, v85
	v_exp_f32_e32 v86, v86
	v_exp_f32_e32 v87, v87
	v_add_f32_e32 v86, 1.0, v86
	v_add_f32_e32 v87, 1.0, v87
	v_rcp_f32_e32 v86, v86
	v_rcp_f32_e32 v87, v87
	s_nop 0
	v_pk_mul_f32 v[84:85], v[84:85], v[86:87]
	s_nop 0
	v_pk_mul_f32 v[82:83], v[82:83], v[84:85]
	s_nop 0
	v_cvt_pk_bf16_f32 v81, v82, v83
	v_lshl_add_u64 v[82:83], v[90:91], 0, v[144:145]
	global_store_dwordx2 v[82:83], v[80:81], off
	v_mov_b32_e32 v80, v249
	v_pk_mul_f32 v[76:77], v[76:77], v[80:81] op_sel_hi:[1,0]
	s_nop 0
	v_mul_f32_e32 v81, 0xbfb8aa3b, v76
	v_exp_f32_e32 v81, v81
	s_nop 0
	v_add_f32_e32 v81, 1.0, v81
	v_rcp_f32_e32 v82, v81
	v_mul_f32_e32 v81, 0xbfb8aa3b, v77
	v_exp_f32_e32 v81, v81
	s_nop 0
	v_add_f32_e32 v81, 1.0, v81
	v_rcp_f32_e32 v83, v81
	v_pk_mul_f32 v[72:73], v[72:73], v[80:81] op_sel_hi:[1,0]
	v_pk_mul_f32 v[74:75], v[74:75], v[80:81] op_sel_hi:[1,0]
	v_pk_mul_f32 v[68:69], v[68:69], v[80:81] op_sel_hi:[1,0]
	v_pk_mul_f32 v[76:77], v[76:77], v[82:83]
	v_pk_mul_f32 v[64:65], v[64:65], v[80:81] op_sel_hi:[1,0]
	v_pk_mul_f32 v[72:73], v[72:73], v[76:77]
	v_pk_mul_f32 v[76:77], v[78:79], v[80:81] op_sel_hi:[1,0]
; __device__ __forceinline__ float sigmoidf_(float x) { return __builtin_amdgcn_rcpf(1.f + __expf(-x)); }
; __device__ __forceinline__ u32x2 pack4(const f32x4& a) { u32x2 w; w.x = pk2(a[0], a[1]); w.y = pk2(a[2], a[3]); return w; }
; #define EPI_LOOP_ROWS for (int am_ = 0; am_ < 8; ++am_)
;     __device__ __forceinline__ void operator()(const f32x4 (&acc)[2][2][4][2], const pg8::Unit& u, int wr, int wc, int fr, int fq) const { asm volatile("" : "+v"(fr), "+v"(fq));
;     ...
;         EPI_LOOP_ROWS { EPI_AM const int row = u.pm * 256 + ai * 128 + wr * 64 + m * 16 + fr; const float rstd = ss_rstd(ss + (size_t)row * 16);
; #pragma unroll
;             for (int bj = 0; bj < 2; ++bj) { const int col0 = u.pn * 256 + bj * 128 + wc * 32 + 8 * fq; const f32x4 g = acc[ai][bj][m][0] * rstd, up = acc[ai][bj][m][1] * rstd; f32x4 o;
; #pragma unroll
;                 for (int j = 0; j < 4; ++j) o[j] = g[j] * sigmoidf_(g[j]) * up[j];
;                 *(u32x2*)(act + (size_t)row * FF + (col0 >> 1)) = pack4(o); } }
	v_cvt_pk_bf16_f32 v72, v72, v73
	v_mul_f32_e32 v78, 0xbfb8aa3b, v76
	v_mul_f32_e32 v79, 0xbfb8aa3b, v77
	v_exp_f32_e32 v78, v78
	v_exp_f32_e32 v79, v79
	v_pk_mul_f32 v[66:67], v[66:67], v[80:81] op_sel_hi:[1,0]
	v_add_f32_e32 v78, 1.0, v78
	v_add_f32_e32 v79, 1.0, v79
	v_rcp_f32_e32 v78, v78
	v_rcp_f32_e32 v79, v79
	s_nop 0
	v_pk_mul_f32 v[76:77], v[76:77], v[78:79]
	s_nop 0
	v_pk_mul_f32 v[74:75], v[74:75], v[76:77]
	s_nop 0
	v_cvt_pk_bf16_f32 v73, v74, v75
	v_mad_i64_i32 v[74:75], s[38:39], v92, s59, v[124:125]
	v_lshl_add_u64 v[76:77], v[74:75], 0, v[126:127]
	global_store_dwordx2 v[76:77], v[72:73], off
	v_mul_f32_e32 v72, 0xbfb8aa3b, v68
	v_mul_f32_e32 v73, 0xbfb8aa3b, v69
	v_exp_f32_e32 v72, v72
	v_exp_f32_e32 v73, v73
	v_add_u32_e32 v76, 0x80, v142
	v_ashrrev_i32_e32 v77, 31, v76
	v_add_f32_e32 v72, 1.0, v72
	v_add_f32_e32 v73, 1.0, v73
	v_rcp_f32_e32 v72, v72
	v_rcp_f32_e32 v73, v73
	s_nop 0
	v_pk_mul_f32 v[68:69], v[68:69], v[72:73]
	s_nop 0
	v_pk_mul_f32 v[64:65], v[64:65], v[68:69]
	v_pk_mul_f32 v[68:69], v[70:71], v[80:81] op_sel_hi:[1,0]
	v_cvt_pk_bf16_f32 v64, v64, v65
	v_mul_f32_e32 v70, 0xbfb8aa3b, v68
	v_mul_f32_e32 v71, 0xbfb8aa3b, v69
	v_exp_f32_e32 v70, v70
	v_exp_f32_e32 v71, v71
	v_add_f32_e32 v70, 1.0, v70
	v_add_f32_e32 v71, 1.0, v71
	v_rcp_f32_e32 v70, v70
	v_rcp_f32_e32 v71, v71
	s_nop 0
	v_pk_mul_f32 v[68:69], v[68:69], v[70:71]
	s_nop 0
	v_pk_mul_f32 v[66:67], v[66:67], v[68:69]
	s_nop 0
	v_cvt_pk_bf16_f32 v65, v66, v67
	v_lshl_add_u64 v[66:67], v[74:75], 0, v[144:145]
	global_store_dwordx2 v[66:67], v[64:65], off
	v_mov_b32_e32 v64, v250
	v_pk_mul_f32 v[60:61], v[60:61], v[64:65] op_sel_hi:[1,0]
	s_nop 0
	v_mul_f32_e32 v65, 0xbfb8aa3b, v60
	v_exp_f32_e32 v65, v65
	s_nop 0
	v_add_f32_e32 v65, 1.0, v65
	v_rcp_f32_e32 v66, v65
	v_mul_f32_e32 v65, 0xbfb8aa3b, v61
	v_exp_f32_e32 v65, v65
	s_nop 0
	v_add_f32_e32 v65, 1.0, v65
	v_rcp_f32_e32 v67, v65
	v_pk_mul_f32 v[56:57], v[56:57], v[64:65] op_sel_hi:[1,0]
	v_pk_mul_f32 v[58:59], v[58:59], v[64:65] op_sel_hi:[1,0]
	v_pk_mul_f32 v[52:53], v[52:53], v[64:65] op_sel_hi:[1,0]
	v_pk_mul_f32 v[60:61], v[60:61], v[66:67]
	v_pk_mul_f32 v[48:49], v[48:49], v[64:65] op_sel_hi:[1,0]
	v_pk_mul_f32 v[56:57], v[56:57], v[60:61]
	v_pk_mul_f32 v[60:61], v[62:63], v[64:65] op_sel_hi:[1,0]
	v_cvt_pk_bf16_f32 v56, v56, v57
	v_mul_f32_e32 v62, 0xbfb8aa3b, v60
	v_mul_f32_e32 v63, 0xbfb8aa3b, v61
	v_exp_f32_e32 v62, v62
	v_exp_f32_e32 v63, v63
	v_pk_mul_f32 v[50:51], v[50:51], v[64:65] op_sel_hi:[1,0]
	v_add_f32_e32 v62, 1.0, v62
	v_add_f32_e32 v63, 1.0, v63
	v_rcp_f32_e32 v62, v62
	v_rcp_f32_e32 v63, v63
	s_nop 0
	v_pk_mul_f32 v[60:61], v[60:61], v[62:63]
	s_nop 0
	v_pk_mul_f32 v[58:59], v[58:59], v[60:61]
	s_nop 0
	v_cvt_pk_bf16_f32 v57, v58, v59
	v_mad_i64_i32 v[58:59], s[38:39], v76, s59, v[124:125]
	v_lshl_add_u64 v[60:61], v[58:59], 0, v[126:127]
	global_store_dwordx2 v[60:61], v[56:57], off
	v_mul_f32_e32 v56, 0xbfb8aa3b, v52
	v_mul_f32_e32 v57, 0xbfb8aa3b, v53
	v_exp_f32_e32 v56, v56
	v_exp_f32_e32 v57, v57
	v_add_u32_e32 v60, 0x90, v142
	v_ashrrev_i32_e32 v61, 31, v60
	v_add_f32_e32 v56, 1.0, v56
	v_add_f32_e32 v57, 1.0, v57
	v_rcp_f32_e32 v56, v56
	v_rcp_f32_e32 v57, v57
	s_nop 0
	v_pk_mul_f32 v[52:53], v[52:53], v[56:57]
	s_nop 0
	v_pk_mul_f32 v[48:49], v[48:49], v[52:53]
	v_pk_mul_f32 v[52:53], v[54:55], v[64:65] op_sel_hi:[1,0]
	v_cvt_pk_bf16_f32 v48, v48, v49
	v_mul_f32_e32 v54, 0xbfb8aa3b, v52
	v_mul_f32_e32 v55, 0xbfb8aa3b, v53
	v_exp_f32_e32 v54, v54
	v_exp_f32_e32 v55, v55
	v_add_f32_e32 v54, 1.0, v54
	v_add_f32_e32 v55, 1.0, v55
	v_rcp_f32_e32 v54, v54
	v_rcp_f32_e32 v55, v55
	s_nop 0
	v_pk_mul_f32 v[52:53], v[52:53], v[54:55]
	s_nop 0
	v_pk_mul_f32 v[50:51], v[50:51], v[52:53]
	s_nop 0
	v_cvt_pk_bf16_f32 v49, v50, v51
	v_lshl_add_u64 v[50:51], v[58:59], 0, v[144:145]
	global_store_dwordx2 v[50:51], v[48:49], off
	v_mov_b32_e32 v48, v251
	v_pk_mul_f32 v[44:45], v[44:45], v[48:49] op_sel_hi:[1,0]
	s_nop 0
	v_mul_f32_e32 v49, 0xbfb8aa3b, v44
	v_exp_f32_e32 v49, v49
	s_nop 0
	v_add_f32_e32 v49, 1.0, v49
	v_rcp_f32_e32 v50, v49
	v_mul_f32_e32 v49, 0xbfb8aa3b, v45
	v_exp_f32_e32 v49, v49
	s_nop 0
	v_add_f32_e32 v49, 1.0, v49
	v_rcp_f32_e32 v51, v49
	v_pk_mul_f32 v[40:41], v[40:41], v[48:49] op_sel_hi:[1,0]
	v_pk_mul_f32 v[42:43], v[42:43], v[48:49] op_sel_hi:[1,0]
	v_pk_mul_f32 v[36:37], v[36:37], v[48:49] op_sel_hi:[1,0]
	v_pk_mul_f32 v[44:45], v[44:45], v[50:51]
	v_pk_mul_f32 v[32:33], v[32:33], v[48:49] op_sel_hi:[1,0]
	v_pk_mul_f32 v[40:41], v[40:41], v[44:45]
	v_pk_mul_f32 v[44:45], v[46:47], v[48:49] op_sel_hi:[1,0]
	v_cvt_pk_bf16_f32 v40, v40, v41
	v_mul_f32_e32 v46, 0xbfb8aa3b, v44
	v_mul_f32_e32 v47, 0xbfb8aa3b, v45
	v_exp_f32_e32 v46, v46
	v_exp_f32_e32 v47, v47
	v_pk_mul_f32 v[34:35], v[34:35], v[48:49] op_sel_hi:[1,0]
	v_add_f32_e32 v46, 1.0, v46
	v_add_f32_e32 v47, 1.0, v47
	v_rcp_f32_e32 v46, v46
	v_rcp_f32_e32 v47, v47
	s_nop 0
	v_pk_mul_f32 v[44:45], v[44:45], v[46:47]
	s_nop 0
	v_pk_mul_f32 v[42:43], v[42:43], v[44:45]
	s_nop 0
	v_cvt_pk_bf16_f32 v41, v42, v43
	v_mad_i64_i32 v[42:43], s[38:39], v60, s59, v[124:125]
	v_lshl_add_u64 v[44:45], v[42:43], 0, v[126:127]
	global_store_dwordx2 v[44:45], v[40:41], off
	v_mul_f32_e32 v40, 0xbfb8aa3b, v36
	v_mul_f32_e32 v41, 0xbfb8aa3b, v37
	v_exp_f32_e32 v40, v40
	v_exp_f32_e32 v41, v41
	v_add_u32_e32 v44, 0xa0, v142
	v_ashrrev_i32_e32 v45, 31, v44
; __device__ __forceinline__ float sigmoidf_(float x) { return __builtin_amdgcn_rcpf(1.f + __expf(-x)); }
; __device__ __forceinline__ u32x2 pack4(const f32x4& a) { u32x2 w; w.x = pk2(a[0], a[1]); w.y = pk2(a[2], a[3]); return w; }
; #define EPI_LOOP_ROWS for (int am_ = 0; am_ < 8; ++am_)
;     __device__ __forceinline__ void operator()(const f32x4 (&acc)[2][2][4][2], const pg8::Unit& u, int wr, int wc, int fr, int fq) const { asm volatile("" : "+v"(fr), "+v"(fq));
;     ...
;         EPI_LOOP_ROWS { EPI_AM const int row = u.pm * 256 + ai * 128 + wr * 64 + m * 16 + fr; const float rstd = ss_rstd(ss + (size_t)row * 16);
; #pragma unroll
;             for (int bj = 0; bj < 2; ++bj) { const int col0 = u.pn * 256 + bj * 128 + wc * 32 + 8 * fq; const f32x4 g = acc[ai][bj][m][0] * rstd, up = acc[ai][bj][m][1] * rstd; f32x4 o;
; #pragma unroll
;                 for (int j = 0; j < 4; ++j) o[j] = g[j] * sigmoidf_(g[j]) * up[j];
;                 *(u32x2*)(act + (size_t)row * FF + (col0 >> 1)) = pack4(o); } }
	v_add_f32_e32 v40, 1.0, v40
	v_add_f32_e32 v41, 1.0, v41
	v_rcp_f32_e32 v40, v40
	v_rcp_f32_e32 v41, v41
	s_nop 0
	v_pk_mul_f32 v[36:37], v[36:37], v[40:41]
	s_nop 0
	v_pk_mul_f32 v[32:33], v[32:33], v[36:37]
	v_pk_mul_f32 v[36:37], v[38:39], v[48:49] op_sel_hi:[1,0]
	v_cvt_pk_bf16_f32 v32, v32, v33
	v_mul_f32_e32 v38, 0xbfb8aa3b, v36
	v_mul_f32_e32 v39, 0xbfb8aa3b, v37
	v_exp_f32_e32 v38, v38
	v_exp_f32_e32 v39, v39
	v_add_f32_e32 v38, 1.0, v38
	v_add_f32_e32 v39, 1.0, v39
	v_rcp_f32_e32 v38, v38
	v_rcp_f32_e32 v39, v39
	s_nop 0
	v_pk_mul_f32 v[36:37], v[36:37], v[38:39]
	s_nop 0
	v_pk_mul_f32 v[34:35], v[34:35], v[36:37]
	s_nop 0
	v_cvt_pk_bf16_f32 v33, v34, v35
	v_lshl_add_u64 v[34:35], v[42:43], 0, v[144:145]
	global_store_dwordx2 v[34:35], v[32:33], off
	v_mov_b32_e32 v32, v252
	v_pk_mul_f32 v[28:29], v[28:29], v[32:33] op_sel_hi:[1,0]
	s_nop 0
	v_mul_f32_e32 v33, 0xbfb8aa3b, v28
	v_exp_f32_e32 v33, v33
	s_nop 0
	v_add_f32_e32 v33, 1.0, v33
	v_rcp_f32_e32 v34, v33
	v_mul_f32_e32 v33, 0xbfb8aa3b, v29
	v_exp_f32_e32 v33, v33
	s_nop 0
	v_add_f32_e32 v33, 1.0, v33
	v_rcp_f32_e32 v35, v33
	v_pk_mul_f32 v[24:25], v[24:25], v[32:33] op_sel_hi:[1,0]
	v_pk_mul_f32 v[26:27], v[26:27], v[32:33] op_sel_hi:[1,0]
	v_pk_mul_f32 v[20:21], v[20:21], v[32:33] op_sel_hi:[1,0]
	v_pk_mul_f32 v[28:29], v[28:29], v[34:35]
	v_pk_mul_f32 v[16:17], v[16:17], v[32:33] op_sel_hi:[1,0]
	v_pk_mul_f32 v[24:25], v[24:25], v[28:29]
	v_pk_mul_f32 v[28:29], v[30:31], v[32:33] op_sel_hi:[1,0]
	v_cvt_pk_bf16_f32 v24, v24, v25
	v_mul_f32_e32 v30, 0xbfb8aa3b, v28
	v_mul_f32_e32 v31, 0xbfb8aa3b, v29
	v_exp_f32_e32 v30, v30
	v_exp_f32_e32 v31, v31
	v_pk_mul_f32 v[18:19], v[18:19], v[32:33] op_sel_hi:[1,0]
	v_add_f32_e32 v30, 1.0, v30
	v_add_f32_e32 v31, 1.0, v31
	v_rcp_f32_e32 v30, v30
	v_rcp_f32_e32 v31, v31
	s_nop 0
	v_pk_mul_f32 v[28:29], v[28:29], v[30:31]
	s_nop 0
	v_pk_mul_f32 v[26:27], v[26:27], v[28:29]
	s_nop 0
	v_cvt_pk_bf16_f32 v25, v26, v27
	v_mad_i64_i32 v[26:27], s[38:39], v44, s59, v[124:125]
	v_lshl_add_u64 v[28:29], v[26:27], 0, v[126:127]
	global_store_dwordx2 v[28:29], v[24:25], off
	v_mul_f32_e32 v24, 0xbfb8aa3b, v20
	v_mul_f32_e32 v25, 0xbfb8aa3b, v21
	v_exp_f32_e32 v24, v24
	v_exp_f32_e32 v25, v25
	v_add_u32_e32 v28, 0xb0, v142
	v_ashrrev_i32_e32 v29, 31, v28
	v_add_f32_e32 v24, 1.0, v24
	v_add_f32_e32 v25, 1.0, v25
	v_rcp_f32_e32 v24, v24
	v_rcp_f32_e32 v25, v25
	s_nop 0
	v_pk_mul_f32 v[20:21], v[20:21], v[24:25]
	s_nop 0
	v_pk_mul_f32 v[16:17], v[16:17], v[20:21]
	v_pk_mul_f32 v[20:21], v[22:23], v[32:33] op_sel_hi:[1,0]
	v_cvt_pk_bf16_f32 v16, v16, v17
	v_mul_f32_e32 v22, 0xbfb8aa3b, v20
	v_mul_f32_e32 v23, 0xbfb8aa3b, v21
	v_exp_f32_e32 v22, v22
	v_exp_f32_e32 v23, v23
	v_add_f32_e32 v22, 1.0, v22
	v_add_f32_e32 v23, 1.0, v23
	v_rcp_f32_e32 v22, v22
	v_rcp_f32_e32 v23, v23
	s_nop 0
	v_pk_mul_f32 v[20:21], v[20:21], v[22:23]
	s_nop 0
	v_pk_mul_f32 v[18:19], v[18:19], v[20:21]
	s_nop 0
	v_cvt_pk_bf16_f32 v17, v18, v19
	v_lshl_add_u64 v[18:19], v[26:27], 0, v[144:145]
	global_store_dwordx2 v[18:19], v[16:17], off
	v_mov_b32_e32 v16, v253
	v_pk_mul_f32 v[12:13], v[12:13], v[16:17] op_sel_hi:[1,0]
	s_and_b64 vcc, exec, s[2:3]
	v_mul_f32_e32 v17, 0xbfb8aa3b, v12
	v_exp_f32_e32 v17, v17
	s_nop 0
	v_add_f32_e32 v17, 1.0, v17
	v_rcp_f32_e32 v18, v17
	v_mul_f32_e32 v17, 0xbfb8aa3b, v13
	v_exp_f32_e32 v17, v17
	s_nop 0
	v_add_f32_e32 v17, 1.0, v17
	v_rcp_f32_e32 v19, v17
	v_pk_mul_f32 v[8:9], v[8:9], v[16:17] op_sel_hi:[1,0]
	v_pk_mul_f32 v[10:11], v[10:11], v[16:17] op_sel_hi:[1,0]
	v_pk_mul_f32 v[4:5], v[4:5], v[16:17] op_sel_hi:[1,0]
	v_pk_mul_f32 v[12:13], v[12:13], v[18:19]
	v_pk_mul_f32 v[0:1], v[0:1], v[16:17] op_sel_hi:[1,0]
	v_pk_mul_f32 v[8:9], v[8:9], v[12:13]
	v_pk_mul_f32 v[12:13], v[14:15], v[16:17] op_sel_hi:[1,0]
	v_cvt_pk_bf16_f32 v8, v8, v9
	v_mul_f32_e32 v14, 0xbfb8aa3b, v12
	v_mul_f32_e32 v15, 0xbfb8aa3b, v13
	v_exp_f32_e32 v14, v14
	v_exp_f32_e32 v15, v15
	v_pk_mul_f32 v[2:3], v[2:3], v[16:17] op_sel_hi:[1,0]
	v_add_f32_e32 v14, 1.0, v14
	v_add_f32_e32 v15, 1.0, v15
	v_rcp_f32_e32 v14, v14
	v_rcp_f32_e32 v15, v15
	s_nop 0
	v_pk_mul_f32 v[12:13], v[12:13], v[14:15]
	s_nop 0
	v_pk_mul_f32 v[10:11], v[10:11], v[12:13]
	s_nop 0
	v_cvt_pk_bf16_f32 v9, v10, v11
	v_mad_i64_i32 v[10:11], s[38:39], v28, s59, v[124:125]
	v_lshl_add_u64 v[12:13], v[10:11], 0, v[126:127]
	global_store_dwordx2 v[12:13], v[8:9], off
	v_mul_f32_e32 v8, 0xbfb8aa3b, v4
	v_mul_f32_e32 v9, 0xbfb8aa3b, v5
	v_exp_f32_e32 v8, v8
	v_exp_f32_e32 v9, v9
	s_mov_b64 s[38:39], -1
	v_add_f32_e32 v8, 1.0, v8
	v_add_f32_e32 v9, 1.0, v9
	v_rcp_f32_e32 v8, v8
	v_rcp_f32_e32 v9, v9
	s_nop 0
	v_pk_mul_f32 v[4:5], v[4:5], v[8:9]
	s_nop 0
	v_pk_mul_f32 v[0:1], v[0:1], v[4:5]
	v_pk_mul_f32 v[4:5], v[6:7], v[16:17] op_sel_hi:[1,0]
	v_cvt_pk_bf16_f32 v0, v0, v1
	v_mul_f32_e32 v6, 0xbfb8aa3b, v4
	v_mul_f32_e32 v7, 0xbfb8aa3b, v5
	v_exp_f32_e32 v6, v6
	v_exp_f32_e32 v7, v7
	v_add_f32_e32 v6, 1.0, v6
	v_add_f32_e32 v7, 1.0, v7
	v_rcp_f32_e32 v6, v6
	v_rcp_f32_e32 v7, v7
	s_nop 0
	v_pk_mul_f32 v[4:5], v[4:5], v[6:7]
	s_nop 0
	v_pk_mul_f32 v[2:3], v[2:3], v[4:5]
	s_nop 0
	v_cvt_pk_bf16_f32 v1, v2, v3
	v_lshl_add_u64 v[2:3], v[10:11], 0, v[144:145]
	global_store_dwordx2 v[2:3], v[0:1], off
	s_cbranch_vccnz .LBB0_179
	s_andn2_b64 vcc, exec, s[14:15]
	s_cbranch_vccnz .LBB0_178
	s_barrier
	s_branch .LBB0_178

; #define MFMA16(a, b, c) __builtin_amdgcn_mfma_f32_16x16x32_bf16((a), (b), (c), 0, 0, 0)
; template <int NB, class AL, class EP>
; __device__ __forceinline__ void sgemm(int tid, int wg_lo, int ntile, int ksplit, int Kc, const bf16_t* Bt, int ldb, const AL al, const EP ep) {
;     ...
;         float sq = 0.f;
; #pragma unroll 8
;         for (int k = 0; k < Kc; k += 32) { const bf16x8 a = al.load(row, kb + k, sq);
; #pragma unroll
;             for (int nb = 0; nb < NB; ++nb) { const bf16x8 b = *(const bf16x8*)(bp[nb] + k); acc[nb] = MFMA16(b, a, acc[nb]); } }
.LBB0_198:
	v_add3_u32 v36, v22, s8, 32
	v_ashrrev_i32_e32 v37, 31, v36
	v_lshl_add_u64 v[40:41], v[36:37], 2, v[16:17]
	global_load_dwordx4 v[36:39], v[40:41], off offset:16
	s_nop 0
	global_load_dwordx4 v[40:43], v[40:41], off
	s_addk_i32 s8, 0x100
	s_cmpk_gt_u32 s8, 0x3df
	s_waitcnt vmcnt(0)
	v_pk_mul_f32 v[52:53], v[42:43], v[42:43]
	v_pk_mul_f32 v[54:55], v[40:41], v[40:41]
	s_nop 0
	v_pk_mov_b32 v[56:57], v[54:55], v[52:53] op_sel:[1,0]
	v_mov_b32_e32 v55, v53
	v_pk_add_f32 v[52:53], v[56:57], v[54:55]
	v_pk_mul_f32 v[54:55], v[38:39], v[38:39]
	v_pk_mul_f32 v[56:57], v[36:37], v[36:37]
	v_mov_b32_e32 v58, v54
	v_mov_b32_e32 v59, v56
	v_mov_b32_e32 v56, v55
	v_pk_add_f32 v[54:55], v[58:59], v[56:57]
	v_add_f32_e32 v51, v52, v53
	v_add_f32_e32 v51, v51, v55
	v_add_f32_e32 v51, v54, v51
	v_cvt_pk_bf16_f32 v54, v36, v37
	v_lshl_add_u64 v[36:37], v[30:31], 0, v[26:27]
	v_cvt_pk_bf16_f32 v52, v40, v41
	v_cvt_pk_bf16_f32 v55, v38, v39
	global_load_dwordx4 v[38:41], v[36:37], off
	v_cvt_pk_bf16_f32 v53, v42, v43
	v_add_f32_e32 v23, v23, v51
	v_lshl_add_u64 v[30:31], v[30:31], 0, s[50:51]
	s_waitcnt vmcnt(0)
	v_mfma_f32_16x16x32_bf16 v[12:15], v[38:41], v[52:55], v[12:15]
	v_lshl_add_u64 v[38:39], v[34:35], 0, v[26:27]
	global_load_dwordx4 v[40:43], v[38:39], off
	v_lshl_add_u64 v[34:35], v[34:35], 0, s[50:51]
	s_waitcnt vmcnt(0)
	v_mfma_f32_16x16x32_bf16 v[8:11], v[40:43], v[52:55], v[8:11]
	v_lshl_add_u64 v[40:41], v[32:33], 0, v[26:27]
	global_load_dwordx4 v[56:59], v[40:41], off
	v_lshl_add_u64 v[42:43], v[28:29], 0, v[26:27]
	v_lshl_add_u64 v[28:29], v[28:29], 0, s[50:51]
	v_lshl_add_u64 v[32:33], v[32:33], 0, s[50:51]
	s_waitcnt vmcnt(0)
	v_mfma_f32_16x16x32_bf16 v[4:7], v[56:59], v[52:55], v[4:7]
	global_load_dwordx4 v[56:59], v[42:43], off
	s_waitcnt vmcnt(0)
	v_mfma_f32_16x16x32_bf16 v[0:3], v[56:59], v[52:55], v[0:3]
	global_load_dwordx4 v[52:55], v[24:25], off offset:-768
	global_load_dwordx4 v[56:59], v[24:25], off offset:-784
	s_waitcnt vmcnt(0)
	v_pk_mul_f32 v[60:61], v[58:59], v[58:59]
	v_pk_mul_f32 v[62:63], v[56:57], v[56:57]
	v_cvt_pk_bf16_f32 v56, v56, v57
	v_pk_mov_b32 v[64:65], v[62:63], v[60:61] op_sel:[1,0]
	v_mov_b32_e32 v63, v61
	v_pk_add_f32 v[60:61], v[64:65], v[62:63]
	v_pk_mul_f32 v[62:63], v[54:55], v[54:55]
	v_pk_mul_f32 v[64:65], v[52:53], v[52:53]
	v_cvt_pk_bf16_f32 v57, v58, v59
	v_cvt_pk_bf16_f32 v58, v52, v53
	v_cvt_pk_bf16_f32 v59, v54, v55
	global_load_dwordx4 v[52:55], v[36:37], off offset:64
	v_mov_b32_e32 v66, v62
	v_mov_b32_e32 v67, v64
	v_mov_b32_e32 v64, v63
	v_pk_add_f32 v[62:63], v[66:67], v[64:65]
	v_add_f32_e32 v51, v60, v61
	v_add_f32_e32 v51, v51, v63
	v_add_f32_e32 v51, v62, v51
	v_add_f32_e32 v23, v23, v51
	s_waitcnt vmcnt(0)
	v_mfma_f32_16x16x32_bf16 v[12:15], v[52:55], v[56:59], v[12:15]
	global_load_dwordx4 v[52:55], v[38:39], off offset:64
	s_waitcnt vmcnt(0)
	v_mfma_f32_16x16x32_bf16 v[8:11], v[52:55], v[56:59], v[8:11]
	global_load_dwordx4 v[52:55], v[40:41], off offset:64
	s_waitcnt vmcnt(0)
	v_mfma_f32_16x16x32_bf16 v[4:7], v[52:55], v[56:59], v[4:7]
	global_load_dwordx4 v[52:55], v[42:43], off offset:64
	s_waitcnt vmcnt(0)
	v_mfma_f32_16x16x32_bf16 v[0:3], v[52:55], v[56:59], v[0:3]
	global_load_dwordx4 v[52:55], v[24:25], off offset:-640
	global_load_dwordx4 v[56:59], v[24:25], off offset:-656
	s_waitcnt vmcnt(0)
	v_pk_mul_f32 v[60:61], v[58:59], v[58:59]
	v_pk_mul_f32 v[62:63], v[56:57], v[56:57]
	v_cvt_pk_bf16_f32 v56, v56, v57
	v_pk_mov_b32 v[64:65], v[62:63], v[60:61] op_sel:[1,0]
	v_mov_b32_e32 v63, v61
	v_pk_add_f32 v[60:61], v[64:65], v[62:63]
	v_pk_mul_f32 v[62:63], v[54:55], v[54:55]
	v_pk_mul_f32 v[64:65], v[52:53], v[52:53]
	v_cvt_pk_bf16_f32 v57, v58, v59
	v_cvt_pk_bf16_f32 v58, v52, v53
	v_cvt_pk_bf16_f32 v59, v54, v55
	global_load_dwordx4 v[52:55], v[36:37], off offset:128
	v_mov_b32_e32 v66, v62
	v_mov_b32_e32 v67, v64
	v_mov_b32_e32 v64, v63
	v_pk_add_f32 v[62:63], v[66:67], v[64:65]
	v_add_f32_e32 v51, v60, v61
	v_add_f32_e32 v51, v51, v63
	v_add_f32_e32 v51, v62, v51
	v_add_f32_e32 v23, v23, v51
	s_waitcnt vmcnt(0)
	v_mfma_f32_16x16x32_bf16 v[12:15], v[52:55], v[56:59], v[12:15]
	global_load_dwordx4 v[52:55], v[38:39], off offset:128
	s_waitcnt vmcnt(0)
	v_mfma_f32_16x16x32_bf16 v[8:11], v[52:55], v[56:59], v[8:11]
	global_load_dwordx4 v[52:55], v[40:41], off offset:128
	s_waitcnt vmcnt(0)
	v_mfma_f32_16x16x32_bf16 v[4:7], v[52:55], v[56:59], v[4:7]
	global_load_dwordx4 v[52:55], v[42:43], off offset:128
	s_waitcnt vmcnt(0)
	v_mfma_f32_16x16x32_bf16 v[0:3], v[52:55], v[56:59], v[0:3]
	global_load_dwordx4 v[52:55], v[24:25], off offset:-512
	global_load_dwordx4 v[56:59], v[24:25], off offset:-528
	s_waitcnt vmcnt(0)
	v_pk_mul_f32 v[60:61], v[58:59], v[58:59]
	v_pk_mul_f32 v[62:63], v[56:57], v[56:57]
	v_cvt_pk_bf16_f32 v56, v56, v57
	v_pk_mov_b32 v[64:65], v[62:63], v[60:61] op_sel:[1,0]
	v_mov_b32_e32 v63, v61
	v_pk_add_f32 v[60:61], v[64:65], v[62:63]
	v_pk_mul_f32 v[62:63], v[54:55], v[54:55]
	v_pk_mul_f32 v[64:65], v[52:53], v[52:53]
	v_cvt_pk_bf16_f32 v57, v58, v59
	v_cvt_pk_bf16_f32 v58, v52, v53
	v_cvt_pk_bf16_f32 v59, v54, v55
	global_load_dwordx4 v[52:55], v[36:37], off offset:192
	v_mov_b32_e32 v66, v62
	v_mov_b32_e32 v67, v64
	v_mov_b32_e32 v64, v63
	v_pk_add_f32 v[62:63], v[66:67], v[64:65]
	v_add_f32_e32 v51, v60, v61
	v_add_f32_e32 v51, v51, v63
	v_add_f32_e32 v51, v62, v51
	v_add_f32_e32 v23, v23, v51
	s_waitcnt vmcnt(0)
	v_mfma_f32_16x16x32_bf16 v[12:15], v[52:55], v[56:59], v[12:15]
	global_load_dwordx4 v[52:55], v[38:39], off offset:192
	s_waitcnt vmcnt(0)
	v_mfma_f32_16x16x32_bf16 v[8:11], v[52:55], v[56:59], v[8:11]
	global_load_dwordx4 v[52:55], v[40:41], off offset:192
	s_waitcnt vmcnt(0)
; #define MFMA16(a, b, c) __builtin_amdgcn_mfma_f32_16x16x32_bf16((a), (b), (c), 0, 0, 0)
; template <int NB, class AL, class EP>
; __device__ __forceinline__ void sgemm(int tid, int wg_lo, int ntile, int ksplit, int Kc, const bf16_t* Bt, int ldb, const AL al, const EP ep) {
;     ...
;         float sq = 0.f;
; #pragma unroll 8
;         for (int k = 0; k < Kc; k += 32) { const bf16x8 a = al.load(row, kb + k, sq);
; #pragma unroll
;             for (int nb = 0; nb < NB; ++nb) { const bf16x8 b = *(const bf16x8*)(bp[nb] + k); acc[nb] = MFMA16(b, a, acc[nb]); } }
	v_mfma_f32_16x16x32_bf16 v[4:7], v[52:55], v[56:59], v[4:7]
	global_load_dwordx4 v[52:55], v[42:43], off offset:192
	s_waitcnt vmcnt(0)
	v_mfma_f32_16x16x32_bf16 v[0:3], v[52:55], v[56:59], v[0:3]
	global_load_dwordx4 v[52:55], v[24:25], off offset:-384
	global_load_dwordx4 v[56:59], v[24:25], off offset:-400
	s_waitcnt vmcnt(0)
	v_pk_mul_f32 v[60:61], v[58:59], v[58:59]
	v_pk_mul_f32 v[62:63], v[56:57], v[56:57]
	v_cvt_pk_bf16_f32 v56, v56, v57
	v_pk_mov_b32 v[64:65], v[62:63], v[60:61] op_sel:[1,0]
	v_mov_b32_e32 v63, v61
	v_pk_add_f32 v[60:61], v[64:65], v[62:63]
	v_pk_mul_f32 v[62:63], v[54:55], v[54:55]
	v_pk_mul_f32 v[64:65], v[52:53], v[52:53]
	v_cvt_pk_bf16_f32 v57, v58, v59
	v_cvt_pk_bf16_f32 v58, v52, v53
	v_cvt_pk_bf16_f32 v59, v54, v55
	global_load_dwordx4 v[52:55], v[36:37], off offset:256
	v_mov_b32_e32 v66, v62
	v_mov_b32_e32 v67, v64
	v_mov_b32_e32 v64, v63
	v_pk_add_f32 v[62:63], v[66:67], v[64:65]
	v_add_f32_e32 v51, v60, v61
	v_add_f32_e32 v51, v51, v63
	v_add_f32_e32 v51, v62, v51
	v_add_f32_e32 v23, v23, v51
	s_waitcnt vmcnt(0)
	v_mfma_f32_16x16x32_bf16 v[12:15], v[52:55], v[56:59], v[12:15]
	global_load_dwordx4 v[52:55], v[38:39], off offset:256
	s_waitcnt vmcnt(0)
	v_mfma_f32_16x16x32_bf16 v[8:11], v[52:55], v[56:59], v[8:11]
	global_load_dwordx4 v[52:55], v[40:41], off offset:256
	s_waitcnt vmcnt(0)
	v_mfma_f32_16x16x32_bf16 v[4:7], v[52:55], v[56:59], v[4:7]
	global_load_dwordx4 v[52:55], v[42:43], off offset:256
	s_waitcnt vmcnt(0)
	v_mfma_f32_16x16x32_bf16 v[0:3], v[52:55], v[56:59], v[0:3]
	global_load_dwordx4 v[52:55], v[24:25], off offset:-256
	global_load_dwordx4 v[56:59], v[24:25], off offset:-272
	s_waitcnt vmcnt(0)
	v_pk_mul_f32 v[60:61], v[58:59], v[58:59]
	v_pk_mul_f32 v[62:63], v[56:57], v[56:57]
	v_cvt_pk_bf16_f32 v56, v56, v57
	v_pk_mov_b32 v[64:65], v[62:63], v[60:61] op_sel:[1,0]
	v_mov_b32_e32 v63, v61
	v_pk_add_f32 v[60:61], v[64:65], v[62:63]
	v_pk_mul_f32 v[62:63], v[54:55], v[54:55]
	v_pk_mul_f32 v[64:65], v[52:53], v[52:53]
	v_cvt_pk_bf16_f32 v57, v58, v59
	v_cvt_pk_bf16_f32 v58, v52, v53
	v_cvt_pk_bf16_f32 v59, v54, v55
	global_load_dwordx4 v[52:55], v[36:37], off offset:320
	v_mov_b32_e32 v66, v62
	v_mov_b32_e32 v67, v64
	v_mov_b32_e32 v64, v63
	v_pk_add_f32 v[62:63], v[66:67], v[64:65]
	v_add_f32_e32 v51, v60, v61
	v_add_f32_e32 v51, v51, v63
	s_waitcnt vmcnt(0)
	v_mfma_f32_16x16x32_bf16 v[12:15], v[52:55], v[56:59], v[12:15]
	global_load_dwordx4 v[52:55], v[38:39], off offset:320
	v_add_f32_e32 v51, v62, v51
	v_add_f32_e32 v23, v23, v51
	s_waitcnt vmcnt(0)
	v_mfma_f32_16x16x32_bf16 v[8:11], v[52:55], v[56:59], v[8:11]
	global_load_dwordx4 v[52:55], v[40:41], off offset:320
	s_waitcnt vmcnt(0)
	v_mfma_f32_16x16x32_bf16 v[4:7], v[52:55], v[56:59], v[4:7]
	global_load_dwordx4 v[52:55], v[42:43], off offset:320
	s_waitcnt vmcnt(0)
	v_mfma_f32_16x16x32_bf16 v[0:3], v[52:55], v[56:59], v[0:3]
	global_load_dwordx4 v[52:55], v[24:25], off offset:-128
	global_load_dwordx4 v[56:59], v[24:25], off offset:-144
	s_waitcnt vmcnt(0)
	v_pk_mul_f32 v[60:61], v[58:59], v[58:59]
	v_pk_mul_f32 v[62:63], v[56:57], v[56:57]
	v_cvt_pk_bf16_f32 v56, v56, v57
	v_pk_mov_b32 v[64:65], v[62:63], v[60:61] op_sel:[1,0]
	v_mov_b32_e32 v63, v61
	v_pk_add_f32 v[60:61], v[64:65], v[62:63]
	v_pk_mul_f32 v[62:63], v[54:55], v[54:55]
	v_pk_mul_f32 v[64:65], v[52:53], v[52:53]
	v_cvt_pk_bf16_f32 v57, v58, v59
	v_cvt_pk_bf16_f32 v58, v52, v53
	v_cvt_pk_bf16_f32 v59, v54, v55
	global_load_dwordx4 v[52:55], v[36:37], off offset:384
	v_mov_b32_e32 v66, v62
	s_waitcnt vmcnt(0)
	v_mfma_f32_16x16x32_bf16 v[12:15], v[52:55], v[56:59], v[12:15]
	global_load_dwordx4 v[52:55], v[38:39], off offset:384
	v_mov_b32_e32 v67, v64
	v_mov_b32_e32 v64, v63
	s_waitcnt vmcnt(0)
	v_mfma_f32_16x16x32_bf16 v[8:11], v[52:55], v[56:59], v[8:11]
	global_load_dwordx4 v[52:55], v[40:41], off offset:384
	v_pk_add_f32 v[62:63], v[66:67], v[64:65]
	v_add_f32_e32 v51, v60, v61
	s_waitcnt vmcnt(0)
	v_mfma_f32_16x16x32_bf16 v[4:7], v[52:55], v[56:59], v[4:7]
	global_load_dwordx4 v[52:55], v[42:43], off offset:384
	v_add_f32_e32 v51, v51, v63
	v_add_f32_e32 v51, v62, v51
	s_waitcnt vmcnt(0)
	v_mfma_f32_16x16x32_bf16 v[0:3], v[52:55], v[56:59], v[0:3]
	global_load_dwordx4 v[52:55], v[24:25], off
	global_load_dwordx4 v[56:59], v[24:25], off offset:-16
	v_add_f32_e32 v23, v23, v51
	v_lshl_add_u64 v[24:25], v[24:25], 0, s[56:57]
	s_waitcnt vmcnt(0)
	v_pk_mul_f32 v[60:61], v[58:59], v[58:59]
	v_pk_mul_f32 v[62:63], v[56:57], v[56:57]
	v_cvt_pk_bf16_f32 v56, v56, v57
	v_pk_mov_b32 v[64:65], v[62:63], v[60:61] op_sel:[1,0]
	v_mov_b32_e32 v63, v61
	v_pk_add_f32 v[60:61], v[64:65], v[62:63]
	v_pk_mul_f32 v[62:63], v[54:55], v[54:55]
	v_pk_mul_f32 v[64:65], v[52:53], v[52:53]
	v_cvt_pk_bf16_f32 v57, v58, v59
	v_cvt_pk_bf16_f32 v58, v52, v53
	v_cvt_pk_bf16_f32 v59, v54, v55
	global_load_dwordx4 v[52:55], v[36:37], off offset:448
	v_mov_b32_e32 v66, v62
	global_load_dwordx4 v[36:39], v[38:39], off offset:448
	s_waitcnt vmcnt(0)
	v_mfma_f32_16x16x32_bf16 v[8:11], v[36:39], v[56:59], v[8:11]
	global_load_dwordx4 v[36:39], v[40:41], off offset:448
	v_mov_b32_e32 v67, v64
	v_mov_b32_e32 v64, v63
	s_waitcnt vmcnt(0)
	v_mfma_f32_16x16x32_bf16 v[4:7], v[36:39], v[56:59], v[4:7]
	global_load_dwordx4 v[36:39], v[42:43], off offset:448
	v_pk_add_f32 v[62:63], v[66:67], v[64:65]
	v_add_f32_e32 v51, v60, v61
	v_mfma_f32_16x16x32_bf16 v[12:15], v[52:55], v[56:59], v[12:15]
	v_add_f32_e32 v51, v51, v63
	v_add_f32_e32 v51, v62, v51
	v_add_f32_e32 v23, v23, v51
	s_waitcnt vmcnt(0)
	v_mfma_f32_16x16x32_bf16 v[0:3], v[36:39], v[56:59], v[0:3]
	s_cbranch_scc0 .LBB0_198
; template <int NB, class AL, class EP>
; __device__ __forceinline__ void sgemm(int tid, int wg_lo, int ntile, int ksplit, int Kc, const bf16_t* Bt, int ldb, const AL al, const EP ep) {
;     ...
;         sq += __shfl_xor(sq, 16); sq += __shfl_xor(sq, 32);
;         ep(tn, row, fq, acc, sq);
;     }
; }
	ds_bpermute_b32 v22, v46, v23
	s_mulk_i32 s5, 0x58
	s_sub_i32 s5, s4, s5
	s_lshl_b32 s8, s5, 5
	s_ashr_i32 s9, s8, 31
	s_waitcnt lgkmcnt(0)
	v_add_f32_e32 v22, v23, v22
	ds_bpermute_b32 v23, v47, v22
	v_lshl_add_u64 v[24:25], s[8:9], 1, v[18:19]
	s_add_i32 s5, s4, 0x80
	s_cmpk_gt_i32 s4, 0xffd7
	s_mov_b32 s4, s5
	s_waitcnt lgkmcnt(0)
	v_add_f32_e32 v22, v22, v23
	v_fmamk_f32 v22, v22, 0x3a800000, v138
	v_cmp_gt_f32_e32 vcc, s64, v22
	v_mul_f32_e32 v23, 0x4b800000, v22
	s_nop 0
	v_cndmask_b32_e32 v22, v22, v23, vcc
	v_rsq_f32_e32 v22, v22
	s_nop 0
	v_mul_f32_e32 v23, 0x45800000, v22
	v_cndmask_b32_e32 v22, v22, v23, vcc
	v_pk_mul_f32 v[12:13], v[12:13], v[22:23] op_sel_hi:[1,0]
	s_nop 0
	v_mul_f32_e32 v23, 0xbfb8aa3b, v12
	v_exp_f32_e32 v23, v23
	s_nop 0
	v_add_f32_e32 v23, 1.0, v23
	v_rcp_f32_e32 v26, v23
	v_mul_f32_e32 v23, 0xbfb8aa3b, v13
	v_exp_f32_e32 v23, v23
	s_nop 0
	v_add_f32_e32 v23, 1.0, v23
	v_rcp_f32_e32 v27, v23
	v_pk_mul_f32 v[8:9], v[8:9], v[22:23] op_sel_hi:[1,0]
	v_pk_mul_f32 v[10:11], v[10:11], v[22:23] op_sel_hi:[1,0]
	v_pk_mul_f32 v[4:5], v[4:5], v[22:23] op_sel_hi:[1,0]
	v_pk_mul_f32 v[12:13], v[12:13], v[26:27]
	v_pk_mul_f32 v[0:1], v[0:1], v[22:23] op_sel_hi:[1,0]
	v_pk_mul_f32 v[8:9], v[8:9], v[12:13]
	v_pk_mul_f32 v[12:13], v[14:15], v[22:23] op_sel_hi:[1,0]
	v_cvt_pk_bf16_f32 v8, v8, v9
	v_mul_f32_e32 v14, 0xbfb8aa3b, v12
	v_mul_f32_e32 v15, 0xbfb8aa3b, v13
	v_exp_f32_e32 v14, v14
	v_exp_f32_e32 v15, v15
	v_pk_mul_f32 v[2:3], v[2:3], v[22:23] op_sel_hi:[1,0]
	v_add_f32_e32 v14, 1.0, v14
	v_add_f32_e32 v15, 1.0, v15
	v_rcp_f32_e32 v14, v14
	v_rcp_f32_e32 v15, v15
	s_nop 0
	v_pk_mul_f32 v[12:13], v[12:13], v[14:15]
	s_nop 0
	v_pk_mul_f32 v[10:11], v[10:11], v[12:13]
	s_nop 0
	v_cvt_pk_bf16_f32 v9, v10, v11
	global_store_dwordx2 v[24:25], v[8:9], off
	v_mul_f32_e32 v8, 0xbfb8aa3b, v4
	v_mul_f32_e32 v9, 0xbfb8aa3b, v5
	v_exp_f32_e32 v8, v8
	v_exp_f32_e32 v9, v9
	v_add_f32_e32 v8, 1.0, v8
	v_add_f32_e32 v9, 1.0, v9
	v_rcp_f32_e32 v8, v8
	v_rcp_f32_e32 v9, v9
	s_nop 0
	v_pk_mul_f32 v[4:5], v[4:5], v[8:9]
	s_nop 0
	v_pk_mul_f32 v[0:1], v[0:1], v[4:5]
	v_pk_mul_f32 v[4:5], v[6:7], v[22:23] op_sel_hi:[1,0]
	v_cvt_pk_bf16_f32 v0, v0, v1
	v_mul_f32_e32 v6, 0xbfb8aa3b, v4
	v_mul_f32_e32 v7, 0xbfb8aa3b, v5
	v_exp_f32_e32 v6, v6
	v_exp_f32_e32 v7, v7
	v_add_f32_e32 v6, 1.0, v6
	v_add_f32_e32 v7, 1.0, v7
	v_rcp_f32_e32 v6, v6
	v_rcp_f32_e32 v7, v7
	s_nop 0
	v_pk_mul_f32 v[4:5], v[4:5], v[6:7]
	s_nop 0
	v_pk_mul_f32 v[2:3], v[2:3], v[4:5]
	s_nop 0
	v_cvt_pk_bf16_f32 v1, v2, v3
	global_store_dwordx2 v[24:25], v[0:1], off offset:32
	s_cbranch_scc0 .LBB0_197

; __device__ __forceinline__ void scan_step(f32x4& S, float& ypo, const u32x4& h0, const u32x4& h1, unsigned e01, unsigned e23, unsigned r01, unsigned r23, float vi) {
;     float s0 = S[0], s1 = S[1], s2 = S[2], s3 = S[3], sa, yp, sb;
;     asm volatile(
;         MIX_SH("%[sa]", "%[s0]", "%[n01]", "0", "0") MIX_SH("%[sb]", "%[s2]", "%[n23]", "0", "0") MIX_SH("%[yp]", "%[s0]", "%[r01]", "0", "0")
;         MIX_SH("%[sa]", "%[s1]", "%[n01]", "%[sa]", "1") MIX_SH("%[sb]", "%[s3]", "%[n23]", "%[sb]", "1") MIX_SH("%[yp]", "%[s1]", "%[r01]", "%[yp]", "1")
;         "v_add_f32 %[sa], %[sa], %[sb]\n\t" MIX_SH("%[yp]", "%[s2]", "%[r23]", "%[yp]", "0") MIX_SH("%[yp]", "%[s3]", "%[r23]", "%[yp]", "1")
;         "v_fma_mix_f32 %[s0], %[e01], %[s0], %[s0] op_sel:[0,0,0] op_sel_hi:[1,0,0]\n\t" "v_fma_mix_f32 %[s1], %[e01], %[s1], %[s1] op_sel:[1,0,0] op_sel_hi:[1,0,0]\n\t"
;         DPP_ADD("%[sa]", "quad_perm:[1,0,3,2]") DPP_ADD("%[yp]", "quad_perm:[1,0,3,2]")
;         "v_fma_mix_f32 %[s2], %[e23], %[s2], %[s2] op_sel:[0,0,0] op_sel_hi:[1,0,0]\n\t" "v_fma_mix_f32 %[s3], %[e23], %[s3], %[s3] op_sel:[1,0,0] op_sel_hi:[1,0,0]\n\t"
;         DPP_ADD("%[sa]", "quad_perm:[2,3,0,1]") DPP_ADD("%[yp]", "quad_perm:[2,3,0,1]")
;         MIX_HS("%[s0]", "%[p01]", "%[vi]", "0") MIX_HS("%[s1]", "%[p01]", "%[vi]", "1")
;         DPP_ADD("%[sa]", "row_half_mirror")
;         MIX_HS("%[s2]", "%[p23]", "%[vi]", "0") MIX_HS("%[s3]", "%[p23]", "%[vi]", "1")
;         DPP_ADD("%[sa]", "row_mirror")
;         MIX_HS("%[s0]", "%[b01]", "%[sa]", "0") MIX_HS("%[s1]", "%[b01]", "%[sa]", "1") MIX_HS("%[s2]", "%[b23]", "%[sa]", "0") "v_fma_mix_f32 %[s3], %[b23], %[sa], %[s3] op_sel:[1,0,0] op_sel_hi:[1,0,0]"
;         : [s0] "+v"(s0), [s1] "+v"(s1), [s2] "+v"(s2), [s3] "+v"(s3), [sa] "=&v"(sa), [yp] "=&v"(yp), [sb] "=&v"(sb)
;         : [n01] "v"(h0.x), [n23] "v"(h0.y), [b01] "v"(h0.z), [b23] "v"(h0.w), [p01] "v"(h1.x), [p23] "v"(h1.y), [r01] "v"(r01), [r23] "v"(r23),
;           [e01] "v"(e01), [e23] "v"(e23), [vi] "v"(vi));
;     S[0] = s0; S[1] = s1; S[2] = s2; S[3] = s3; ypo = yp;
.LBB0_1108:
	s_and_b64 vcc, exec, s[44:45]
	s_cbranch_vccz .LBB0_1128
	s_lshl_b32 s44, s47, 15
	s_add_i32 s44, s44, 0
	v_add_u32_e32 v61, s44, v65
	v_lshl_add_u32 v60, v62, 2, s44
	ds_read_b128 v[100:103], v61 offset:24576
	ds_read_b128 v[104:107], v60 offset:16384
	ds_read_b128 v[108:111], v60 offset:18432
	ds_read_b128 v[112:115], v60
	ds_read_b128 v[116:119], v60 offset:8192
	ds_read_b128 v[120:123], v60 offset:256
	ds_read_b128 v[124:127], v60 offset:8448
	ds_read_b128 v[128:131], v60 offset:512
	ds_read_b128 v[132:135], v60 offset:8704
	ds_read_b128 v[140:143], v60 offset:768
	ds_read_b128 v[52:55], v60 offset:8960
	ds_read_b128 v[172:175], v61 offset:24592
	ds_read_b128 v[176:179], v60 offset:16640
	ds_read_b128 v[180:183], v60 offset:18688
	ds_read_b128 v[184:187], v60 offset:1024
	ds_read_b128 v[188:191], v60 offset:9216
	ds_read_b128 v[192:195], v60 offset:1280
	ds_read_b128 v[196:199], v60 offset:9472
	ds_read_b128 v[200:203], v60 offset:1536
	ds_read_b128 v[204:207], v60 offset:9728
	ds_read_b128 v[208:211], v60 offset:1792
	ds_read_b128 v[212:215], v60 offset:9984
	s_waitcnt lgkmcnt(11)
	v_fma_mix_f32 v224, v24, v112, 0 op_sel:[0,0,0] op_sel_hi:[0,1,0]
	v_fma_mix_f32 v225, v26, v113, 0 op_sel:[0,0,0] op_sel_hi:[0,1,0]
	v_fma_mix_f32 v216, v24, v137, 0 op_sel:[0,0,0] op_sel_hi:[0,1,0]
	v_fma_mix_f32 v224, v25, v112, v224 op_sel:[0,1,0] op_sel_hi:[0,1,0]
	v_fma_mix_f32 v225, v27, v113, v225 op_sel:[0,1,0] op_sel_hi:[0,1,0]
	v_fma_mix_f32 v216, v25, v137, v216 op_sel:[0,1,0] op_sel_hi:[0,1,0]
	v_add_f32 v224, v224, v225
	v_fma_mix_f32 v216, v26, v137, v216 op_sel:[0,0,0] op_sel_hi:[0,1,0]
	v_fma_mix_f32 v216, v27, v137, v216 op_sel:[0,1,0] op_sel_hi:[0,1,0]
	v_fma_mix_f32 v24, v104, v24, v24 op_sel:[0,0,0] op_sel_hi:[1,0,0]
	v_fma_mix_f32 v25, v104, v25, v25 op_sel:[1,0,0] op_sel_hi:[1,0,0]
	v_add_f32_dpp v224, v224, v224 quad_perm:[1,0,3,2] row_mask:0xf bank_mask:0xf bound_ctrl:1
	v_add_f32_dpp v216, v216, v216 quad_perm:[1,0,3,2] row_mask:0xf bank_mask:0xf bound_ctrl:1
	v_fma_mix_f32 v26, v105, v26, v26 op_sel:[0,0,0] op_sel_hi:[1,0,0]
	v_fma_mix_f32 v27, v105, v27, v27 op_sel:[1,0,0] op_sel_hi:[1,0,0]
	v_add_f32_dpp v224, v224, v224 quad_perm:[2,3,0,1] row_mask:0xf bank_mask:0xf bound_ctrl:1
	v_add_f32_dpp v216, v216, v216 quad_perm:[2,3,0,1] row_mask:0xf bank_mask:0xf bound_ctrl:1
	v_fma_mix_f32 v24, v116, v100, v24 op_sel:[0,0,0] op_sel_hi:[1,0,0]
	v_fma_mix_f32 v25, v116, v100, v25 op_sel:[1,0,0] op_sel_hi:[1,0,0]
	v_add_f32_dpp v224, v224, v224 row_half_mirror row_mask:0xf bank_mask:0xf bound_ctrl:1
	v_fma_mix_f32 v26, v117, v100, v26 op_sel:[0,0,0] op_sel_hi:[1,0,0]
	v_fma_mix_f32 v27, v117, v100, v27 op_sel:[1,0,0] op_sel_hi:[1,0,0]
	v_add_f32_dpp v224, v224, v224 row_mirror row_mask:0xf bank_mask:0xf bound_ctrl:1
	v_fma_mix_f32 v24, v114, v224, v24 op_sel:[0,0,0] op_sel_hi:[1,0,0]
	v_fma_mix_f32 v25, v114, v224, v25 op_sel:[1,0,0] op_sel_hi:[1,0,0]
	v_fma_mix_f32 v26, v115, v224, v26 op_sel:[0,0,0] op_sel_hi:[1,0,0]
	v_fma_mix_f32 v27, v115, v224, v27 op_sel:[1,0,0] op_sel_hi:[1,0,0]
	v_fma_mix_f32 v226, v24, v120, 0 op_sel:[0,0,0] op_sel_hi:[0,1,0]
	v_fma_mix_f32 v227, v26, v121, 0 op_sel:[0,0,0] op_sel_hi:[0,1,0]
	v_fma_mix_f32 v217, v24, v118, 0 op_sel:[0,0,0] op_sel_hi:[0,1,0]
	v_fma_mix_f32 v226, v25, v120, v226 op_sel:[0,1,0] op_sel_hi:[0,1,0]
	v_fma_mix_f32 v227, v27, v121, v227 op_sel:[0,1,0] op_sel_hi:[0,1,0]
	v_fma_mix_f32 v217, v25, v118, v217 op_sel:[0,1,0] op_sel_hi:[0,1,0]
	v_add_f32 v226, v226, v227
	v_fma_mix_f32 v217, v26, v119, v217 op_sel:[0,0,0] op_sel_hi:[0,1,0]
	v_fma_mix_f32 v217, v27, v119, v217 op_sel:[0,1,0] op_sel_hi:[0,1,0]
	v_fma_mix_f32 v24, v106, v24, v24 op_sel:[0,0,0] op_sel_hi:[1,0,0]
	v_fma_mix_f32 v25, v106, v25, v25 op_sel:[1,0,0] op_sel_hi:[1,0,0]
	v_add_f32_dpp v226, v226, v226 quad_perm:[1,0,3,2] row_mask:0xf bank_mask:0xf bound_ctrl:1
	v_add_f32_dpp v217, v217, v217 quad_perm:[1,0,3,2] row_mask:0xf bank_mask:0xf bound_ctrl:1
	v_fma_mix_f32 v26, v107, v26, v26 op_sel:[0,0,0] op_sel_hi:[1,0,0]
	v_fma_mix_f32 v27, v107, v27, v27 op_sel:[1,0,0] op_sel_hi:[1,0,0]
	v_add_f32_dpp v226, v226, v226 quad_perm:[2,3,0,1] row_mask:0xf bank_mask:0xf bound_ctrl:1
	v_add_f32_dpp v217, v217, v217 quad_perm:[2,3,0,1] row_mask:0xf bank_mask:0xf bound_ctrl:1
	v_fma_mix_f32 v24, v124, v101, v24 op_sel:[0,0,0] op_sel_hi:[1,0,0]
	v_fma_mix_f32 v25, v124, v101, v25 op_sel:[1,0,0] op_sel_hi:[1,0,0]
	v_add_f32_dpp v226, v226, v226 row_half_mirror row_mask:0xf bank_mask:0xf bound_ctrl:1
	v_fma_mix_f32 v26, v125, v101, v26 op_sel:[0,0,0] op_sel_hi:[1,0,0]
	v_fma_mix_f32 v27, v125, v101, v27 op_sel:[1,0,0] op_sel_hi:[1,0,0]
	v_add_f32_dpp v226, v226, v226 row_mirror row_mask:0xf bank_mask:0xf bound_ctrl:1
	v_fma_mix_f32 v24, v122, v226, v24 op_sel:[0,0,0] op_sel_hi:[1,0,0]
	v_fma_mix_f32 v25, v122, v226, v25 op_sel:[1,0,0] op_sel_hi:[1,0,0]
	v_fma_mix_f32 v26, v123, v226, v26 op_sel:[0,0,0] op_sel_hi:[1,0,0]
	v_fma_mix_f32 v27, v123, v226, v27 op_sel:[1,0,0] op_sel_hi:[1,0,0]
	v_fma_mix_f32 v224, v24, v128, 0 op_sel:[0,0,0] op_sel_hi:[0,1,0]
	v_fma_mix_f32 v225, v26, v129, 0 op_sel:[0,0,0] op_sel_hi:[0,1,0]
	v_fma_mix_f32 v218, v24, v126, 0 op_sel:[0,0,0] op_sel_hi:[0,1,0]
	v_fma_mix_f32 v224, v25, v128, v224 op_sel:[0,1,0] op_sel_hi:[0,1,0]
	v_fma_mix_f32 v225, v27, v129, v225 op_sel:[0,1,0] op_sel_hi:[0,1,0]
	v_fma_mix_f32 v218, v25, v126, v218 op_sel:[0,1,0] op_sel_hi:[0,1,0]
	v_add_f32 v224, v224, v225
	v_fma_mix_f32 v218, v26, v127, v218 op_sel:[0,0,0] op_sel_hi:[0,1,0]
	v_fma_mix_f32 v218, v27, v127, v218 op_sel:[0,1,0] op_sel_hi:[0,1,0]
	v_fma_mix_f32 v24, v108, v24, v24 op_sel:[0,0,0] op_sel_hi:[1,0,0]
; __device__ __forceinline__ void scan_step(f32x4& S, float& ypo, const u32x4& h0, const u32x4& h1, unsigned e01, unsigned e23, unsigned r01, unsigned r23, float vi) {
;     float s0 = S[0], s1 = S[1], s2 = S[2], s3 = S[3], sa, yp, sb;
;     asm volatile(
;         MIX_SH("%[sa]", "%[s0]", "%[n01]", "0", "0") MIX_SH("%[sb]", "%[s2]", "%[n23]", "0", "0") MIX_SH("%[yp]", "%[s0]", "%[r01]", "0", "0")
;         MIX_SH("%[sa]", "%[s1]", "%[n01]", "%[sa]", "1") MIX_SH("%[sb]", "%[s3]", "%[n23]", "%[sb]", "1") MIX_SH("%[yp]", "%[s1]", "%[r01]", "%[yp]", "1")
;         "v_add_f32 %[sa], %[sa], %[sb]\n\t" MIX_SH("%[yp]", "%[s2]", "%[r23]", "%[yp]", "0") MIX_SH("%[yp]", "%[s3]", "%[r23]", "%[yp]", "1")
;         "v_fma_mix_f32 %[s0], %[e01], %[s0], %[s0] op_sel:[0,0,0] op_sel_hi:[1,0,0]\n\t" "v_fma_mix_f32 %[s1], %[e01], %[s1], %[s1] op_sel:[1,0,0] op_sel_hi:[1,0,0]\n\t"
;         DPP_ADD("%[sa]", "quad_perm:[1,0,3,2]") DPP_ADD("%[yp]", "quad_perm:[1,0,3,2]")
;         "v_fma_mix_f32 %[s2], %[e23], %[s2], %[s2] op_sel:[0,0,0] op_sel_hi:[1,0,0]\n\t" "v_fma_mix_f32 %[s3], %[e23], %[s3], %[s3] op_sel:[1,0,0] op_sel_hi:[1,0,0]\n\t"
;         DPP_ADD("%[sa]", "quad_perm:[2,3,0,1]") DPP_ADD("%[yp]", "quad_perm:[2,3,0,1]")
;         MIX_HS("%[s0]", "%[p01]", "%[vi]", "0") MIX_HS("%[s1]", "%[p01]", "%[vi]", "1")
;         DPP_ADD("%[sa]", "row_half_mirror")
;         MIX_HS("%[s2]", "%[p23]", "%[vi]", "0") MIX_HS("%[s3]", "%[p23]", "%[vi]", "1")
;         DPP_ADD("%[sa]", "row_mirror")
;         MIX_HS("%[s0]", "%[b01]", "%[sa]", "0") MIX_HS("%[s1]", "%[b01]", "%[sa]", "1") MIX_HS("%[s2]", "%[b23]", "%[sa]", "0") "v_fma_mix_f32 %[s3], %[b23], %[sa], %[s3] op_sel:[1,0,0] op_sel_hi:[1,0,0]"
;         : [s0] "+v"(s0), [s1] "+v"(s1), [s2] "+v"(s2), [s3] "+v"(s3), [sa] "=&v"(sa), [yp] "=&v"(yp), [sb] "=&v"(sb)
;         : [n01] "v"(h0.x), [n23] "v"(h0.y), [b01] "v"(h0.z), [b23] "v"(h0.w), [p01] "v"(h1.x), [p23] "v"(h1.y), [r01] "v"(r01), [r23] "v"(r23),
;           [e01] "v"(e01), [e23] "v"(e23), [vi] "v"(vi));
;     S[0] = s0; S[1] = s1; S[2] = s2; S[3] = s3; ypo = yp;
	v_fma_mix_f32 v25, v108, v25, v25 op_sel:[1,0,0] op_sel_hi:[1,0,0]
	v_add_f32_dpp v224, v224, v224 quad_perm:[1,0,3,2] row_mask:0xf bank_mask:0xf bound_ctrl:1
	v_add_f32_dpp v218, v218, v218 quad_perm:[1,0,3,2] row_mask:0xf bank_mask:0xf bound_ctrl:1
	v_fma_mix_f32 v26, v109, v26, v26 op_sel:[0,0,0] op_sel_hi:[1,0,0]
	v_fma_mix_f32 v27, v109, v27, v27 op_sel:[1,0,0] op_sel_hi:[1,0,0]
	v_add_f32_dpp v224, v224, v224 quad_perm:[2,3,0,1] row_mask:0xf bank_mask:0xf bound_ctrl:1
	v_add_f32_dpp v218, v218, v218 quad_perm:[2,3,0,1] row_mask:0xf bank_mask:0xf bound_ctrl:1
	v_fma_mix_f32 v24, v132, v102, v24 op_sel:[0,0,0] op_sel_hi:[1,0,0]
	v_fma_mix_f32 v25, v132, v102, v25 op_sel:[1,0,0] op_sel_hi:[1,0,0]
	v_add_f32_dpp v224, v224, v224 row_half_mirror row_mask:0xf bank_mask:0xf bound_ctrl:1
	v_fma_mix_f32 v26, v133, v102, v26 op_sel:[0,0,0] op_sel_hi:[1,0,0]
	v_fma_mix_f32 v27, v133, v102, v27 op_sel:[1,0,0] op_sel_hi:[1,0,0]
	v_add_f32_dpp v224, v224, v224 row_mirror row_mask:0xf bank_mask:0xf bound_ctrl:1
	v_fma_mix_f32 v24, v130, v224, v24 op_sel:[0,0,0] op_sel_hi:[1,0,0]
	v_fma_mix_f32 v25, v130, v224, v25 op_sel:[1,0,0] op_sel_hi:[1,0,0]
	v_fma_mix_f32 v26, v131, v224, v26 op_sel:[0,0,0] op_sel_hi:[1,0,0]
	v_fma_mix_f32 v27, v131, v224, v27 op_sel:[1,0,0] op_sel_hi:[1,0,0]
	v_fma_mix_f32 v226, v24, v140, 0 op_sel:[0,0,0] op_sel_hi:[0,1,0]
	v_fma_mix_f32 v227, v26, v141, 0 op_sel:[0,0,0] op_sel_hi:[0,1,0]
	v_fma_mix_f32 v219, v24, v134, 0 op_sel:[0,0,0] op_sel_hi:[0,1,0]
	v_fma_mix_f32 v226, v25, v140, v226 op_sel:[0,1,0] op_sel_hi:[0,1,0]
	v_fma_mix_f32 v227, v27, v141, v227 op_sel:[0,1,0] op_sel_hi:[0,1,0]
	v_fma_mix_f32 v219, v25, v134, v219 op_sel:[0,1,0] op_sel_hi:[0,1,0]
	v_add_f32 v226, v226, v227
	v_fma_mix_f32 v219, v26, v135, v219 op_sel:[0,0,0] op_sel_hi:[0,1,0]
	v_fma_mix_f32 v219, v27, v135, v219 op_sel:[0,1,0] op_sel_hi:[0,1,0]
	v_fma_mix_f32 v24, v110, v24, v24 op_sel:[0,0,0] op_sel_hi:[1,0,0]
	v_fma_mix_f32 v25, v110, v25, v25 op_sel:[1,0,0] op_sel_hi:[1,0,0]
	v_add_f32_dpp v226, v226, v226 quad_perm:[1,0,3,2] row_mask:0xf bank_mask:0xf bound_ctrl:1
	v_add_f32_dpp v219, v219, v219 quad_perm:[1,0,3,2] row_mask:0xf bank_mask:0xf bound_ctrl:1
	v_fma_mix_f32 v26, v111, v26, v26 op_sel:[0,0,0] op_sel_hi:[1,0,0]
	v_fma_mix_f32 v27, v111, v27, v27 op_sel:[1,0,0] op_sel_hi:[1,0,0]
	v_add_f32_dpp v226, v226, v226 quad_perm:[2,3,0,1] row_mask:0xf bank_mask:0xf bound_ctrl:1
	v_add_f32_dpp v219, v219, v219 quad_perm:[2,3,0,1] row_mask:0xf bank_mask:0xf bound_ctrl:1
	v_fma_mix_f32 v24, v52, v103, v24 op_sel:[0,0,0] op_sel_hi:[1,0,0]
	v_fma_mix_f32 v25, v52, v103, v25 op_sel:[1,0,0] op_sel_hi:[1,0,0]
	v_add_f32_dpp v226, v226, v226 row_half_mirror row_mask:0xf bank_mask:0xf bound_ctrl:1
	v_fma_mix_f32 v26, v53, v103, v26 op_sel:[0,0,0] op_sel_hi:[1,0,0]
	v_fma_mix_f32 v27, v53, v103, v27 op_sel:[1,0,0] op_sel_hi:[1,0,0]
	v_add_f32_dpp v226, v226, v226 row_mirror row_mask:0xf bank_mask:0xf bound_ctrl:1
	v_fma_mix_f32 v24, v142, v226, v24 op_sel:[0,0,0] op_sel_hi:[1,0,0]
	v_fma_mix_f32 v25, v142, v226, v25 op_sel:[1,0,0] op_sel_hi:[1,0,0]
	v_fma_mix_f32 v26, v143, v226, v26 op_sel:[0,0,0] op_sel_hi:[1,0,0]
	v_fma_mix_f32 v27, v143, v226, v27 op_sel:[1,0,0] op_sel_hi:[1,0,0]
	s_and_saveexec_b64 s[44:45], s[10:11]
	ds_write_b128 v99, v[216:219]
	s_or_b64 exec, exec, s[44:45]
	v_mov_b32_e32 v228, v54
	v_mov_b32_e32 v229, v55
	ds_read_b128 v[100:103], v61 offset:24608
	ds_read_b128 v[104:107], v60 offset:16896
	ds_read_b128 v[108:111], v60 offset:18944
	ds_read_b128 v[112:115], v60 offset:2048
	ds_read_b128 v[116:119], v60 offset:10240
	ds_read_b128 v[120:123], v60 offset:2304
	ds_read_b128 v[124:127], v60 offset:10496
	ds_read_b128 v[128:131], v60 offset:2560
	ds_read_b128 v[132:135], v60 offset:10752
	ds_read_b128 v[140:143], v60 offset:2816
	ds_read_b128 v[52:55], v60 offset:11008
	s_waitcnt lgkmcnt(11)
	v_fma_mix_f32 v224, v24, v184, 0 op_sel:[0,0,0] op_sel_hi:[0,1,0]
	v_fma_mix_f32 v225, v26, v185, 0 op_sel:[0,0,0] op_sel_hi:[0,1,0]
	v_fma_mix_f32 v220, v24, v228, 0 op_sel:[0,0,0] op_sel_hi:[0,1,0]
	v_fma_mix_f32 v224, v25, v184, v224 op_sel:[0,1,0] op_sel_hi:[0,1,0]
	v_fma_mix_f32 v225, v27, v185, v225 op_sel:[0,1,0] op_sel_hi:[0,1,0]
	v_fma_mix_f32 v220, v25, v228, v220 op_sel:[0,1,0] op_sel_hi:[0,1,0]
	v_add_f32 v224, v224, v225
	v_fma_mix_f32 v220, v26, v229, v220 op_sel:[0,0,0] op_sel_hi:[0,1,0]
	v_fma_mix_f32 v220, v27, v229, v220 op_sel:[0,1,0] op_sel_hi:[0,1,0]
	v_fma_mix_f32 v24, v176, v24, v24 op_sel:[0,0,0] op_sel_hi:[1,0,0]
	v_fma_mix_f32 v25, v176, v25, v25 op_sel:[1,0,0] op_sel_hi:[1,0,0]
	v_add_f32_dpp v224, v224, v224 quad_perm:[1,0,3,2] row_mask:0xf bank_mask:0xf bound_ctrl:1
	v_add_f32_dpp v220, v220, v220 quad_perm:[1,0,3,2] row_mask:0xf bank_mask:0xf bound_ctrl:1
	v_fma_mix_f32 v26, v177, v26, v26 op_sel:[0,0,0] op_sel_hi:[1,0,0]
	v_fma_mix_f32 v27, v177, v27, v27 op_sel:[1,0,0] op_sel_hi:[1,0,0]
	v_add_f32_dpp v224, v224, v224 quad_perm:[2,3,0,1] row_mask:0xf bank_mask:0xf bound_ctrl:1
	v_add_f32_dpp v220, v220, v220 quad_perm:[2,3,0,1] row_mask:0xf bank_mask:0xf bound_ctrl:1
	v_fma_mix_f32 v24, v188, v172, v24 op_sel:[0,0,0] op_sel_hi:[1,0,0]
	v_fma_mix_f32 v25, v188, v172, v25 op_sel:[1,0,0] op_sel_hi:[1,0,0]
	v_add_f32_dpp v224, v224, v224 row_half_mirror row_mask:0xf bank_mask:0xf bound_ctrl:1
	v_fma_mix_f32 v26, v189, v172, v26 op_sel:[0,0,0] op_sel_hi:[1,0,0]
	v_fma_mix_f32 v27, v189, v172, v27 op_sel:[1,0,0] op_sel_hi:[1,0,0]
	v_add_f32_dpp v224, v224, v224 row_mirror row_mask:0xf bank_mask:0xf bound_ctrl:1
	v_fma_mix_f32 v24, v186, v224, v24 op_sel:[0,0,0] op_sel_hi:[1,0,0]
; __device__ __forceinline__ void scan_step(f32x4& S, float& ypo, const u32x4& h0, const u32x4& h1, unsigned e01, unsigned e23, unsigned r01, unsigned r23, float vi) {
;     float s0 = S[0], s1 = S[1], s2 = S[2], s3 = S[3], sa, yp, sb;
;     asm volatile(
;         MIX_SH("%[sa]", "%[s0]", "%[n01]", "0", "0") MIX_SH("%[sb]", "%[s2]", "%[n23]", "0", "0") MIX_SH("%[yp]", "%[s0]", "%[r01]", "0", "0")
;         MIX_SH("%[sa]", "%[s1]", "%[n01]", "%[sa]", "1") MIX_SH("%[sb]", "%[s3]", "%[n23]", "%[sb]", "1") MIX_SH("%[yp]", "%[s1]", "%[r01]", "%[yp]", "1")
;         "v_add_f32 %[sa], %[sa], %[sb]\n\t" MIX_SH("%[yp]", "%[s2]", "%[r23]", "%[yp]", "0") MIX_SH("%[yp]", "%[s3]", "%[r23]", "%[yp]", "1")
;         "v_fma_mix_f32 %[s0], %[e01], %[s0], %[s0] op_sel:[0,0,0] op_sel_hi:[1,0,0]\n\t" "v_fma_mix_f32 %[s1], %[e01], %[s1], %[s1] op_sel:[1,0,0] op_sel_hi:[1,0,0]\n\t"
;         DPP_ADD("%[sa]", "quad_perm:[1,0,3,2]") DPP_ADD("%[yp]", "quad_perm:[1,0,3,2]")
;         "v_fma_mix_f32 %[s2], %[e23], %[s2], %[s2] op_sel:[0,0,0] op_sel_hi:[1,0,0]\n\t" "v_fma_mix_f32 %[s3], %[e23], %[s3], %[s3] op_sel:[1,0,0] op_sel_hi:[1,0,0]\n\t"
;         DPP_ADD("%[sa]", "quad_perm:[2,3,0,1]") DPP_ADD("%[yp]", "quad_perm:[2,3,0,1]")
;         MIX_HS("%[s0]", "%[p01]", "%[vi]", "0") MIX_HS("%[s1]", "%[p01]", "%[vi]", "1")
;         DPP_ADD("%[sa]", "row_half_mirror")
;         MIX_HS("%[s2]", "%[p23]", "%[vi]", "0") MIX_HS("%[s3]", "%[p23]", "%[vi]", "1")
;         DPP_ADD("%[sa]", "row_mirror")
;         MIX_HS("%[s0]", "%[b01]", "%[sa]", "0") MIX_HS("%[s1]", "%[b01]", "%[sa]", "1") MIX_HS("%[s2]", "%[b23]", "%[sa]", "0") "v_fma_mix_f32 %[s3], %[b23], %[sa], %[s3] op_sel:[1,0,0] op_sel_hi:[1,0,0]"
;         : [s0] "+v"(s0), [s1] "+v"(s1), [s2] "+v"(s2), [s3] "+v"(s3), [sa] "=&v"(sa), [yp] "=&v"(yp), [sb] "=&v"(sb)
;         : [n01] "v"(h0.x), [n23] "v"(h0.y), [b01] "v"(h0.z), [b23] "v"(h0.w), [p01] "v"(h1.x), [p23] "v"(h1.y), [r01] "v"(r01), [r23] "v"(r23),
;           [e01] "v"(e01), [e23] "v"(e23), [vi] "v"(vi));
;     S[0] = s0; S[1] = s1; S[2] = s2; S[3] = s3; ypo = yp;
	v_fma_mix_f32 v25, v186, v224, v25 op_sel:[1,0,0] op_sel_hi:[1,0,0]
	v_fma_mix_f32 v26, v187, v224, v26 op_sel:[0,0,0] op_sel_hi:[1,0,0]
	v_fma_mix_f32 v27, v187, v224, v27 op_sel:[1,0,0] op_sel_hi:[1,0,0]
	v_fma_mix_f32 v226, v24, v192, 0 op_sel:[0,0,0] op_sel_hi:[0,1,0]
	v_fma_mix_f32 v227, v26, v193, 0 op_sel:[0,0,0] op_sel_hi:[0,1,0]
	v_fma_mix_f32 v221, v24, v190, 0 op_sel:[0,0,0] op_sel_hi:[0,1,0]
	v_fma_mix_f32 v226, v25, v192, v226 op_sel:[0,1,0] op_sel_hi:[0,1,0]
	v_fma_mix_f32 v227, v27, v193, v227 op_sel:[0,1,0] op_sel_hi:[0,1,0]
	v_fma_mix_f32 v221, v25, v190, v221 op_sel:[0,1,0] op_sel_hi:[0,1,0]
	v_add_f32 v226, v226, v227
	v_fma_mix_f32 v221, v26, v191, v221 op_sel:[0,0,0] op_sel_hi:[0,1,0]
	v_fma_mix_f32 v221, v27, v191, v221 op_sel:[0,1,0] op_sel_hi:[0,1,0]
	v_fma_mix_f32 v24, v178, v24, v24 op_sel:[0,0,0] op_sel_hi:[1,0,0]
	v_fma_mix_f32 v25, v178, v25, v25 op_sel:[1,0,0] op_sel_hi:[1,0,0]
	v_add_f32_dpp v226, v226, v226 quad_perm:[1,0,3,2] row_mask:0xf bank_mask:0xf bound_ctrl:1
	v_add_f32_dpp v221, v221, v221 quad_perm:[1,0,3,2] row_mask:0xf bank_mask:0xf bound_ctrl:1
	v_fma_mix_f32 v26, v179, v26, v26 op_sel:[0,0,0] op_sel_hi:[1,0,0]
	v_fma_mix_f32 v27, v179, v27, v27 op_sel:[1,0,0] op_sel_hi:[1,0,0]
	v_add_f32_dpp v226, v226, v226 quad_perm:[2,3,0,1] row_mask:0xf bank_mask:0xf bound_ctrl:1
	v_add_f32_dpp v221, v221, v221 quad_perm:[2,3,0,1] row_mask:0xf bank_mask:0xf bound_ctrl:1
	v_fma_mix_f32 v24, v196, v173, v24 op_sel:[0,0,0] op_sel_hi:[1,0,0]
	v_fma_mix_f32 v25, v196, v173, v25 op_sel:[1,0,0] op_sel_hi:[1,0,0]
	v_add_f32_dpp v226, v226, v226 row_half_mirror row_mask:0xf bank_mask:0xf bound_ctrl:1
	v_fma_mix_f32 v26, v197, v173, v26 op_sel:[0,0,0] op_sel_hi:[1,0,0]
	v_fma_mix_f32 v27, v197, v173, v27 op_sel:[1,0,0] op_sel_hi:[1,0,0]
	v_add_f32_dpp v226, v226, v226 row_mirror row_mask:0xf bank_mask:0xf bound_ctrl:1
	v_fma_mix_f32 v24, v194, v226, v24 op_sel:[0,0,0] op_sel_hi:[1,0,0]
	v_fma_mix_f32 v25, v194, v226, v25 op_sel:[1,0,0] op_sel_hi:[1,0,0]
	v_fma_mix_f32 v26, v195, v226, v26 op_sel:[0,0,0] op_sel_hi:[1,0,0]
	v_fma_mix_f32 v27, v195, v226, v27 op_sel:[1,0,0] op_sel_hi:[1,0,0]
	v_fma_mix_f32 v224, v24, v200, 0 op_sel:[0,0,0] op_sel_hi:[0,1,0]
	v_fma_mix_f32 v225, v26, v201, 0 op_sel:[0,0,0] op_sel_hi:[0,1,0]
	v_fma_mix_f32 v222, v24, v198, 0 op_sel:[0,0,0] op_sel_hi:[0,1,0]
	v_fma_mix_f32 v224, v25, v200, v224 op_sel:[0,1,0] op_sel_hi:[0,1,0]
	v_fma_mix_f32 v225, v27, v201, v225 op_sel:[0,1,0] op_sel_hi:[0,1,0]
	v_fma_mix_f32 v222, v25, v198, v222 op_sel:[0,1,0] op_sel_hi:[0,1,0]
	v_add_f32 v224, v224, v225
	v_fma_mix_f32 v222, v26, v199, v222 op_sel:[0,0,0] op_sel_hi:[0,1,0]
	v_fma_mix_f32 v222, v27, v199, v222 op_sel:[0,1,0] op_sel_hi:[0,1,0]
	v_fma_mix_f32 v24, v180, v24, v24 op_sel:[0,0,0] op_sel_hi:[1,0,0]
	v_fma_mix_f32 v25, v180, v25, v25 op_sel:[1,0,0] op_sel_hi:[1,0,0]
	v_add_f32_dpp v224, v224, v224 quad_perm:[1,0,3,2] row_mask:0xf bank_mask:0xf bound_ctrl:1
	v_add_f32_dpp v222, v222, v222 quad_perm:[1,0,3,2] row_mask:0xf bank_mask:0xf bound_ctrl:1
	v_fma_mix_f32 v26, v181, v26, v26 op_sel:[0,0,0] op_sel_hi:[1,0,0]
	v_fma_mix_f32 v27, v181, v27, v27 op_sel:[1,0,0] op_sel_hi:[1,0,0]
	v_add_f32_dpp v224, v224, v224 quad_perm:[2,3,0,1] row_mask:0xf bank_mask:0xf bound_ctrl:1
	v_add_f32_dpp v222, v222, v222 quad_perm:[2,3,0,1] row_mask:0xf bank_mask:0xf bound_ctrl:1
	v_fma_mix_f32 v24, v204, v174, v24 op_sel:[0,0,0] op_sel_hi:[1,0,0]
	v_fma_mix_f32 v25, v204, v174, v25 op_sel:[1,0,0] op_sel_hi:[1,0,0]
	v_add_f32_dpp v224, v224, v224 row_half_mirror row_mask:0xf bank_mask:0xf bound_ctrl:1
	v_fma_mix_f32 v26, v205, v174, v26 op_sel:[0,0,0] op_sel_hi:[1,0,0]
	v_fma_mix_f32 v27, v205, v174, v27 op_sel:[1,0,0] op_sel_hi:[1,0,0]
	v_add_f32_dpp v224, v224, v224 row_mirror row_mask:0xf bank_mask:0xf bound_ctrl:1
	v_fma_mix_f32 v24, v202, v224, v24 op_sel:[0,0,0] op_sel_hi:[1,0,0]
	v_fma_mix_f32 v25, v202, v224, v25 op_sel:[1,0,0] op_sel_hi:[1,0,0]
	v_fma_mix_f32 v26, v203, v224, v26 op_sel:[0,0,0] op_sel_hi:[1,0,0]
	v_fma_mix_f32 v27, v203, v224, v27 op_sel:[1,0,0] op_sel_hi:[1,0,0]
	v_fma_mix_f32 v226, v24, v208, 0 op_sel:[0,0,0] op_sel_hi:[0,1,0]
	v_fma_mix_f32 v227, v26, v209, 0 op_sel:[0,0,0] op_sel_hi:[0,1,0]
	v_fma_mix_f32 v223, v24, v206, 0 op_sel:[0,0,0] op_sel_hi:[0,1,0]
	v_fma_mix_f32 v226, v25, v208, v226 op_sel:[0,1,0] op_sel_hi:[0,1,0]
	v_fma_mix_f32 v227, v27, v209, v227 op_sel:[0,1,0] op_sel_hi:[0,1,0]
	v_fma_mix_f32 v223, v25, v206, v223 op_sel:[0,1,0] op_sel_hi:[0,1,0]
	v_add_f32 v226, v226, v227
	v_fma_mix_f32 v223, v26, v207, v223 op_sel:[0,0,0] op_sel_hi:[0,1,0]
	v_fma_mix_f32 v223, v27, v207, v223 op_sel:[0,1,0] op_sel_hi:[0,1,0]
	v_fma_mix_f32 v24, v182, v24, v24 op_sel:[0,0,0] op_sel_hi:[1,0,0]
	v_fma_mix_f32 v25, v182, v25, v25 op_sel:[1,0,0] op_sel_hi:[1,0,0]
	v_add_f32_dpp v226, v226, v226 quad_perm:[1,0,3,2] row_mask:0xf bank_mask:0xf bound_ctrl:1
	v_add_f32_dpp v223, v223, v223 quad_perm:[1,0,3,2] row_mask:0xf bank_mask:0xf bound_ctrl:1
	v_fma_mix_f32 v26, v183, v26, v26 op_sel:[0,0,0] op_sel_hi:[1,0,0]
	v_fma_mix_f32 v27, v183, v27, v27 op_sel:[1,0,0] op_sel_hi:[1,0,0]
	v_add_f32_dpp v226, v226, v226 quad_perm:[2,3,0,1] row_mask:0xf bank_mask:0xf bound_ctrl:1
	v_add_f32_dpp v223, v223, v223 quad_perm:[2,3,0,1] row_mask:0xf bank_mask:0xf bound_ctrl:1
	v_fma_mix_f32 v24, v212, v175, v24 op_sel:[0,0,0] op_sel_hi:[1,0,0]
	v_fma_mix_f32 v25, v212, v175, v25 op_sel:[1,0,0] op_sel_hi:[1,0,0]
	v_add_f32_dpp v226, v226, v226 row_half_mirror row_mask:0xf bank_mask:0xf bound_ctrl:1
	v_fma_mix_f32 v26, v213, v175, v26 op_sel:[0,0,0] op_sel_hi:[1,0,0]
	v_fma_mix_f32 v27, v213, v175, v27 op_sel:[1,0,0] op_sel_hi:[1,0,0]
	v_add_f32_dpp v226, v226, v226 row_mirror row_mask:0xf bank_mask:0xf bound_ctrl:1
	v_fma_mix_f32 v24, v210, v226, v24 op_sel:[0,0,0] op_sel_hi:[1,0,0]
	v_fma_mix_f32 v25, v210, v226, v25 op_sel:[1,0,0] op_sel_hi:[1,0,0]
	v_fma_mix_f32 v26, v211, v226, v26 op_sel:[0,0,0] op_sel_hi:[1,0,0]
	v_fma_mix_f32 v27, v211, v226, v27 op_sel:[1,0,0] op_sel_hi:[1,0,0]
	s_and_saveexec_b64 s[44:45], s[10:11]
	ds_write_b128 v99, v[220:223] offset:16
	s_or_b64 exec, exec, s[44:45]
	v_mov_b32_e32 v228, v214
	v_mov_b32_e32 v229, v215
	ds_read_b128 v[172:175], v61 offset:24624
	ds_read_b128 v[176:179], v60 offset:17152
	ds_read_b128 v[180:183], v60 offset:19200
	ds_read_b128 v[184:187], v60 offset:3072
	ds_read_b128 v[188:191], v60 offset:11264
	ds_read_b128 v[192:195], v60 offset:3328
	ds_read_b128 v[196:199], v60 offset:11520
	ds_read_b128 v[200:203], v60 offset:3584
	ds_read_b128 v[204:207], v60 offset:11776
	ds_read_b128 v[208:211], v60 offset:3840
	ds_read_b128 v[212:215], v60 offset:12032
	s_waitcnt lgkmcnt(11)
; __device__ __forceinline__ void scan_step(f32x4& S, float& ypo, const u32x4& h0, const u32x4& h1, unsigned e01, unsigned e23, unsigned r01, unsigned r23, float vi) {
;     float s0 = S[0], s1 = S[1], s2 = S[2], s3 = S[3], sa, yp, sb;
;     asm volatile(
;         MIX_SH("%[sa]", "%[s0]", "%[n01]", "0", "0") MIX_SH("%[sb]", "%[s2]", "%[n23]", "0", "0") MIX_SH("%[yp]", "%[s0]", "%[r01]", "0", "0")
;         MIX_SH("%[sa]", "%[s1]", "%[n01]", "%[sa]", "1") MIX_SH("%[sb]", "%[s3]", "%[n23]", "%[sb]", "1") MIX_SH("%[yp]", "%[s1]", "%[r01]", "%[yp]", "1")
;         "v_add_f32 %[sa], %[sa], %[sb]\n\t" MIX_SH("%[yp]", "%[s2]", "%[r23]", "%[yp]", "0") MIX_SH("%[yp]", "%[s3]", "%[r23]", "%[yp]", "1")
;         "v_fma_mix_f32 %[s0], %[e01], %[s0], %[s0] op_sel:[0,0,0] op_sel_hi:[1,0,0]\n\t" "v_fma_mix_f32 %[s1], %[e01], %[s1], %[s1] op_sel:[1,0,0] op_sel_hi:[1,0,0]\n\t"
;         DPP_ADD("%[sa]", "quad_perm:[1,0,3,2]") DPP_ADD("%[yp]", "quad_perm:[1,0,3,2]")
;         "v_fma_mix_f32 %[s2], %[e23], %[s2], %[s2] op_sel:[0,0,0] op_sel_hi:[1,0,0]\n\t" "v_fma_mix_f32 %[s3], %[e23], %[s3], %[s3] op_sel:[1,0,0] op_sel_hi:[1,0,0]\n\t"
;         DPP_ADD("%[sa]", "quad_perm:[2,3,0,1]") DPP_ADD("%[yp]", "quad_perm:[2,3,0,1]")
;         MIX_HS("%[s0]", "%[p01]", "%[vi]", "0") MIX_HS("%[s1]", "%[p01]", "%[vi]", "1")
;         DPP_ADD("%[sa]", "row_half_mirror")
;         MIX_HS("%[s2]", "%[p23]", "%[vi]", "0") MIX_HS("%[s3]", "%[p23]", "%[vi]", "1")
;         DPP_ADD("%[sa]", "row_mirror")
;         MIX_HS("%[s0]", "%[b01]", "%[sa]", "0") MIX_HS("%[s1]", "%[b01]", "%[sa]", "1") MIX_HS("%[s2]", "%[b23]", "%[sa]", "0") "v_fma_mix_f32 %[s3], %[b23], %[sa], %[s3] op_sel:[1,0,0] op_sel_hi:[1,0,0]"
;         : [s0] "+v"(s0), [s1] "+v"(s1), [s2] "+v"(s2), [s3] "+v"(s3), [sa] "=&v"(sa), [yp] "=&v"(yp), [sb] "=&v"(sb)
;         : [n01] "v"(h0.x), [n23] "v"(h0.y), [b01] "v"(h0.z), [b23] "v"(h0.w), [p01] "v"(h1.x), [p23] "v"(h1.y), [r01] "v"(r01), [r23] "v"(r23),
;           [e01] "v"(e01), [e23] "v"(e23), [vi] "v"(vi));
;     S[0] = s0; S[1] = s1; S[2] = s2; S[3] = s3; ypo = yp;
	v_fma_mix_f32 v224, v24, v112, 0 op_sel:[0,0,0] op_sel_hi:[0,1,0]
	v_fma_mix_f32 v225, v26, v113, 0 op_sel:[0,0,0] op_sel_hi:[0,1,0]
	v_fma_mix_f32 v216, v24, v228, 0 op_sel:[0,0,0] op_sel_hi:[0,1,0]
	v_fma_mix_f32 v224, v25, v112, v224 op_sel:[0,1,0] op_sel_hi:[0,1,0]
	v_fma_mix_f32 v225, v27, v113, v225 op_sel:[0,1,0] op_sel_hi:[0,1,0]
	v_fma_mix_f32 v216, v25, v228, v216 op_sel:[0,1,0] op_sel_hi:[0,1,0]
	v_add_f32 v224, v224, v225
	v_fma_mix_f32 v216, v26, v229, v216 op_sel:[0,0,0] op_sel_hi:[0,1,0]
	v_fma_mix_f32 v216, v27, v229, v216 op_sel:[0,1,0] op_sel_hi:[0,1,0]
	v_fma_mix_f32 v24, v104, v24, v24 op_sel:[0,0,0] op_sel_hi:[1,0,0]
	v_fma_mix_f32 v25, v104, v25, v25 op_sel:[1,0,0] op_sel_hi:[1,0,0]
	v_add_f32_dpp v224, v224, v224 quad_perm:[1,0,3,2] row_mask:0xf bank_mask:0xf bound_ctrl:1
	v_add_f32_dpp v216, v216, v216 quad_perm:[1,0,3,2] row_mask:0xf bank_mask:0xf bound_ctrl:1
	v_fma_mix_f32 v26, v105, v26, v26 op_sel:[0,0,0] op_sel_hi:[1,0,0]
	v_fma_mix_f32 v27, v105, v27, v27 op_sel:[1,0,0] op_sel_hi:[1,0,0]
	v_add_f32_dpp v224, v224, v224 quad_perm:[2,3,0,1] row_mask:0xf bank_mask:0xf bound_ctrl:1
	v_add_f32_dpp v216, v216, v216 quad_perm:[2,3,0,1] row_mask:0xf bank_mask:0xf bound_ctrl:1
	v_fma_mix_f32 v24, v116, v100, v24 op_sel:[0,0,0] op_sel_hi:[1,0,0]
	v_fma_mix_f32 v25, v116, v100, v25 op_sel:[1,0,0] op_sel_hi:[1,0,0]
	v_add_f32_dpp v224, v224, v224 row_half_mirror row_mask:0xf bank_mask:0xf bound_ctrl:1
	v_fma_mix_f32 v26, v117, v100, v26 op_sel:[0,0,0] op_sel_hi:[1,0,0]
	v_fma_mix_f32 v27, v117, v100, v27 op_sel:[1,0,0] op_sel_hi:[1,0,0]
	v_add_f32_dpp v224, v224, v224 row_mirror row_mask:0xf bank_mask:0xf bound_ctrl:1
	v_fma_mix_f32 v24, v114, v224, v24 op_sel:[0,0,0] op_sel_hi:[1,0,0]
	v_fma_mix_f32 v25, v114, v224, v25 op_sel:[1,0,0] op_sel_hi:[1,0,0]
	v_fma_mix_f32 v26, v115, v224, v26 op_sel:[0,0,0] op_sel_hi:[1,0,0]
	v_fma_mix_f32 v27, v115, v224, v27 op_sel:[1,0,0] op_sel_hi:[1,0,0]
	v_fma_mix_f32 v226, v24, v120, 0 op_sel:[0,0,0] op_sel_hi:[0,1,0]
	v_fma_mix_f32 v227, v26, v121, 0 op_sel:[0,0,0] op_sel_hi:[0,1,0]
	v_fma_mix_f32 v217, v24, v118, 0 op_sel:[0,0,0] op_sel_hi:[0,1,0]
	v_fma_mix_f32 v226, v25, v120, v226 op_sel:[0,1,0] op_sel_hi:[0,1,0]
	v_fma_mix_f32 v227, v27, v121, v227 op_sel:[0,1,0] op_sel_hi:[0,1,0]
	v_fma_mix_f32 v217, v25, v118, v217 op_sel:[0,1,0] op_sel_hi:[0,1,0]
	v_add_f32 v226, v226, v227
	v_fma_mix_f32 v217, v26, v119, v217 op_sel:[0,0,0] op_sel_hi:[0,1,0]
	v_fma_mix_f32 v217, v27, v119, v217 op_sel:[0,1,0] op_sel_hi:[0,1,0]
	v_fma_mix_f32 v24, v106, v24, v24 op_sel:[0,0,0] op_sel_hi:[1,0,0]
	v_fma_mix_f32 v25, v106, v25, v25 op_sel:[1,0,0] op_sel_hi:[1,0,0]
	v_add_f32_dpp v226, v226, v226 quad_perm:[1,0,3,2] row_mask:0xf bank_mask:0xf bound_ctrl:1
	v_add_f32_dpp v217, v217, v217 quad_perm:[1,0,3,2] row_mask:0xf bank_mask:0xf bound_ctrl:1
	v_fma_mix_f32 v26, v107, v26, v26 op_sel:[0,0,0] op_sel_hi:[1,0,0]
	v_fma_mix_f32 v27, v107, v27, v27 op_sel:[1,0,0] op_sel_hi:[1,0,0]
	v_add_f32_dpp v226, v226, v226 quad_perm:[2,3,0,1] row_mask:0xf bank_mask:0xf bound_ctrl:1
	v_add_f32_dpp v217, v217, v217 quad_perm:[2,3,0,1] row_mask:0xf bank_mask:0xf bound_ctrl:1
	v_fma_mix_f32 v24, v124, v101, v24 op_sel:[0,0,0] op_sel_hi:[1,0,0]
	v_fma_mix_f32 v25, v124, v101, v25 op_sel:[1,0,0] op_sel_hi:[1,0,0]
	v_add_f32_dpp v226, v226, v226 row_half_mirror row_mask:0xf bank_mask:0xf bound_ctrl:1
	v_fma_mix_f32 v26, v125, v101, v26 op_sel:[0,0,0] op_sel_hi:[1,0,0]
	v_fma_mix_f32 v27, v125, v101, v27 op_sel:[1,0,0] op_sel_hi:[1,0,0]
	v_add_f32_dpp v226, v226, v226 row_mirror row_mask:0xf bank_mask:0xf bound_ctrl:1
	v_fma_mix_f32 v24, v122, v226, v24 op_sel:[0,0,0] op_sel_hi:[1,0,0]
	v_fma_mix_f32 v25, v122, v226, v25 op_sel:[1,0,0] op_sel_hi:[1,0,0]
	v_fma_mix_f32 v26, v123, v226, v26 op_sel:[0,0,0] op_sel_hi:[1,0,0]
	v_fma_mix_f32 v27, v123, v226, v27 op_sel:[1,0,0] op_sel_hi:[1,0,0]
	v_fma_mix_f32 v224, v24, v128, 0 op_sel:[0,0,0] op_sel_hi:[0,1,0]
	v_fma_mix_f32 v225, v26, v129, 0 op_sel:[0,0,0] op_sel_hi:[0,1,0]
	v_fma_mix_f32 v218, v24, v126, 0 op_sel:[0,0,0] op_sel_hi:[0,1,0]
	v_fma_mix_f32 v224, v25, v128, v224 op_sel:[0,1,0] op_sel_hi:[0,1,0]
	v_fma_mix_f32 v225, v27, v129, v225 op_sel:[0,1,0] op_sel_hi:[0,1,0]
	v_fma_mix_f32 v218, v25, v126, v218 op_sel:[0,1,0] op_sel_hi:[0,1,0]
	v_add_f32 v224, v224, v225
	v_fma_mix_f32 v218, v26, v127, v218 op_sel:[0,0,0] op_sel_hi:[0,1,0]
	v_fma_mix_f32 v218, v27, v127, v218 op_sel:[0,1,0] op_sel_hi:[0,1,0]
	v_fma_mix_f32 v24, v108, v24, v24 op_sel:[0,0,0] op_sel_hi:[1,0,0]
	v_fma_mix_f32 v25, v108, v25, v25 op_sel:[1,0,0] op_sel_hi:[1,0,0]
	v_add_f32_dpp v224, v224, v224 quad_perm:[1,0,3,2] row_mask:0xf bank_mask:0xf bound_ctrl:1
	v_add_f32_dpp v218, v218, v218 quad_perm:[1,0,3,2] row_mask:0xf bank_mask:0xf bound_ctrl:1
	v_fma_mix_f32 v26, v109, v26, v26 op_sel:[0,0,0] op_sel_hi:[1,0,0]
	v_fma_mix_f32 v27, v109, v27, v27 op_sel:[1,0,0] op_sel_hi:[1,0,0]
	v_add_f32_dpp v224, v224, v224 quad_perm:[2,3,0,1] row_mask:0xf bank_mask:0xf bound_ctrl:1
	v_add_f32_dpp v218, v218, v218 quad_perm:[2,3,0,1] row_mask:0xf bank_mask:0xf bound_ctrl:1
	v_fma_mix_f32 v24, v132, v102, v24 op_sel:[0,0,0] op_sel_hi:[1,0,0]
	v_fma_mix_f32 v25, v132, v102, v25 op_sel:[1,0,0] op_sel_hi:[1,0,0]
	v_add_f32_dpp v224, v224, v224 row_half_mirror row_mask:0xf bank_mask:0xf bound_ctrl:1
	v_fma_mix_f32 v26, v133, v102, v26 op_sel:[0,0,0] op_sel_hi:[1,0,0]
	v_fma_mix_f32 v27, v133, v102, v27 op_sel:[1,0,0] op_sel_hi:[1,0,0]
	v_add_f32_dpp v224, v224, v224 row_mirror row_mask:0xf bank_mask:0xf bound_ctrl:1
	v_fma_mix_f32 v24, v130, v224, v24 op_sel:[0,0,0] op_sel_hi:[1,0,0]
; __device__ __forceinline__ void scan_step(f32x4& S, float& ypo, const u32x4& h0, const u32x4& h1, unsigned e01, unsigned e23, unsigned r01, unsigned r23, float vi) {
;     float s0 = S[0], s1 = S[1], s2 = S[2], s3 = S[3], sa, yp, sb;
;     asm volatile(
;         MIX_SH("%[sa]", "%[s0]", "%[n01]", "0", "0") MIX_SH("%[sb]", "%[s2]", "%[n23]", "0", "0") MIX_SH("%[yp]", "%[s0]", "%[r01]", "0", "0")
;         MIX_SH("%[sa]", "%[s1]", "%[n01]", "%[sa]", "1") MIX_SH("%[sb]", "%[s3]", "%[n23]", "%[sb]", "1") MIX_SH("%[yp]", "%[s1]", "%[r01]", "%[yp]", "1")
;         "v_add_f32 %[sa], %[sa], %[sb]\n\t" MIX_SH("%[yp]", "%[s2]", "%[r23]", "%[yp]", "0") MIX_SH("%[yp]", "%[s3]", "%[r23]", "%[yp]", "1")
;         "v_fma_mix_f32 %[s0], %[e01], %[s0], %[s0] op_sel:[0,0,0] op_sel_hi:[1,0,0]\n\t" "v_fma_mix_f32 %[s1], %[e01], %[s1], %[s1] op_sel:[1,0,0] op_sel_hi:[1,0,0]\n\t"
;         DPP_ADD("%[sa]", "quad_perm:[1,0,3,2]") DPP_ADD("%[yp]", "quad_perm:[1,0,3,2]")
;         "v_fma_mix_f32 %[s2], %[e23], %[s2], %[s2] op_sel:[0,0,0] op_sel_hi:[1,0,0]\n\t" "v_fma_mix_f32 %[s3], %[e23], %[s3], %[s3] op_sel:[1,0,0] op_sel_hi:[1,0,0]\n\t"
;         DPP_ADD("%[sa]", "quad_perm:[2,3,0,1]") DPP_ADD("%[yp]", "quad_perm:[2,3,0,1]")
;         MIX_HS("%[s0]", "%[p01]", "%[vi]", "0") MIX_HS("%[s1]", "%[p01]", "%[vi]", "1")
;         DPP_ADD("%[sa]", "row_half_mirror")
;         MIX_HS("%[s2]", "%[p23]", "%[vi]", "0") MIX_HS("%[s3]", "%[p23]", "%[vi]", "1")
;         DPP_ADD("%[sa]", "row_mirror")
;         MIX_HS("%[s0]", "%[b01]", "%[sa]", "0") MIX_HS("%[s1]", "%[b01]", "%[sa]", "1") MIX_HS("%[s2]", "%[b23]", "%[sa]", "0") "v_fma_mix_f32 %[s3], %[b23], %[sa], %[s3] op_sel:[1,0,0] op_sel_hi:[1,0,0]"
;         : [s0] "+v"(s0), [s1] "+v"(s1), [s2] "+v"(s2), [s3] "+v"(s3), [sa] "=&v"(sa), [yp] "=&v"(yp), [sb] "=&v"(sb)
;         : [n01] "v"(h0.x), [n23] "v"(h0.y), [b01] "v"(h0.z), [b23] "v"(h0.w), [p01] "v"(h1.x), [p23] "v"(h1.y), [r01] "v"(r01), [r23] "v"(r23),
;           [e01] "v"(e01), [e23] "v"(e23), [vi] "v"(vi));
;     S[0] = s0; S[1] = s1; S[2] = s2; S[3] = s3; ypo = yp;
	v_fma_mix_f32 v25, v130, v224, v25 op_sel:[1,0,0] op_sel_hi:[1,0,0]
	v_fma_mix_f32 v26, v131, v224, v26 op_sel:[0,0,0] op_sel_hi:[1,0,0]
	v_fma_mix_f32 v27, v131, v224, v27 op_sel:[1,0,0] op_sel_hi:[1,0,0]
	v_fma_mix_f32 v226, v24, v140, 0 op_sel:[0,0,0] op_sel_hi:[0,1,0]
	v_fma_mix_f32 v227, v26, v141, 0 op_sel:[0,0,0] op_sel_hi:[0,1,0]
	v_fma_mix_f32 v219, v24, v134, 0 op_sel:[0,0,0] op_sel_hi:[0,1,0]
	v_fma_mix_f32 v226, v25, v140, v226 op_sel:[0,1,0] op_sel_hi:[0,1,0]
	v_fma_mix_f32 v227, v27, v141, v227 op_sel:[0,1,0] op_sel_hi:[0,1,0]
	v_fma_mix_f32 v219, v25, v134, v219 op_sel:[0,1,0] op_sel_hi:[0,1,0]
	v_add_f32 v226, v226, v227
	v_fma_mix_f32 v219, v26, v135, v219 op_sel:[0,0,0] op_sel_hi:[0,1,0]
	v_fma_mix_f32 v219, v27, v135, v219 op_sel:[0,1,0] op_sel_hi:[0,1,0]
	v_fma_mix_f32 v24, v110, v24, v24 op_sel:[0,0,0] op_sel_hi:[1,0,0]
	v_fma_mix_f32 v25, v110, v25, v25 op_sel:[1,0,0] op_sel_hi:[1,0,0]
	v_add_f32_dpp v226, v226, v226 quad_perm:[1,0,3,2] row_mask:0xf bank_mask:0xf bound_ctrl:1
	v_add_f32_dpp v219, v219, v219 quad_perm:[1,0,3,2] row_mask:0xf bank_mask:0xf bound_ctrl:1
	v_fma_mix_f32 v26, v111, v26, v26 op_sel:[0,0,0] op_sel_hi:[1,0,0]
	v_fma_mix_f32 v27, v111, v27, v27 op_sel:[1,0,0] op_sel_hi:[1,0,0]
	v_add_f32_dpp v226, v226, v226 quad_perm:[2,3,0,1] row_mask:0xf bank_mask:0xf bound_ctrl:1
	v_add_f32_dpp v219, v219, v219 quad_perm:[2,3,0,1] row_mask:0xf bank_mask:0xf bound_ctrl:1
	v_fma_mix_f32 v24, v52, v103, v24 op_sel:[0,0,0] op_sel_hi:[1,0,0]
	v_fma_mix_f32 v25, v52, v103, v25 op_sel:[1,0,0] op_sel_hi:[1,0,0]
	v_add_f32_dpp v226, v226, v226 row_half_mirror row_mask:0xf bank_mask:0xf bound_ctrl:1
	v_fma_mix_f32 v26, v53, v103, v26 op_sel:[0,0,0] op_sel_hi:[1,0,0]
	v_fma_mix_f32 v27, v53, v103, v27 op_sel:[1,0,0] op_sel_hi:[1,0,0]
	v_add_f32_dpp v226, v226, v226 row_mirror row_mask:0xf bank_mask:0xf bound_ctrl:1
	v_fma_mix_f32 v24, v142, v226, v24 op_sel:[0,0,0] op_sel_hi:[1,0,0]
	v_fma_mix_f32 v25, v142, v226, v25 op_sel:[1,0,0] op_sel_hi:[1,0,0]
	v_fma_mix_f32 v26, v143, v226, v26 op_sel:[0,0,0] op_sel_hi:[1,0,0]
	v_fma_mix_f32 v27, v143, v226, v27 op_sel:[1,0,0] op_sel_hi:[1,0,0]
	s_and_saveexec_b64 s[44:45], s[10:11]
	ds_write_b128 v99, v[216:219] offset:32
	s_or_b64 exec, exec, s[44:45]
	v_mov_b32_e32 v228, v54
	v_mov_b32_e32 v229, v55
	ds_read_b128 v[100:103], v61 offset:24640
	ds_read_b128 v[104:107], v60 offset:17408
	ds_read_b128 v[108:111], v60 offset:19456
	ds_read_b128 v[112:115], v60 offset:4096
	ds_read_b128 v[116:119], v60 offset:12288
	ds_read_b128 v[120:123], v60 offset:4352
	ds_read_b128 v[124:127], v60 offset:12544
	ds_read_b128 v[128:131], v60 offset:4608
	ds_read_b128 v[132:135], v60 offset:12800
	ds_read_b128 v[140:143], v60 offset:4864
	ds_read_b128 v[52:55], v60 offset:13056
	s_waitcnt lgkmcnt(11)
	v_fma_mix_f32 v224, v24, v184, 0 op_sel:[0,0,0] op_sel_hi:[0,1,0]
	v_fma_mix_f32 v225, v26, v185, 0 op_sel:[0,0,0] op_sel_hi:[0,1,0]
	v_fma_mix_f32 v220, v24, v228, 0 op_sel:[0,0,0] op_sel_hi:[0,1,0]
	v_fma_mix_f32 v224, v25, v184, v224 op_sel:[0,1,0] op_sel_hi:[0,1,0]
	v_fma_mix_f32 v225, v27, v185, v225 op_sel:[0,1,0] op_sel_hi:[0,1,0]
	v_fma_mix_f32 v220, v25, v228, v220 op_sel:[0,1,0] op_sel_hi:[0,1,0]
	v_add_f32 v224, v224, v225
	v_fma_mix_f32 v220, v26, v229, v220 op_sel:[0,0,0] op_sel_hi:[0,1,0]
	v_fma_mix_f32 v220, v27, v229, v220 op_sel:[0,1,0] op_sel_hi:[0,1,0]
	v_fma_mix_f32 v24, v176, v24, v24 op_sel:[0,0,0] op_sel_hi:[1,0,0]
	v_fma_mix_f32 v25, v176, v25, v25 op_sel:[1,0,0] op_sel_hi:[1,0,0]
	v_add_f32_dpp v224, v224, v224 quad_perm:[1,0,3,2] row_mask:0xf bank_mask:0xf bound_ctrl:1
	v_add_f32_dpp v220, v220, v220 quad_perm:[1,0,3,2] row_mask:0xf bank_mask:0xf bound_ctrl:1
	v_fma_mix_f32 v26, v177, v26, v26 op_sel:[0,0,0] op_sel_hi:[1,0,0]
	v_fma_mix_f32 v27, v177, v27, v27 op_sel:[1,0,0] op_sel_hi:[1,0,0]
	v_add_f32_dpp v224, v224, v224 quad_perm:[2,3,0,1] row_mask:0xf bank_mask:0xf bound_ctrl:1
	v_add_f32_dpp v220, v220, v220 quad_perm:[2,3,0,1] row_mask:0xf bank_mask:0xf bound_ctrl:1
	v_fma_mix_f32 v24, v188, v172, v24 op_sel:[0,0,0] op_sel_hi:[1,0,0]
	v_fma_mix_f32 v25, v188, v172, v25 op_sel:[1,0,0] op_sel_hi:[1,0,0]
	v_add_f32_dpp v224, v224, v224 row_half_mirror row_mask:0xf bank_mask:0xf bound_ctrl:1
	v_fma_mix_f32 v26, v189, v172, v26 op_sel:[0,0,0] op_sel_hi:[1,0,0]
	v_fma_mix_f32 v27, v189, v172, v27 op_sel:[1,0,0] op_sel_hi:[1,0,0]
	v_add_f32_dpp v224, v224, v224 row_mirror row_mask:0xf bank_mask:0xf bound_ctrl:1
	v_fma_mix_f32 v24, v186, v224, v24 op_sel:[0,0,0] op_sel_hi:[1,0,0]
	v_fma_mix_f32 v25, v186, v224, v25 op_sel:[1,0,0] op_sel_hi:[1,0,0]
	v_fma_mix_f32 v26, v187, v224, v26 op_sel:[0,0,0] op_sel_hi:[1,0,0]
	v_fma_mix_f32 v27, v187, v224, v27 op_sel:[1,0,0] op_sel_hi:[1,0,0]
	v_fma_mix_f32 v226, v24, v192, 0 op_sel:[0,0,0] op_sel_hi:[0,1,0]
	v_fma_mix_f32 v227, v26, v193, 0 op_sel:[0,0,0] op_sel_hi:[0,1,0]
	v_fma_mix_f32 v221, v24, v190, 0 op_sel:[0,0,0] op_sel_hi:[0,1,0]
	v_fma_mix_f32 v226, v25, v192, v226 op_sel:[0,1,0] op_sel_hi:[0,1,0]
	v_fma_mix_f32 v227, v27, v193, v227 op_sel:[0,1,0] op_sel_hi:[0,1,0]
	v_fma_mix_f32 v221, v25, v190, v221 op_sel:[0,1,0] op_sel_hi:[0,1,0]
	v_add_f32 v226, v226, v227
	v_fma_mix_f32 v221, v26, v191, v221 op_sel:[0,0,0] op_sel_hi:[0,1,0]
	v_fma_mix_f32 v221, v27, v191, v221 op_sel:[0,1,0] op_sel_hi:[0,1,0]
	v_fma_mix_f32 v24, v178, v24, v24 op_sel:[0,0,0] op_sel_hi:[1,0,0]
	v_fma_mix_f32 v25, v178, v25, v25 op_sel:[1,0,0] op_sel_hi:[1,0,0]
	v_add_f32_dpp v226, v226, v226 quad_perm:[1,0,3,2] row_mask:0xf bank_mask:0xf bound_ctrl:1
	v_add_f32_dpp v221, v221, v221 quad_perm:[1,0,3,2] row_mask:0xf bank_mask:0xf bound_ctrl:1
; __device__ __forceinline__ void scan_step(f32x4& S, float& ypo, const u32x4& h0, const u32x4& h1, unsigned e01, unsigned e23, unsigned r01, unsigned r23, float vi) {
;     float s0 = S[0], s1 = S[1], s2 = S[2], s3 = S[3], sa, yp, sb;
;     asm volatile(
;         MIX_SH("%[sa]", "%[s0]", "%[n01]", "0", "0") MIX_SH("%[sb]", "%[s2]", "%[n23]", "0", "0") MIX_SH("%[yp]", "%[s0]", "%[r01]", "0", "0")
;         MIX_SH("%[sa]", "%[s1]", "%[n01]", "%[sa]", "1") MIX_SH("%[sb]", "%[s3]", "%[n23]", "%[sb]", "1") MIX_SH("%[yp]", "%[s1]", "%[r01]", "%[yp]", "1")
;         "v_add_f32 %[sa], %[sa], %[sb]\n\t" MIX_SH("%[yp]", "%[s2]", "%[r23]", "%[yp]", "0") MIX_SH("%[yp]", "%[s3]", "%[r23]", "%[yp]", "1")
;         "v_fma_mix_f32 %[s0], %[e01], %[s0], %[s0] op_sel:[0,0,0] op_sel_hi:[1,0,0]\n\t" "v_fma_mix_f32 %[s1], %[e01], %[s1], %[s1] op_sel:[1,0,0] op_sel_hi:[1,0,0]\n\t"
;         DPP_ADD("%[sa]", "quad_perm:[1,0,3,2]") DPP_ADD("%[yp]", "quad_perm:[1,0,3,2]")
;         "v_fma_mix_f32 %[s2], %[e23], %[s2], %[s2] op_sel:[0,0,0] op_sel_hi:[1,0,0]\n\t" "v_fma_mix_f32 %[s3], %[e23], %[s3], %[s3] op_sel:[1,0,0] op_sel_hi:[1,0,0]\n\t"
;         DPP_ADD("%[sa]", "quad_perm:[2,3,0,1]") DPP_ADD("%[yp]", "quad_perm:[2,3,0,1]")
;         MIX_HS("%[s0]", "%[p01]", "%[vi]", "0") MIX_HS("%[s1]", "%[p01]", "%[vi]", "1")
;         DPP_ADD("%[sa]", "row_half_mirror")
;         MIX_HS("%[s2]", "%[p23]", "%[vi]", "0") MIX_HS("%[s3]", "%[p23]", "%[vi]", "1")
;         DPP_ADD("%[sa]", "row_mirror")
;         MIX_HS("%[s0]", "%[b01]", "%[sa]", "0") MIX_HS("%[s1]", "%[b01]", "%[sa]", "1") MIX_HS("%[s2]", "%[b23]", "%[sa]", "0") "v_fma_mix_f32 %[s3], %[b23], %[sa], %[s3] op_sel:[1,0,0] op_sel_hi:[1,0,0]"
;         : [s0] "+v"(s0), [s1] "+v"(s1), [s2] "+v"(s2), [s3] "+v"(s3), [sa] "=&v"(sa), [yp] "=&v"(yp), [sb] "=&v"(sb)
;         : [n01] "v"(h0.x), [n23] "v"(h0.y), [b01] "v"(h0.z), [b23] "v"(h0.w), [p01] "v"(h1.x), [p23] "v"(h1.y), [r01] "v"(r01), [r23] "v"(r23),
;           [e01] "v"(e01), [e23] "v"(e23), [vi] "v"(vi));
;     S[0] = s0; S[1] = s1; S[2] = s2; S[3] = s3; ypo = yp;
	v_fma_mix_f32 v26, v179, v26, v26 op_sel:[0,0,0] op_sel_hi:[1,0,0]
	v_fma_mix_f32 v27, v179, v27, v27 op_sel:[1,0,0] op_sel_hi:[1,0,0]
	v_add_f32_dpp v226, v226, v226 quad_perm:[2,3,0,1] row_mask:0xf bank_mask:0xf bound_ctrl:1
	v_add_f32_dpp v221, v221, v221 quad_perm:[2,3,0,1] row_mask:0xf bank_mask:0xf bound_ctrl:1
	v_fma_mix_f32 v24, v196, v173, v24 op_sel:[0,0,0] op_sel_hi:[1,0,0]
	v_fma_mix_f32 v25, v196, v173, v25 op_sel:[1,0,0] op_sel_hi:[1,0,0]
	v_add_f32_dpp v226, v226, v226 row_half_mirror row_mask:0xf bank_mask:0xf bound_ctrl:1
	v_fma_mix_f32 v26, v197, v173, v26 op_sel:[0,0,0] op_sel_hi:[1,0,0]
	v_fma_mix_f32 v27, v197, v173, v27 op_sel:[1,0,0] op_sel_hi:[1,0,0]
	v_add_f32_dpp v226, v226, v226 row_mirror row_mask:0xf bank_mask:0xf bound_ctrl:1
	v_fma_mix_f32 v24, v194, v226, v24 op_sel:[0,0,0] op_sel_hi:[1,0,0]
	v_fma_mix_f32 v25, v194, v226, v25 op_sel:[1,0,0] op_sel_hi:[1,0,0]
	v_fma_mix_f32 v26, v195, v226, v26 op_sel:[0,0,0] op_sel_hi:[1,0,0]
	v_fma_mix_f32 v27, v195, v226, v27 op_sel:[1,0,0] op_sel_hi:[1,0,0]
	v_fma_mix_f32 v224, v24, v200, 0 op_sel:[0,0,0] op_sel_hi:[0,1,0]
	v_fma_mix_f32 v225, v26, v201, 0 op_sel:[0,0,0] op_sel_hi:[0,1,0]
	v_fma_mix_f32 v222, v24, v198, 0 op_sel:[0,0,0] op_sel_hi:[0,1,0]
	v_fma_mix_f32 v224, v25, v200, v224 op_sel:[0,1,0] op_sel_hi:[0,1,0]
	v_fma_mix_f32 v225, v27, v201, v225 op_sel:[0,1,0] op_sel_hi:[0,1,0]
	v_fma_mix_f32 v222, v25, v198, v222 op_sel:[0,1,0] op_sel_hi:[0,1,0]
	v_add_f32 v224, v224, v225
	v_fma_mix_f32 v222, v26, v199, v222 op_sel:[0,0,0] op_sel_hi:[0,1,0]
	v_fma_mix_f32 v222, v27, v199, v222 op_sel:[0,1,0] op_sel_hi:[0,1,0]
	v_fma_mix_f32 v24, v180, v24, v24 op_sel:[0,0,0] op_sel_hi:[1,0,0]
	v_fma_mix_f32 v25, v180, v25, v25 op_sel:[1,0,0] op_sel_hi:[1,0,0]
	v_add_f32_dpp v224, v224, v224 quad_perm:[1,0,3,2] row_mask:0xf bank_mask:0xf bound_ctrl:1
	v_add_f32_dpp v222, v222, v222 quad_perm:[1,0,3,2] row_mask:0xf bank_mask:0xf bound_ctrl:1
	v_fma_mix_f32 v26, v181, v26, v26 op_sel:[0,0,0] op_sel_hi:[1,0,0]
	v_fma_mix_f32 v27, v181, v27, v27 op_sel:[1,0,0] op_sel_hi:[1,0,0]
	v_add_f32_dpp v224, v224, v224 quad_perm:[2,3,0,1] row_mask:0xf bank_mask:0xf bound_ctrl:1
	v_add_f32_dpp v222, v222, v222 quad_perm:[2,3,0,1] row_mask:0xf bank_mask:0xf bound_ctrl:1
	v_fma_mix_f32 v24, v204, v174, v24 op_sel:[0,0,0] op_sel_hi:[1,0,0]
	v_fma_mix_f32 v25, v204, v174, v25 op_sel:[1,0,0] op_sel_hi:[1,0,0]
	v_add_f32_dpp v224, v224, v224 row_half_mirror row_mask:0xf bank_mask:0xf bound_ctrl:1
	v_fma_mix_f32 v26, v205, v174, v26 op_sel:[0,0,0] op_sel_hi:[1,0,0]
	v_fma_mix_f32 v27, v205, v174, v27 op_sel:[1,0,0] op_sel_hi:[1,0,0]
	v_add_f32_dpp v224, v224, v224 row_mirror row_mask:0xf bank_mask:0xf bound_ctrl:1
	v_fma_mix_f32 v24, v202, v224, v24 op_sel:[0,0,0] op_sel_hi:[1,0,0]
	v_fma_mix_f32 v25, v202, v224, v25 op_sel:[1,0,0] op_sel_hi:[1,0,0]
	v_fma_mix_f32 v26, v203, v224, v26 op_sel:[0,0,0] op_sel_hi:[1,0,0]
	v_fma_mix_f32 v27, v203, v224, v27 op_sel:[1,0,0] op_sel_hi:[1,0,0]
	v_fma_mix_f32 v226, v24, v208, 0 op_sel:[0,0,0] op_sel_hi:[0,1,0]
	v_fma_mix_f32 v227, v26, v209, 0 op_sel:[0,0,0] op_sel_hi:[0,1,0]
	v_fma_mix_f32 v223, v24, v206, 0 op_sel:[0,0,0] op_sel_hi:[0,1,0]
	v_fma_mix_f32 v226, v25, v208, v226 op_sel:[0,1,0] op_sel_hi:[0,1,0]
	v_fma_mix_f32 v227, v27, v209, v227 op_sel:[0,1,0] op_sel_hi:[0,1,0]
	v_fma_mix_f32 v223, v25, v206, v223 op_sel:[0,1,0] op_sel_hi:[0,1,0]
	v_add_f32 v226, v226, v227
	v_fma_mix_f32 v223, v26, v207, v223 op_sel:[0,0,0] op_sel_hi:[0,1,0]
	v_fma_mix_f32 v223, v27, v207, v223 op_sel:[0,1,0] op_sel_hi:[0,1,0]
	v_fma_mix_f32 v24, v182, v24, v24 op_sel:[0,0,0] op_sel_hi:[1,0,0]
	v_fma_mix_f32 v25, v182, v25, v25 op_sel:[1,0,0] op_sel_hi:[1,0,0]
	v_add_f32_dpp v226, v226, v226 quad_perm:[1,0,3,2] row_mask:0xf bank_mask:0xf bound_ctrl:1
	v_add_f32_dpp v223, v223, v223 quad_perm:[1,0,3,2] row_mask:0xf bank_mask:0xf bound_ctrl:1
	v_fma_mix_f32 v26, v183, v26, v26 op_sel:[0,0,0] op_sel_hi:[1,0,0]
	v_fma_mix_f32 v27, v183, v27, v27 op_sel:[1,0,0] op_sel_hi:[1,0,0]
	v_add_f32_dpp v226, v226, v226 quad_perm:[2,3,0,1] row_mask:0xf bank_mask:0xf bound_ctrl:1
	v_add_f32_dpp v223, v223, v223 quad_perm:[2,3,0,1] row_mask:0xf bank_mask:0xf bound_ctrl:1
	v_fma_mix_f32 v24, v212, v175, v24 op_sel:[0,0,0] op_sel_hi:[1,0,0]
	v_fma_mix_f32 v25, v212, v175, v25 op_sel:[1,0,0] op_sel_hi:[1,0,0]
	v_add_f32_dpp v226, v226, v226 row_half_mirror row_mask:0xf bank_mask:0xf bound_ctrl:1
	v_fma_mix_f32 v26, v213, v175, v26 op_sel:[0,0,0] op_sel_hi:[1,0,0]
	v_fma_mix_f32 v27, v213, v175, v27 op_sel:[1,0,0] op_sel_hi:[1,0,0]
	v_add_f32_dpp v226, v226, v226 row_mirror row_mask:0xf bank_mask:0xf bound_ctrl:1
	v_fma_mix_f32 v24, v210, v226, v24 op_sel:[0,0,0] op_sel_hi:[1,0,0]
	v_fma_mix_f32 v25, v210, v226, v25 op_sel:[1,0,0] op_sel_hi:[1,0,0]
	v_fma_mix_f32 v26, v211, v226, v26 op_sel:[0,0,0] op_sel_hi:[1,0,0]
	v_fma_mix_f32 v27, v211, v226, v27 op_sel:[1,0,0] op_sel_hi:[1,0,0]
	s_and_saveexec_b64 s[44:45], s[10:11]
	ds_write_b128 v99, v[220:223] offset:48
	s_or_b64 exec, exec, s[44:45]
	v_mov_b32_e32 v228, v214
	v_mov_b32_e32 v229, v215
	ds_read_b128 v[172:175], v61 offset:24656
	ds_read_b128 v[176:179], v60 offset:17664
	ds_read_b128 v[180:183], v60 offset:19712
	ds_read_b128 v[184:187], v60 offset:5120
	ds_read_b128 v[188:191], v60 offset:13312
	ds_read_b128 v[192:195], v60 offset:5376
	ds_read_b128 v[196:199], v60 offset:13568
	ds_read_b128 v[200:203], v60 offset:5632
	ds_read_b128 v[204:207], v60 offset:13824
	ds_read_b128 v[208:211], v60 offset:5888
	ds_read_b128 v[212:215], v60 offset:14080
	s_waitcnt lgkmcnt(11)
; __device__ __forceinline__ void scan_step(f32x4& S, float& ypo, const u32x4& h0, const u32x4& h1, unsigned e01, unsigned e23, unsigned r01, unsigned r23, float vi) {
;     float s0 = S[0], s1 = S[1], s2 = S[2], s3 = S[3], sa, yp, sb;
;     asm volatile(
;         MIX_SH("%[sa]", "%[s0]", "%[n01]", "0", "0") MIX_SH("%[sb]", "%[s2]", "%[n23]", "0", "0") MIX_SH("%[yp]", "%[s0]", "%[r01]", "0", "0")
;         MIX_SH("%[sa]", "%[s1]", "%[n01]", "%[sa]", "1") MIX_SH("%[sb]", "%[s3]", "%[n23]", "%[sb]", "1") MIX_SH("%[yp]", "%[s1]", "%[r01]", "%[yp]", "1")
;         "v_add_f32 %[sa], %[sa], %[sb]\n\t" MIX_SH("%[yp]", "%[s2]", "%[r23]", "%[yp]", "0") MIX_SH("%[yp]", "%[s3]", "%[r23]", "%[yp]", "1")
;         "v_fma_mix_f32 %[s0], %[e01], %[s0], %[s0] op_sel:[0,0,0] op_sel_hi:[1,0,0]\n\t" "v_fma_mix_f32 %[s1], %[e01], %[s1], %[s1] op_sel:[1,0,0] op_sel_hi:[1,0,0]\n\t"
;         DPP_ADD("%[sa]", "quad_perm:[1,0,3,2]") DPP_ADD("%[yp]", "quad_perm:[1,0,3,2]")
;         "v_fma_mix_f32 %[s2], %[e23], %[s2], %[s2] op_sel:[0,0,0] op_sel_hi:[1,0,0]\n\t" "v_fma_mix_f32 %[s3], %[e23], %[s3], %[s3] op_sel:[1,0,0] op_sel_hi:[1,0,0]\n\t"
;         DPP_ADD("%[sa]", "quad_perm:[2,3,0,1]") DPP_ADD("%[yp]", "quad_perm:[2,3,0,1]")
;         MIX_HS("%[s0]", "%[p01]", "%[vi]", "0") MIX_HS("%[s1]", "%[p01]", "%[vi]", "1")
;         DPP_ADD("%[sa]", "row_half_mirror")
;         MIX_HS("%[s2]", "%[p23]", "%[vi]", "0") MIX_HS("%[s3]", "%[p23]", "%[vi]", "1")
;         DPP_ADD("%[sa]", "row_mirror")
;         MIX_HS("%[s0]", "%[b01]", "%[sa]", "0") MIX_HS("%[s1]", "%[b01]", "%[sa]", "1") MIX_HS("%[s2]", "%[b23]", "%[sa]", "0") "v_fma_mix_f32 %[s3], %[b23], %[sa], %[s3] op_sel:[1,0,0] op_sel_hi:[1,0,0]"
;         : [s0] "+v"(s0), [s1] "+v"(s1), [s2] "+v"(s2), [s3] "+v"(s3), [sa] "=&v"(sa), [yp] "=&v"(yp), [sb] "=&v"(sb)
;         : [n01] "v"(h0.x), [n23] "v"(h0.y), [b01] "v"(h0.z), [b23] "v"(h0.w), [p01] "v"(h1.x), [p23] "v"(h1.y), [r01] "v"(r01), [r23] "v"(r23),
;           [e01] "v"(e01), [e23] "v"(e23), [vi] "v"(vi));
;     S[0] = s0; S[1] = s1; S[2] = s2; S[3] = s3; ypo = yp;
	v_fma_mix_f32 v224, v24, v112, 0 op_sel:[0,0,0] op_sel_hi:[0,1,0]
	v_fma_mix_f32 v225, v26, v113, 0 op_sel:[0,0,0] op_sel_hi:[0,1,0]
	v_fma_mix_f32 v216, v24, v228, 0 op_sel:[0,0,0] op_sel_hi:[0,1,0]
	v_fma_mix_f32 v224, v25, v112, v224 op_sel:[0,1,0] op_sel_hi:[0,1,0]
	v_fma_mix_f32 v225, v27, v113, v225 op_sel:[0,1,0] op_sel_hi:[0,1,0]
	v_fma_mix_f32 v216, v25, v228, v216 op_sel:[0,1,0] op_sel_hi:[0,1,0]
	v_add_f32 v224, v224, v225
	v_fma_mix_f32 v216, v26, v229, v216 op_sel:[0,0,0] op_sel_hi:[0,1,0]
	v_fma_mix_f32 v216, v27, v229, v216 op_sel:[0,1,0] op_sel_hi:[0,1,0]
	v_fma_mix_f32 v24, v104, v24, v24 op_sel:[0,0,0] op_sel_hi:[1,0,0]
	v_fma_mix_f32 v25, v104, v25, v25 op_sel:[1,0,0] op_sel_hi:[1,0,0]
	v_add_f32_dpp v224, v224, v224 quad_perm:[1,0,3,2] row_mask:0xf bank_mask:0xf bound_ctrl:1
	v_add_f32_dpp v216, v216, v216 quad_perm:[1,0,3,2] row_mask:0xf bank_mask:0xf bound_ctrl:1
	v_fma_mix_f32 v26, v105, v26, v26 op_sel:[0,0,0] op_sel_hi:[1,0,0]
	v_fma_mix_f32 v27, v105, v27, v27 op_sel:[1,0,0] op_sel_hi:[1,0,0]
	v_add_f32_dpp v224, v224, v224 quad_perm:[2,3,0,1] row_mask:0xf bank_mask:0xf bound_ctrl:1
	v_add_f32_dpp v216, v216, v216 quad_perm:[2,3,0,1] row_mask:0xf bank_mask:0xf bound_ctrl:1
	v_fma_mix_f32 v24, v116, v100, v24 op_sel:[0,0,0] op_sel_hi:[1,0,0]
	v_fma_mix_f32 v25, v116, v100, v25 op_sel:[1,0,0] op_sel_hi:[1,0,0]
	v_add_f32_dpp v224, v224, v224 row_half_mirror row_mask:0xf bank_mask:0xf bound_ctrl:1
	v_fma_mix_f32 v26, v117, v100, v26 op_sel:[0,0,0] op_sel_hi:[1,0,0]
	v_fma_mix_f32 v27, v117, v100, v27 op_sel:[1,0,0] op_sel_hi:[1,0,0]
	v_add_f32_dpp v224, v224, v224 row_mirror row_mask:0xf bank_mask:0xf bound_ctrl:1
	v_fma_mix_f32 v24, v114, v224, v24 op_sel:[0,0,0] op_sel_hi:[1,0,0]
	v_fma_mix_f32 v25, v114, v224, v25 op_sel:[1,0,0] op_sel_hi:[1,0,0]
	v_fma_mix_f32 v26, v115, v224, v26 op_sel:[0,0,0] op_sel_hi:[1,0,0]
	v_fma_mix_f32 v27, v115, v224, v27 op_sel:[1,0,0] op_sel_hi:[1,0,0]
	v_fma_mix_f32 v226, v24, v120, 0 op_sel:[0,0,0] op_sel_hi:[0,1,0]
	v_fma_mix_f32 v227, v26, v121, 0 op_sel:[0,0,0] op_sel_hi:[0,1,0]
	v_fma_mix_f32 v217, v24, v118, 0 op_sel:[0,0,0] op_sel_hi:[0,1,0]
	v_fma_mix_f32 v226, v25, v120, v226 op_sel:[0,1,0] op_sel_hi:[0,1,0]
	v_fma_mix_f32 v227, v27, v121, v227 op_sel:[0,1,0] op_sel_hi:[0,1,0]
	v_fma_mix_f32 v217, v25, v118, v217 op_sel:[0,1,0] op_sel_hi:[0,1,0]
	v_add_f32 v226, v226, v227
	v_fma_mix_f32 v217, v26, v119, v217 op_sel:[0,0,0] op_sel_hi:[0,1,0]
	v_fma_mix_f32 v217, v27, v119, v217 op_sel:[0,1,0] op_sel_hi:[0,1,0]
	v_fma_mix_f32 v24, v106, v24, v24 op_sel:[0,0,0] op_sel_hi:[1,0,0]
	v_fma_mix_f32 v25, v106, v25, v25 op_sel:[1,0,0] op_sel_hi:[1,0,0]
	v_add_f32_dpp v226, v226, v226 quad_perm:[1,0,3,2] row_mask:0xf bank_mask:0xf bound_ctrl:1
	v_add_f32_dpp v217, v217, v217 quad_perm:[1,0,3,2] row_mask:0xf bank_mask:0xf bound_ctrl:1
	v_fma_mix_f32 v26, v107, v26, v26 op_sel:[0,0,0] op_sel_hi:[1,0,0]
	v_fma_mix_f32 v27, v107, v27, v27 op_sel:[1,0,0] op_sel_hi:[1,0,0]
	v_add_f32_dpp v226, v226, v226 quad_perm:[2,3,0,1] row_mask:0xf bank_mask:0xf bound_ctrl:1
	v_add_f32_dpp v217, v217, v217 quad_perm:[2,3,0,1] row_mask:0xf bank_mask:0xf bound_ctrl:1
	v_fma_mix_f32 v24, v124, v101, v24 op_sel:[0,0,0] op_sel_hi:[1,0,0]
	v_fma_mix_f32 v25, v124, v101, v25 op_sel:[1,0,0] op_sel_hi:[1,0,0]
	v_add_f32_dpp v226, v226, v226 row_half_mirror row_mask:0xf bank_mask:0xf bound_ctrl:1
	v_fma_mix_f32 v26, v125, v101, v26 op_sel:[0,0,0] op_sel_hi:[1,0,0]
	v_fma_mix_f32 v27, v125, v101, v27 op_sel:[1,0,0] op_sel_hi:[1,0,0]
	v_add_f32_dpp v226, v226, v226 row_mirror row_mask:0xf bank_mask:0xf bound_ctrl:1
	v_fma_mix_f32 v24, v122, v226, v24 op_sel:[0,0,0] op_sel_hi:[1,0,0]
	v_fma_mix_f32 v25, v122, v226, v25 op_sel:[1,0,0] op_sel_hi:[1,0,0]
	v_fma_mix_f32 v26, v123, v226, v26 op_sel:[0,0,0] op_sel_hi:[1,0,0]
	v_fma_mix_f32 v27, v123, v226, v27 op_sel:[1,0,0] op_sel_hi:[1,0,0]
	v_fma_mix_f32 v224, v24, v128, 0 op_sel:[0,0,0] op_sel_hi:[0,1,0]
	v_fma_mix_f32 v225, v26, v129, 0 op_sel:[0,0,0] op_sel_hi:[0,1,0]
	v_fma_mix_f32 v218, v24, v126, 0 op_sel:[0,0,0] op_sel_hi:[0,1,0]
	v_fma_mix_f32 v224, v25, v128, v224 op_sel:[0,1,0] op_sel_hi:[0,1,0]
	v_fma_mix_f32 v225, v27, v129, v225 op_sel:[0,1,0] op_sel_hi:[0,1,0]
	v_fma_mix_f32 v218, v25, v126, v218 op_sel:[0,1,0] op_sel_hi:[0,1,0]
	v_add_f32 v224, v224, v225
	v_fma_mix_f32 v218, v26, v127, v218 op_sel:[0,0,0] op_sel_hi:[0,1,0]
	v_fma_mix_f32 v218, v27, v127, v218 op_sel:[0,1,0] op_sel_hi:[0,1,0]
	v_fma_mix_f32 v24, v108, v24, v24 op_sel:[0,0,0] op_sel_hi:[1,0,0]
	v_fma_mix_f32 v25, v108, v25, v25 op_sel:[1,0,0] op_sel_hi:[1,0,0]
	v_add_f32_dpp v224, v224, v224 quad_perm:[1,0,3,2] row_mask:0xf bank_mask:0xf bound_ctrl:1
	v_add_f32_dpp v218, v218, v218 quad_perm:[1,0,3,2] row_mask:0xf bank_mask:0xf bound_ctrl:1
	v_fma_mix_f32 v26, v109, v26, v26 op_sel:[0,0,0] op_sel_hi:[1,0,0]
	v_fma_mix_f32 v27, v109, v27, v27 op_sel:[1,0,0] op_sel_hi:[1,0,0]
	v_add_f32_dpp v224, v224, v224 quad_perm:[2,3,0,1] row_mask:0xf bank_mask:0xf bound_ctrl:1
	v_add_f32_dpp v218, v218, v218 quad_perm:[2,3,0,1] row_mask:0xf bank_mask:0xf bound_ctrl:1
	v_fma_mix_f32 v24, v132, v102, v24 op_sel:[0,0,0] op_sel_hi:[1,0,0]
	v_fma_mix_f32 v25, v132, v102, v25 op_sel:[1,0,0] op_sel_hi:[1,0,0]
	v_add_f32_dpp v224, v224, v224 row_half_mirror row_mask:0xf bank_mask:0xf bound_ctrl:1
	v_fma_mix_f32 v26, v133, v102, v26 op_sel:[0,0,0] op_sel_hi:[1,0,0]
	v_fma_mix_f32 v27, v133, v102, v27 op_sel:[1,0,0] op_sel_hi:[1,0,0]
	v_add_f32_dpp v224, v224, v224 row_mirror row_mask:0xf bank_mask:0xf bound_ctrl:1
	v_fma_mix_f32 v24, v130, v224, v24 op_sel:[0,0,0] op_sel_hi:[1,0,0]
; __device__ __forceinline__ void scan_step(f32x4& S, float& ypo, const u32x4& h0, const u32x4& h1, unsigned e01, unsigned e23, unsigned r01, unsigned r23, float vi) {
;     float s0 = S[0], s1 = S[1], s2 = S[2], s3 = S[3], sa, yp, sb;
;     asm volatile(
;         MIX_SH("%[sa]", "%[s0]", "%[n01]", "0", "0") MIX_SH("%[sb]", "%[s2]", "%[n23]", "0", "0") MIX_SH("%[yp]", "%[s0]", "%[r01]", "0", "0")
;         MIX_SH("%[sa]", "%[s1]", "%[n01]", "%[sa]", "1") MIX_SH("%[sb]", "%[s3]", "%[n23]", "%[sb]", "1") MIX_SH("%[yp]", "%[s1]", "%[r01]", "%[yp]", "1")
;         "v_add_f32 %[sa], %[sa], %[sb]\n\t" MIX_SH("%[yp]", "%[s2]", "%[r23]", "%[yp]", "0") MIX_SH("%[yp]", "%[s3]", "%[r23]", "%[yp]", "1")
;         "v_fma_mix_f32 %[s0], %[e01], %[s0], %[s0] op_sel:[0,0,0] op_sel_hi:[1,0,0]\n\t" "v_fma_mix_f32 %[s1], %[e01], %[s1], %[s1] op_sel:[1,0,0] op_sel_hi:[1,0,0]\n\t"
;         DPP_ADD("%[sa]", "quad_perm:[1,0,3,2]") DPP_ADD("%[yp]", "quad_perm:[1,0,3,2]")
;         "v_fma_mix_f32 %[s2], %[e23], %[s2], %[s2] op_sel:[0,0,0] op_sel_hi:[1,0,0]\n\t" "v_fma_mix_f32 %[s3], %[e23], %[s3], %[s3] op_sel:[1,0,0] op_sel_hi:[1,0,0]\n\t"
;         DPP_ADD("%[sa]", "quad_perm:[2,3,0,1]") DPP_ADD("%[yp]", "quad_perm:[2,3,0,1]")
;         MIX_HS("%[s0]", "%[p01]", "%[vi]", "0") MIX_HS("%[s1]", "%[p01]", "%[vi]", "1")
;         DPP_ADD("%[sa]", "row_half_mirror")
;         MIX_HS("%[s2]", "%[p23]", "%[vi]", "0") MIX_HS("%[s3]", "%[p23]", "%[vi]", "1")
;         DPP_ADD("%[sa]", "row_mirror")
;         MIX_HS("%[s0]", "%[b01]", "%[sa]", "0") MIX_HS("%[s1]", "%[b01]", "%[sa]", "1") MIX_HS("%[s2]", "%[b23]", "%[sa]", "0") "v_fma_mix_f32 %[s3], %[b23], %[sa], %[s3] op_sel:[1,0,0] op_sel_hi:[1,0,0]"
;         : [s0] "+v"(s0), [s1] "+v"(s1), [s2] "+v"(s2), [s3] "+v"(s3), [sa] "=&v"(sa), [yp] "=&v"(yp), [sb] "=&v"(sb)
;         : [n01] "v"(h0.x), [n23] "v"(h0.y), [b01] "v"(h0.z), [b23] "v"(h0.w), [p01] "v"(h1.x), [p23] "v"(h1.y), [r01] "v"(r01), [r23] "v"(r23),
;           [e01] "v"(e01), [e23] "v"(e23), [vi] "v"(vi));
;     S[0] = s0; S[1] = s1; S[2] = s2; S[3] = s3; ypo = yp;
	v_fma_mix_f32 v25, v130, v224, v25 op_sel:[1,0,0] op_sel_hi:[1,0,0]
	v_fma_mix_f32 v26, v131, v224, v26 op_sel:[0,0,0] op_sel_hi:[1,0,0]
	v_fma_mix_f32 v27, v131, v224, v27 op_sel:[1,0,0] op_sel_hi:[1,0,0]
	v_fma_mix_f32 v226, v24, v140, 0 op_sel:[0,0,0] op_sel_hi:[0,1,0]
	v_fma_mix_f32 v227, v26, v141, 0 op_sel:[0,0,0] op_sel_hi:[0,1,0]
	v_fma_mix_f32 v219, v24, v134, 0 op_sel:[0,0,0] op_sel_hi:[0,1,0]
	v_fma_mix_f32 v226, v25, v140, v226 op_sel:[0,1,0] op_sel_hi:[0,1,0]
	v_fma_mix_f32 v227, v27, v141, v227 op_sel:[0,1,0] op_sel_hi:[0,1,0]
	v_fma_mix_f32 v219, v25, v134, v219 op_sel:[0,1,0] op_sel_hi:[0,1,0]
	v_add_f32 v226, v226, v227
	v_fma_mix_f32 v219, v26, v135, v219 op_sel:[0,0,0] op_sel_hi:[0,1,0]
	v_fma_mix_f32 v219, v27, v135, v219 op_sel:[0,1,0] op_sel_hi:[0,1,0]
	v_fma_mix_f32 v24, v110, v24, v24 op_sel:[0,0,0] op_sel_hi:[1,0,0]
	v_fma_mix_f32 v25, v110, v25, v25 op_sel:[1,0,0] op_sel_hi:[1,0,0]
	v_add_f32_dpp v226, v226, v226 quad_perm:[1,0,3,2] row_mask:0xf bank_mask:0xf bound_ctrl:1
	v_add_f32_dpp v219, v219, v219 quad_perm:[1,0,3,2] row_mask:0xf bank_mask:0xf bound_ctrl:1
	v_fma_mix_f32 v26, v111, v26, v26 op_sel:[0,0,0] op_sel_hi:[1,0,0]
	v_fma_mix_f32 v27, v111, v27, v27 op_sel:[1,0,0] op_sel_hi:[1,0,0]
	v_add_f32_dpp v226, v226, v226 quad_perm:[2,3,0,1] row_mask:0xf bank_mask:0xf bound_ctrl:1
	v_add_f32_dpp v219, v219, v219 quad_perm:[2,3,0,1] row_mask:0xf bank_mask:0xf bound_ctrl:1
	v_fma_mix_f32 v24, v52, v103, v24 op_sel:[0,0,0] op_sel_hi:[1,0,0]
	v_fma_mix_f32 v25, v52, v103, v25 op_sel:[1,0,0] op_sel_hi:[1,0,0]
	v_add_f32_dpp v226, v226, v226 row_half_mirror row_mask:0xf bank_mask:0xf bound_ctrl:1
	v_fma_mix_f32 v26, v53, v103, v26 op_sel:[0,0,0] op_sel_hi:[1,0,0]
	v_fma_mix_f32 v27, v53, v103, v27 op_sel:[1,0,0] op_sel_hi:[1,0,0]
	v_add_f32_dpp v226, v226, v226 row_mirror row_mask:0xf bank_mask:0xf bound_ctrl:1
	v_fma_mix_f32 v24, v142, v226, v24 op_sel:[0,0,0] op_sel_hi:[1,0,0]
	v_fma_mix_f32 v25, v142, v226, v25 op_sel:[1,0,0] op_sel_hi:[1,0,0]
	v_fma_mix_f32 v26, v143, v226, v26 op_sel:[0,0,0] op_sel_hi:[1,0,0]
	v_fma_mix_f32 v27, v143, v226, v27 op_sel:[1,0,0] op_sel_hi:[1,0,0]
	s_and_saveexec_b64 s[44:45], s[10:11]
	ds_write_b128 v99, v[216:219] offset:64
	s_or_b64 exec, exec, s[44:45]
	v_mov_b32_e32 v228, v54
	v_mov_b32_e32 v229, v55
	ds_read_b128 v[100:103], v61 offset:24672
	ds_read_b128 v[104:107], v60 offset:17920
	ds_read_b128 v[108:111], v60 offset:19968
	ds_read_b128 v[112:115], v60 offset:6144
	ds_read_b128 v[116:119], v60 offset:14336
	ds_read_b128 v[120:123], v60 offset:6400
	ds_read_b128 v[124:127], v60 offset:14592
	ds_read_b128 v[128:131], v60 offset:6656
	ds_read_b128 v[132:135], v60 offset:14848
	ds_read_b128 v[140:143], v60 offset:6912
	ds_read_b128 v[52:55], v60 offset:15104
	s_waitcnt lgkmcnt(11)
	v_fma_mix_f32 v224, v24, v184, 0 op_sel:[0,0,0] op_sel_hi:[0,1,0]
	v_fma_mix_f32 v225, v26, v185, 0 op_sel:[0,0,0] op_sel_hi:[0,1,0]
	v_fma_mix_f32 v220, v24, v228, 0 op_sel:[0,0,0] op_sel_hi:[0,1,0]
	v_fma_mix_f32 v224, v25, v184, v224 op_sel:[0,1,0] op_sel_hi:[0,1,0]
	v_fma_mix_f32 v225, v27, v185, v225 op_sel:[0,1,0] op_sel_hi:[0,1,0]
	v_fma_mix_f32 v220, v25, v228, v220 op_sel:[0,1,0] op_sel_hi:[0,1,0]
	v_add_f32 v224, v224, v225
	v_fma_mix_f32 v220, v26, v229, v220 op_sel:[0,0,0] op_sel_hi:[0,1,0]
	v_fma_mix_f32 v220, v27, v229, v220 op_sel:[0,1,0] op_sel_hi:[0,1,0]
	v_fma_mix_f32 v24, v176, v24, v24 op_sel:[0,0,0] op_sel_hi:[1,0,0]
	v_fma_mix_f32 v25, v176, v25, v25 op_sel:[1,0,0] op_sel_hi:[1,0,0]
	v_add_f32_dpp v224, v224, v224 quad_perm:[1,0,3,2] row_mask:0xf bank_mask:0xf bound_ctrl:1
	v_add_f32_dpp v220, v220, v220 quad_perm:[1,0,3,2] row_mask:0xf bank_mask:0xf bound_ctrl:1
	v_fma_mix_f32 v26, v177, v26, v26 op_sel:[0,0,0] op_sel_hi:[1,0,0]
	v_fma_mix_f32 v27, v177, v27, v27 op_sel:[1,0,0] op_sel_hi:[1,0,0]
	v_add_f32_dpp v224, v224, v224 quad_perm:[2,3,0,1] row_mask:0xf bank_mask:0xf bound_ctrl:1
	v_add_f32_dpp v220, v220, v220 quad_perm:[2,3,0,1] row_mask:0xf bank_mask:0xf bound_ctrl:1
	v_fma_mix_f32 v24, v188, v172, v24 op_sel:[0,0,0] op_sel_hi:[1,0,0]
	v_fma_mix_f32 v25, v188, v172, v25 op_sel:[1,0,0] op_sel_hi:[1,0,0]
	v_add_f32_dpp v224, v224, v224 row_half_mirror row_mask:0xf bank_mask:0xf bound_ctrl:1
	v_fma_mix_f32 v26, v189, v172, v26 op_sel:[0,0,0] op_sel_hi:[1,0,0]
	v_fma_mix_f32 v27, v189, v172, v27 op_sel:[1,0,0] op_sel_hi:[1,0,0]
	v_add_f32_dpp v224, v224, v224 row_mirror row_mask:0xf bank_mask:0xf bound_ctrl:1
	v_fma_mix_f32 v24, v186, v224, v24 op_sel:[0,0,0] op_sel_hi:[1,0,0]
	v_fma_mix_f32 v25, v186, v224, v25 op_sel:[1,0,0] op_sel_hi:[1,0,0]
	v_fma_mix_f32 v26, v187, v224, v26 op_sel:[0,0,0] op_sel_hi:[1,0,0]
	v_fma_mix_f32 v27, v187, v224, v27 op_sel:[1,0,0] op_sel_hi:[1,0,0]
	v_fma_mix_f32 v226, v24, v192, 0 op_sel:[0,0,0] op_sel_hi:[0,1,0]
	v_fma_mix_f32 v227, v26, v193, 0 op_sel:[0,0,0] op_sel_hi:[0,1,0]
	v_fma_mix_f32 v221, v24, v190, 0 op_sel:[0,0,0] op_sel_hi:[0,1,0]
	v_fma_mix_f32 v226, v25, v192, v226 op_sel:[0,1,0] op_sel_hi:[0,1,0]
	v_fma_mix_f32 v227, v27, v193, v227 op_sel:[0,1,0] op_sel_hi:[0,1,0]
	v_fma_mix_f32 v221, v25, v190, v221 op_sel:[0,1,0] op_sel_hi:[0,1,0]
	v_add_f32 v226, v226, v227
	v_fma_mix_f32 v221, v26, v191, v221 op_sel:[0,0,0] op_sel_hi:[0,1,0]
	v_fma_mix_f32 v221, v27, v191, v221 op_sel:[0,1,0] op_sel_hi:[0,1,0]
	v_fma_mix_f32 v24, v178, v24, v24 op_sel:[0,0,0] op_sel_hi:[1,0,0]
	v_fma_mix_f32 v25, v178, v25, v25 op_sel:[1,0,0] op_sel_hi:[1,0,0]
	v_add_f32_dpp v226, v226, v226 quad_perm:[1,0,3,2] row_mask:0xf bank_mask:0xf bound_ctrl:1
	v_add_f32_dpp v221, v221, v221 quad_perm:[1,0,3,2] row_mask:0xf bank_mask:0xf bound_ctrl:1
; __device__ __forceinline__ void scan_step(f32x4& S, float& ypo, const u32x4& h0, const u32x4& h1, unsigned e01, unsigned e23, unsigned r01, unsigned r23, float vi) {
;     float s0 = S[0], s1 = S[1], s2 = S[2], s3 = S[3], sa, yp, sb;
;     asm volatile(
;         MIX_SH("%[sa]", "%[s0]", "%[n01]", "0", "0") MIX_SH("%[sb]", "%[s2]", "%[n23]", "0", "0") MIX_SH("%[yp]", "%[s0]", "%[r01]", "0", "0")
;         MIX_SH("%[sa]", "%[s1]", "%[n01]", "%[sa]", "1") MIX_SH("%[sb]", "%[s3]", "%[n23]", "%[sb]", "1") MIX_SH("%[yp]", "%[s1]", "%[r01]", "%[yp]", "1")
;         "v_add_f32 %[sa], %[sa], %[sb]\n\t" MIX_SH("%[yp]", "%[s2]", "%[r23]", "%[yp]", "0") MIX_SH("%[yp]", "%[s3]", "%[r23]", "%[yp]", "1")
;         "v_fma_mix_f32 %[s0], %[e01], %[s0], %[s0] op_sel:[0,0,0] op_sel_hi:[1,0,0]\n\t" "v_fma_mix_f32 %[s1], %[e01], %[s1], %[s1] op_sel:[1,0,0] op_sel_hi:[1,0,0]\n\t"
;         DPP_ADD("%[sa]", "quad_perm:[1,0,3,2]") DPP_ADD("%[yp]", "quad_perm:[1,0,3,2]")
;         "v_fma_mix_f32 %[s2], %[e23], %[s2], %[s2] op_sel:[0,0,0] op_sel_hi:[1,0,0]\n\t" "v_fma_mix_f32 %[s3], %[e23], %[s3], %[s3] op_sel:[1,0,0] op_sel_hi:[1,0,0]\n\t"
;         DPP_ADD("%[sa]", "quad_perm:[2,3,0,1]") DPP_ADD("%[yp]", "quad_perm:[2,3,0,1]")
;         MIX_HS("%[s0]", "%[p01]", "%[vi]", "0") MIX_HS("%[s1]", "%[p01]", "%[vi]", "1")
;         DPP_ADD("%[sa]", "row_half_mirror")
;         MIX_HS("%[s2]", "%[p23]", "%[vi]", "0") MIX_HS("%[s3]", "%[p23]", "%[vi]", "1")
;         DPP_ADD("%[sa]", "row_mirror")
;         MIX_HS("%[s0]", "%[b01]", "%[sa]", "0") MIX_HS("%[s1]", "%[b01]", "%[sa]", "1") MIX_HS("%[s2]", "%[b23]", "%[sa]", "0") "v_fma_mix_f32 %[s3], %[b23], %[sa], %[s3] op_sel:[1,0,0] op_sel_hi:[1,0,0]"
;         : [s0] "+v"(s0), [s1] "+v"(s1), [s2] "+v"(s2), [s3] "+v"(s3), [sa] "=&v"(sa), [yp] "=&v"(yp), [sb] "=&v"(sb)
;         : [n01] "v"(h0.x), [n23] "v"(h0.y), [b01] "v"(h0.z), [b23] "v"(h0.w), [p01] "v"(h1.x), [p23] "v"(h1.y), [r01] "v"(r01), [r23] "v"(r23),
;           [e01] "v"(e01), [e23] "v"(e23), [vi] "v"(vi));
;     S[0] = s0; S[1] = s1; S[2] = s2; S[3] = s3; ypo = yp;
; }
; __device__ __forceinline__ float h2f_lo(unsigned u) { return (float)__builtin_bit_cast(__fp16, (unsigned short)(u & 0xffffu)); }
; __device__ __forceinline__ float h2f_hi(unsigned u) { return (float)__builtin_bit_cast(__fp16, (unsigned short)(u >> 16)); }
	v_fma_mix_f32 v26, v179, v26, v26 op_sel:[0,0,0] op_sel_hi:[1,0,0]
	v_fma_mix_f32 v27, v179, v27, v27 op_sel:[1,0,0] op_sel_hi:[1,0,0]
	v_add_f32_dpp v226, v226, v226 quad_perm:[2,3,0,1] row_mask:0xf bank_mask:0xf bound_ctrl:1
	v_add_f32_dpp v221, v221, v221 quad_perm:[2,3,0,1] row_mask:0xf bank_mask:0xf bound_ctrl:1
	v_fma_mix_f32 v24, v196, v173, v24 op_sel:[0,0,0] op_sel_hi:[1,0,0]
	v_fma_mix_f32 v25, v196, v173, v25 op_sel:[1,0,0] op_sel_hi:[1,0,0]
	v_add_f32_dpp v226, v226, v226 row_half_mirror row_mask:0xf bank_mask:0xf bound_ctrl:1
	v_fma_mix_f32 v26, v197, v173, v26 op_sel:[0,0,0] op_sel_hi:[1,0,0]
	v_fma_mix_f32 v27, v197, v173, v27 op_sel:[1,0,0] op_sel_hi:[1,0,0]
	v_add_f32_dpp v226, v226, v226 row_mirror row_mask:0xf bank_mask:0xf bound_ctrl:1
	v_fma_mix_f32 v24, v194, v226, v24 op_sel:[0,0,0] op_sel_hi:[1,0,0]
	v_fma_mix_f32 v25, v194, v226, v25 op_sel:[1,0,0] op_sel_hi:[1,0,0]
	v_fma_mix_f32 v26, v195, v226, v26 op_sel:[0,0,0] op_sel_hi:[1,0,0]
	v_fma_mix_f32 v27, v195, v226, v27 op_sel:[1,0,0] op_sel_hi:[1,0,0]
	v_fma_mix_f32 v224, v24, v200, 0 op_sel:[0,0,0] op_sel_hi:[0,1,0]
	v_fma_mix_f32 v225, v26, v201, 0 op_sel:[0,0,0] op_sel_hi:[0,1,0]
	v_fma_mix_f32 v222, v24, v198, 0 op_sel:[0,0,0] op_sel_hi:[0,1,0]
	v_fma_mix_f32 v224, v25, v200, v224 op_sel:[0,1,0] op_sel_hi:[0,1,0]
	v_fma_mix_f32 v225, v27, v201, v225 op_sel:[0,1,0] op_sel_hi:[0,1,0]
	v_fma_mix_f32 v222, v25, v198, v222 op_sel:[0,1,0] op_sel_hi:[0,1,0]
	v_add_f32 v224, v224, v225
	v_fma_mix_f32 v222, v26, v199, v222 op_sel:[0,0,0] op_sel_hi:[0,1,0]
	v_fma_mix_f32 v222, v27, v199, v222 op_sel:[0,1,0] op_sel_hi:[0,1,0]
	v_fma_mix_f32 v24, v180, v24, v24 op_sel:[0,0,0] op_sel_hi:[1,0,0]
	v_fma_mix_f32 v25, v180, v25, v25 op_sel:[1,0,0] op_sel_hi:[1,0,0]
	v_add_f32_dpp v224, v224, v224 quad_perm:[1,0,3,2] row_mask:0xf bank_mask:0xf bound_ctrl:1
	v_add_f32_dpp v222, v222, v222 quad_perm:[1,0,3,2] row_mask:0xf bank_mask:0xf bound_ctrl:1
	v_fma_mix_f32 v26, v181, v26, v26 op_sel:[0,0,0] op_sel_hi:[1,0,0]
	v_fma_mix_f32 v27, v181, v27, v27 op_sel:[1,0,0] op_sel_hi:[1,0,0]
	v_add_f32_dpp v224, v224, v224 quad_perm:[2,3,0,1] row_mask:0xf bank_mask:0xf bound_ctrl:1
	v_add_f32_dpp v222, v222, v222 quad_perm:[2,3,0,1] row_mask:0xf bank_mask:0xf bound_ctrl:1
	v_fma_mix_f32 v24, v204, v174, v24 op_sel:[0,0,0] op_sel_hi:[1,0,0]
	v_fma_mix_f32 v25, v204, v174, v25 op_sel:[1,0,0] op_sel_hi:[1,0,0]
	v_add_f32_dpp v224, v224, v224 row_half_mirror row_mask:0xf bank_mask:0xf bound_ctrl:1
	v_fma_mix_f32 v26, v205, v174, v26 op_sel:[0,0,0] op_sel_hi:[1,0,0]
	v_fma_mix_f32 v27, v205, v174, v27 op_sel:[1,0,0] op_sel_hi:[1,0,0]
	v_add_f32_dpp v224, v224, v224 row_mirror row_mask:0xf bank_mask:0xf bound_ctrl:1
	v_fma_mix_f32 v24, v202, v224, v24 op_sel:[0,0,0] op_sel_hi:[1,0,0]
	v_fma_mix_f32 v25, v202, v224, v25 op_sel:[1,0,0] op_sel_hi:[1,0,0]
	v_fma_mix_f32 v26, v203, v224, v26 op_sel:[0,0,0] op_sel_hi:[1,0,0]
	v_fma_mix_f32 v27, v203, v224, v27 op_sel:[1,0,0] op_sel_hi:[1,0,0]
	v_fma_mix_f32 v226, v24, v208, 0 op_sel:[0,0,0] op_sel_hi:[0,1,0]
	v_fma_mix_f32 v227, v26, v209, 0 op_sel:[0,0,0] op_sel_hi:[0,1,0]
	v_fma_mix_f32 v223, v24, v206, 0 op_sel:[0,0,0] op_sel_hi:[0,1,0]
	v_fma_mix_f32 v226, v25, v208, v226 op_sel:[0,1,0] op_sel_hi:[0,1,0]
	v_fma_mix_f32 v227, v27, v209, v227 op_sel:[0,1,0] op_sel_hi:[0,1,0]
	v_fma_mix_f32 v223, v25, v206, v223 op_sel:[0,1,0] op_sel_hi:[0,1,0]
	v_add_f32 v226, v226, v227
	v_fma_mix_f32 v223, v26, v207, v223 op_sel:[0,0,0] op_sel_hi:[0,1,0]
	v_fma_mix_f32 v223, v27, v207, v223 op_sel:[0,1,0] op_sel_hi:[0,1,0]
	v_fma_mix_f32 v24, v182, v24, v24 op_sel:[0,0,0] op_sel_hi:[1,0,0]
	v_fma_mix_f32 v25, v182, v25, v25 op_sel:[1,0,0] op_sel_hi:[1,0,0]
	v_add_f32_dpp v226, v226, v226 quad_perm:[1,0,3,2] row_mask:0xf bank_mask:0xf bound_ctrl:1
	v_add_f32_dpp v223, v223, v223 quad_perm:[1,0,3,2] row_mask:0xf bank_mask:0xf bound_ctrl:1
	v_fma_mix_f32 v26, v183, v26, v26 op_sel:[0,0,0] op_sel_hi:[1,0,0]
	v_fma_mix_f32 v27, v183, v27, v27 op_sel:[1,0,0] op_sel_hi:[1,0,0]
	v_add_f32_dpp v226, v226, v226 quad_perm:[2,3,0,1] row_mask:0xf bank_mask:0xf bound_ctrl:1
	v_add_f32_dpp v223, v223, v223 quad_perm:[2,3,0,1] row_mask:0xf bank_mask:0xf bound_ctrl:1
	v_fma_mix_f32 v24, v212, v175, v24 op_sel:[0,0,0] op_sel_hi:[1,0,0]
	v_fma_mix_f32 v25, v212, v175, v25 op_sel:[1,0,0] op_sel_hi:[1,0,0]
	v_add_f32_dpp v226, v226, v226 row_half_mirror row_mask:0xf bank_mask:0xf bound_ctrl:1
	v_fma_mix_f32 v26, v213, v175, v26 op_sel:[0,0,0] op_sel_hi:[1,0,0]
	v_fma_mix_f32 v27, v213, v175, v27 op_sel:[1,0,0] op_sel_hi:[1,0,0]
	v_add_f32_dpp v226, v226, v226 row_mirror row_mask:0xf bank_mask:0xf bound_ctrl:1
	v_fma_mix_f32 v24, v210, v226, v24 op_sel:[0,0,0] op_sel_hi:[1,0,0]
	v_fma_mix_f32 v25, v210, v226, v25 op_sel:[1,0,0] op_sel_hi:[1,0,0]
	v_fma_mix_f32 v26, v211, v226, v26 op_sel:[0,0,0] op_sel_hi:[1,0,0]
	v_fma_mix_f32 v27, v211, v226, v27 op_sel:[1,0,0] op_sel_hi:[1,0,0]
	s_and_saveexec_b64 s[44:45], s[10:11]
	ds_write_b128 v99, v[220:223] offset:80
	s_or_b64 exec, exec, s[44:45]
	v_mov_b32_e32 v228, v214
	v_mov_b32_e32 v229, v215
	ds_read_b128 v[172:175], v61 offset:24688
	ds_read_b128 v[176:179], v60 offset:18176
	ds_read_b128 v[180:183], v60 offset:20224
	ds_read_b128 v[184:187], v60 offset:7168
	ds_read_b128 v[188:191], v60 offset:15360
	ds_read_b128 v[192:195], v60 offset:7424
	ds_read_b128 v[196:199], v60 offset:15616
	ds_read_b128 v[200:203], v60 offset:7680
	ds_read_b128 v[204:207], v60 offset:15872
	ds_read_b128 v[208:211], v60 offset:7936
	ds_read_b128 v[212:215], v60 offset:16128
	s_waitcnt lgkmcnt(11)
; __device__ __forceinline__ void scan_step(f32x4& S, float& ypo, const u32x4& h0, const u32x4& h1, unsigned e01, unsigned e23, unsigned r01, unsigned r23, float vi) {
;     float s0 = S[0], s1 = S[1], s2 = S[2], s3 = S[3], sa, yp, sb;
;     asm volatile(
;         MIX_SH("%[sa]", "%[s0]", "%[n01]", "0", "0") MIX_SH("%[sb]", "%[s2]", "%[n23]", "0", "0") MIX_SH("%[yp]", "%[s0]", "%[r01]", "0", "0")
;         MIX_SH("%[sa]", "%[s1]", "%[n01]", "%[sa]", "1") MIX_SH("%[sb]", "%[s3]", "%[n23]", "%[sb]", "1") MIX_SH("%[yp]", "%[s1]", "%[r01]", "%[yp]", "1")
;         "v_add_f32 %[sa], %[sa], %[sb]\n\t" MIX_SH("%[yp]", "%[s2]", "%[r23]", "%[yp]", "0") MIX_SH("%[yp]", "%[s3]", "%[r23]", "%[yp]", "1")
;         "v_fma_mix_f32 %[s0], %[e01], %[s0], %[s0] op_sel:[0,0,0] op_sel_hi:[1,0,0]\n\t" "v_fma_mix_f32 %[s1], %[e01], %[s1], %[s1] op_sel:[1,0,0] op_sel_hi:[1,0,0]\n\t"
;         DPP_ADD("%[sa]", "quad_perm:[1,0,3,2]") DPP_ADD("%[yp]", "quad_perm:[1,0,3,2]")
;         "v_fma_mix_f32 %[s2], %[e23], %[s2], %[s2] op_sel:[0,0,0] op_sel_hi:[1,0,0]\n\t" "v_fma_mix_f32 %[s3], %[e23], %[s3], %[s3] op_sel:[1,0,0] op_sel_hi:[1,0,0]\n\t"
;         DPP_ADD("%[sa]", "quad_perm:[2,3,0,1]") DPP_ADD("%[yp]", "quad_perm:[2,3,0,1]")
;         MIX_HS("%[s0]", "%[p01]", "%[vi]", "0") MIX_HS("%[s1]", "%[p01]", "%[vi]", "1")
;         DPP_ADD("%[sa]", "row_half_mirror")
;         MIX_HS("%[s2]", "%[p23]", "%[vi]", "0") MIX_HS("%[s3]", "%[p23]", "%[vi]", "1")
;         DPP_ADD("%[sa]", "row_mirror")
;         MIX_HS("%[s0]", "%[b01]", "%[sa]", "0") MIX_HS("%[s1]", "%[b01]", "%[sa]", "1") MIX_HS("%[s2]", "%[b23]", "%[sa]", "0") "v_fma_mix_f32 %[s3], %[b23], %[sa], %[s3] op_sel:[1,0,0] op_sel_hi:[1,0,0]"
;         : [s0] "+v"(s0), [s1] "+v"(s1), [s2] "+v"(s2), [s3] "+v"(s3), [sa] "=&v"(sa), [yp] "=&v"(yp), [sb] "=&v"(sb)
;         : [n01] "v"(h0.x), [n23] "v"(h0.y), [b01] "v"(h0.z), [b23] "v"(h0.w), [p01] "v"(h1.x), [p23] "v"(h1.y), [r01] "v"(r01), [r23] "v"(r23),
;           [e01] "v"(e01), [e23] "v"(e23), [vi] "v"(vi));
;     S[0] = s0; S[1] = s1; S[2] = s2; S[3] = s3; ypo = yp;
; }
; __device__ __forceinline__ float h2f_lo(unsigned u) { return (float)__builtin_bit_cast(__fp16, (unsigned short)(u & 0xffffu)); }
; __device__ __forceinline__ float h2f_hi(unsigned u) { return (float)__builtin_bit_cast(__fp16, (unsigned short)(u >> 16)); }
	v_fma_mix_f32 v224, v24, v112, 0 op_sel:[0,0,0] op_sel_hi:[0,1,0]
	v_fma_mix_f32 v225, v26, v113, 0 op_sel:[0,0,0] op_sel_hi:[0,1,0]
	v_fma_mix_f32 v216, v24, v228, 0 op_sel:[0,0,0] op_sel_hi:[0,1,0]
	v_fma_mix_f32 v224, v25, v112, v224 op_sel:[0,1,0] op_sel_hi:[0,1,0]
	v_fma_mix_f32 v225, v27, v113, v225 op_sel:[0,1,0] op_sel_hi:[0,1,0]
	v_fma_mix_f32 v216, v25, v228, v216 op_sel:[0,1,0] op_sel_hi:[0,1,0]
	v_add_f32 v224, v224, v225
	v_fma_mix_f32 v216, v26, v229, v216 op_sel:[0,0,0] op_sel_hi:[0,1,0]
	v_fma_mix_f32 v216, v27, v229, v216 op_sel:[0,1,0] op_sel_hi:[0,1,0]
	v_fma_mix_f32 v24, v104, v24, v24 op_sel:[0,0,0] op_sel_hi:[1,0,0]
	v_fma_mix_f32 v25, v104, v25, v25 op_sel:[1,0,0] op_sel_hi:[1,0,0]
	v_add_f32_dpp v224, v224, v224 quad_perm:[1,0,3,2] row_mask:0xf bank_mask:0xf bound_ctrl:1
	v_add_f32_dpp v216, v216, v216 quad_perm:[1,0,3,2] row_mask:0xf bank_mask:0xf bound_ctrl:1
	v_fma_mix_f32 v26, v105, v26, v26 op_sel:[0,0,0] op_sel_hi:[1,0,0]
	v_fma_mix_f32 v27, v105, v27, v27 op_sel:[1,0,0] op_sel_hi:[1,0,0]
	v_add_f32_dpp v224, v224, v224 quad_perm:[2,3,0,1] row_mask:0xf bank_mask:0xf bound_ctrl:1
	v_add_f32_dpp v216, v216, v216 quad_perm:[2,3,0,1] row_mask:0xf bank_mask:0xf bound_ctrl:1
	v_fma_mix_f32 v24, v116, v100, v24 op_sel:[0,0,0] op_sel_hi:[1,0,0]
	v_fma_mix_f32 v25, v116, v100, v25 op_sel:[1,0,0] op_sel_hi:[1,0,0]
	v_add_f32_dpp v224, v224, v224 row_half_mirror row_mask:0xf bank_mask:0xf bound_ctrl:1
	v_fma_mix_f32 v26, v117, v100, v26 op_sel:[0,0,0] op_sel_hi:[1,0,0]
	v_fma_mix_f32 v27, v117, v100, v27 op_sel:[1,0,0] op_sel_hi:[1,0,0]
	v_add_f32_dpp v224, v224, v224 row_mirror row_mask:0xf bank_mask:0xf bound_ctrl:1
	v_fma_mix_f32 v24, v114, v224, v24 op_sel:[0,0,0] op_sel_hi:[1,0,0]
	v_fma_mix_f32 v25, v114, v224, v25 op_sel:[1,0,0] op_sel_hi:[1,0,0]
	v_fma_mix_f32 v26, v115, v224, v26 op_sel:[0,0,0] op_sel_hi:[1,0,0]
	v_fma_mix_f32 v27, v115, v224, v27 op_sel:[1,0,0] op_sel_hi:[1,0,0]
	v_fma_mix_f32 v226, v24, v120, 0 op_sel:[0,0,0] op_sel_hi:[0,1,0]
	v_fma_mix_f32 v227, v26, v121, 0 op_sel:[0,0,0] op_sel_hi:[0,1,0]
	v_fma_mix_f32 v217, v24, v118, 0 op_sel:[0,0,0] op_sel_hi:[0,1,0]
	v_fma_mix_f32 v226, v25, v120, v226 op_sel:[0,1,0] op_sel_hi:[0,1,0]
	v_fma_mix_f32 v227, v27, v121, v227 op_sel:[0,1,0] op_sel_hi:[0,1,0]
	v_fma_mix_f32 v217, v25, v118, v217 op_sel:[0,1,0] op_sel_hi:[0,1,0]
	v_add_f32 v226, v226, v227
	v_fma_mix_f32 v217, v26, v119, v217 op_sel:[0,0,0] op_sel_hi:[0,1,0]
	v_fma_mix_f32 v217, v27, v119, v217 op_sel:[0,1,0] op_sel_hi:[0,1,0]
	v_fma_mix_f32 v24, v106, v24, v24 op_sel:[0,0,0] op_sel_hi:[1,0,0]
	v_fma_mix_f32 v25, v106, v25, v25 op_sel:[1,0,0] op_sel_hi:[1,0,0]
	v_add_f32_dpp v226, v226, v226 quad_perm:[1,0,3,2] row_mask:0xf bank_mask:0xf bound_ctrl:1
	v_add_f32_dpp v217, v217, v217 quad_perm:[1,0,3,2] row_mask:0xf bank_mask:0xf bound_ctrl:1
	v_fma_mix_f32 v26, v107, v26, v26 op_sel:[0,0,0] op_sel_hi:[1,0,0]
	v_fma_mix_f32 v27, v107, v27, v27 op_sel:[1,0,0] op_sel_hi:[1,0,0]
	v_add_f32_dpp v226, v226, v226 quad_perm:[2,3,0,1] row_mask:0xf bank_mask:0xf bound_ctrl:1
	v_add_f32_dpp v217, v217, v217 quad_perm:[2,3,0,1] row_mask:0xf bank_mask:0xf bound_ctrl:1
	v_fma_mix_f32 v24, v124, v101, v24 op_sel:[0,0,0] op_sel_hi:[1,0,0]
	v_fma_mix_f32 v25, v124, v101, v25 op_sel:[1,0,0] op_sel_hi:[1,0,0]
	v_add_f32_dpp v226, v226, v226 row_half_mirror row_mask:0xf bank_mask:0xf bound_ctrl:1
	v_fma_mix_f32 v26, v125, v101, v26 op_sel:[0,0,0] op_sel_hi:[1,0,0]
	v_fma_mix_f32 v27, v125, v101, v27 op_sel:[1,0,0] op_sel_hi:[1,0,0]
	v_add_f32_dpp v226, v226, v226 row_mirror row_mask:0xf bank_mask:0xf bound_ctrl:1
	v_fma_mix_f32 v24, v122, v226, v24 op_sel:[0,0,0] op_sel_hi:[1,0,0]
	v_fma_mix_f32 v25, v122, v226, v25 op_sel:[1,0,0] op_sel_hi:[1,0,0]
	v_fma_mix_f32 v26, v123, v226, v26 op_sel:[0,0,0] op_sel_hi:[1,0,0]
	v_fma_mix_f32 v27, v123, v226, v27 op_sel:[1,0,0] op_sel_hi:[1,0,0]
	v_fma_mix_f32 v224, v24, v128, 0 op_sel:[0,0,0] op_sel_hi:[0,1,0]
	v_fma_mix_f32 v225, v26, v129, 0 op_sel:[0,0,0] op_sel_hi:[0,1,0]
	v_fma_mix_f32 v218, v24, v126, 0 op_sel:[0,0,0] op_sel_hi:[0,1,0]
	v_fma_mix_f32 v224, v25, v128, v224 op_sel:[0,1,0] op_sel_hi:[0,1,0]
	v_fma_mix_f32 v225, v27, v129, v225 op_sel:[0,1,0] op_sel_hi:[0,1,0]
	v_fma_mix_f32 v218, v25, v126, v218 op_sel:[0,1,0] op_sel_hi:[0,1,0]
	v_add_f32 v224, v224, v225
	v_fma_mix_f32 v218, v26, v127, v218 op_sel:[0,0,0] op_sel_hi:[0,1,0]
	v_fma_mix_f32 v218, v27, v127, v218 op_sel:[0,1,0] op_sel_hi:[0,1,0]
	v_fma_mix_f32 v24, v108, v24, v24 op_sel:[0,0,0] op_sel_hi:[1,0,0]
	v_fma_mix_f32 v25, v108, v25, v25 op_sel:[1,0,0] op_sel_hi:[1,0,0]
	v_add_f32_dpp v224, v224, v224 quad_perm:[1,0,3,2] row_mask:0xf bank_mask:0xf bound_ctrl:1
	v_add_f32_dpp v218, v218, v218 quad_perm:[1,0,3,2] row_mask:0xf bank_mask:0xf bound_ctrl:1
	v_fma_mix_f32 v26, v109, v26, v26 op_sel:[0,0,0] op_sel_hi:[1,0,0]
	v_fma_mix_f32 v27, v109, v27, v27 op_sel:[1,0,0] op_sel_hi:[1,0,0]
	v_add_f32_dpp v224, v224, v224 quad_perm:[2,3,0,1] row_mask:0xf bank_mask:0xf bound_ctrl:1
	v_add_f32_dpp v218, v218, v218 quad_perm:[2,3,0,1] row_mask:0xf bank_mask:0xf bound_ctrl:1
	v_fma_mix_f32 v24, v132, v102, v24 op_sel:[0,0,0] op_sel_hi:[1,0,0]
	v_fma_mix_f32 v25, v132, v102, v25 op_sel:[1,0,0] op_sel_hi:[1,0,0]
	v_add_f32_dpp v224, v224, v224 row_half_mirror row_mask:0xf bank_mask:0xf bound_ctrl:1
	v_fma_mix_f32 v26, v133, v102, v26 op_sel:[0,0,0] op_sel_hi:[1,0,0]
	v_fma_mix_f32 v27, v133, v102, v27 op_sel:[1,0,0] op_sel_hi:[1,0,0]
	v_add_f32_dpp v224, v224, v224 row_mirror row_mask:0xf bank_mask:0xf bound_ctrl:1
	v_fma_mix_f32 v24, v130, v224, v24 op_sel:[0,0,0] op_sel_hi:[1,0,0]
; __device__ __forceinline__ void scan_step(f32x4& S, float& ypo, const u32x4& h0, const u32x4& h1, unsigned e01, unsigned e23, unsigned r01, unsigned r23, float vi) {
;     float s0 = S[0], s1 = S[1], s2 = S[2], s3 = S[3], sa, yp, sb;
;     asm volatile(
;         MIX_SH("%[sa]", "%[s0]", "%[n01]", "0", "0") MIX_SH("%[sb]", "%[s2]", "%[n23]", "0", "0") MIX_SH("%[yp]", "%[s0]", "%[r01]", "0", "0")
;         MIX_SH("%[sa]", "%[s1]", "%[n01]", "%[sa]", "1") MIX_SH("%[sb]", "%[s3]", "%[n23]", "%[sb]", "1") MIX_SH("%[yp]", "%[s1]", "%[r01]", "%[yp]", "1")
;         "v_add_f32 %[sa], %[sa], %[sb]\n\t" MIX_SH("%[yp]", "%[s2]", "%[r23]", "%[yp]", "0") MIX_SH("%[yp]", "%[s3]", "%[r23]", "%[yp]", "1")
;         "v_fma_mix_f32 %[s0], %[e01], %[s0], %[s0] op_sel:[0,0,0] op_sel_hi:[1,0,0]\n\t" "v_fma_mix_f32 %[s1], %[e01], %[s1], %[s1] op_sel:[1,0,0] op_sel_hi:[1,0,0]\n\t"
;         DPP_ADD("%[sa]", "quad_perm:[1,0,3,2]") DPP_ADD("%[yp]", "quad_perm:[1,0,3,2]")
;         "v_fma_mix_f32 %[s2], %[e23], %[s2], %[s2] op_sel:[0,0,0] op_sel_hi:[1,0,0]\n\t" "v_fma_mix_f32 %[s3], %[e23], %[s3], %[s3] op_sel:[1,0,0] op_sel_hi:[1,0,0]\n\t"
;         DPP_ADD("%[sa]", "quad_perm:[2,3,0,1]") DPP_ADD("%[yp]", "quad_perm:[2,3,0,1]")
;         MIX_HS("%[s0]", "%[p01]", "%[vi]", "0") MIX_HS("%[s1]", "%[p01]", "%[vi]", "1")
;         DPP_ADD("%[sa]", "row_half_mirror")
;         MIX_HS("%[s2]", "%[p23]", "%[vi]", "0") MIX_HS("%[s3]", "%[p23]", "%[vi]", "1")
;         DPP_ADD("%[sa]", "row_mirror")
;         MIX_HS("%[s0]", "%[b01]", "%[sa]", "0") MIX_HS("%[s1]", "%[b01]", "%[sa]", "1") MIX_HS("%[s2]", "%[b23]", "%[sa]", "0") "v_fma_mix_f32 %[s3], %[b23], %[sa], %[s3] op_sel:[1,0,0] op_sel_hi:[1,0,0]"
;         : [s0] "+v"(s0), [s1] "+v"(s1), [s2] "+v"(s2), [s3] "+v"(s3), [sa] "=&v"(sa), [yp] "=&v"(yp), [sb] "=&v"(sb)
;         : [n01] "v"(h0.x), [n23] "v"(h0.y), [b01] "v"(h0.z), [b23] "v"(h0.w), [p01] "v"(h1.x), [p23] "v"(h1.y), [r01] "v"(r01), [r23] "v"(r23),
;           [e01] "v"(e01), [e23] "v"(e23), [vi] "v"(vi));
;     S[0] = s0; S[1] = s1; S[2] = s2; S[3] = s3; ypo = yp;
; }
; __device__ __forceinline__ float h2f_lo(unsigned u) { return (float)__builtin_bit_cast(__fp16, (unsigned short)(u & 0xffffu)); }
; __device__ __forceinline__ float h2f_hi(unsigned u) { return (float)__builtin_bit_cast(__fp16, (unsigned short)(u >> 16)); }
	v_fma_mix_f32 v25, v130, v224, v25 op_sel:[1,0,0] op_sel_hi:[1,0,0]
	v_fma_mix_f32 v26, v131, v224, v26 op_sel:[0,0,0] op_sel_hi:[1,0,0]
	v_fma_mix_f32 v27, v131, v224, v27 op_sel:[1,0,0] op_sel_hi:[1,0,0]
	v_fma_mix_f32 v226, v24, v140, 0 op_sel:[0,0,0] op_sel_hi:[0,1,0]
	v_fma_mix_f32 v227, v26, v141, 0 op_sel:[0,0,0] op_sel_hi:[0,1,0]
	v_fma_mix_f32 v219, v24, v134, 0 op_sel:[0,0,0] op_sel_hi:[0,1,0]
	v_fma_mix_f32 v226, v25, v140, v226 op_sel:[0,1,0] op_sel_hi:[0,1,0]
	v_fma_mix_f32 v227, v27, v141, v227 op_sel:[0,1,0] op_sel_hi:[0,1,0]
	v_fma_mix_f32 v219, v25, v134, v219 op_sel:[0,1,0] op_sel_hi:[0,1,0]
	v_add_f32 v226, v226, v227
	v_fma_mix_f32 v219, v26, v135, v219 op_sel:[0,0,0] op_sel_hi:[0,1,0]
	v_fma_mix_f32 v219, v27, v135, v219 op_sel:[0,1,0] op_sel_hi:[0,1,0]
	v_fma_mix_f32 v24, v110, v24, v24 op_sel:[0,0,0] op_sel_hi:[1,0,0]
	v_fma_mix_f32 v25, v110, v25, v25 op_sel:[1,0,0] op_sel_hi:[1,0,0]
	v_add_f32_dpp v226, v226, v226 quad_perm:[1,0,3,2] row_mask:0xf bank_mask:0xf bound_ctrl:1
	v_add_f32_dpp v219, v219, v219 quad_perm:[1,0,3,2] row_mask:0xf bank_mask:0xf bound_ctrl:1
	v_fma_mix_f32 v26, v111, v26, v26 op_sel:[0,0,0] op_sel_hi:[1,0,0]
	v_fma_mix_f32 v27, v111, v27, v27 op_sel:[1,0,0] op_sel_hi:[1,0,0]
	v_add_f32_dpp v226, v226, v226 quad_perm:[2,3,0,1] row_mask:0xf bank_mask:0xf bound_ctrl:1
	v_add_f32_dpp v219, v219, v219 quad_perm:[2,3,0,1] row_mask:0xf bank_mask:0xf bound_ctrl:1
	v_fma_mix_f32 v24, v52, v103, v24 op_sel:[0,0,0] op_sel_hi:[1,0,0]
	v_fma_mix_f32 v25, v52, v103, v25 op_sel:[1,0,0] op_sel_hi:[1,0,0]
	v_add_f32_dpp v226, v226, v226 row_half_mirror row_mask:0xf bank_mask:0xf bound_ctrl:1
	v_fma_mix_f32 v26, v53, v103, v26 op_sel:[0,0,0] op_sel_hi:[1,0,0]
	v_fma_mix_f32 v27, v53, v103, v27 op_sel:[1,0,0] op_sel_hi:[1,0,0]
	v_add_f32_dpp v226, v226, v226 row_mirror row_mask:0xf bank_mask:0xf bound_ctrl:1
	v_fma_mix_f32 v24, v142, v226, v24 op_sel:[0,0,0] op_sel_hi:[1,0,0]
	v_fma_mix_f32 v25, v142, v226, v25 op_sel:[1,0,0] op_sel_hi:[1,0,0]
	v_fma_mix_f32 v26, v143, v226, v26 op_sel:[0,0,0] op_sel_hi:[1,0,0]
	v_fma_mix_f32 v27, v143, v226, v27 op_sel:[1,0,0] op_sel_hi:[1,0,0]
	s_and_saveexec_b64 s[44:45], s[10:11]
	ds_write_b128 v99, v[216:219] offset:96
	s_or_b64 exec, exec, s[44:45]
	v_mov_b32_e32 v228, v54
	v_mov_b32_e32 v229, v55
	s_waitcnt lgkmcnt(0)
	v_fma_mix_f32 v224, v24, v184, 0 op_sel:[0,0,0] op_sel_hi:[0,1,0]
	v_fma_mix_f32 v225, v26, v185, 0 op_sel:[0,0,0] op_sel_hi:[0,1,0]
	v_fma_mix_f32 v220, v24, v228, 0 op_sel:[0,0,0] op_sel_hi:[0,1,0]
	v_fma_mix_f32 v224, v25, v184, v224 op_sel:[0,1,0] op_sel_hi:[0,1,0]
	v_fma_mix_f32 v225, v27, v185, v225 op_sel:[0,1,0] op_sel_hi:[0,1,0]
	v_fma_mix_f32 v220, v25, v228, v220 op_sel:[0,1,0] op_sel_hi:[0,1,0]
	v_add_f32 v224, v224, v225
	v_fma_mix_f32 v220, v26, v229, v220 op_sel:[0,0,0] op_sel_hi:[0,1,0]
	v_fma_mix_f32 v220, v27, v229, v220 op_sel:[0,1,0] op_sel_hi:[0,1,0]
	v_fma_mix_f32 v24, v176, v24, v24 op_sel:[0,0,0] op_sel_hi:[1,0,0]
	v_fma_mix_f32 v25, v176, v25, v25 op_sel:[1,0,0] op_sel_hi:[1,0,0]
	v_add_f32_dpp v224, v224, v224 quad_perm:[1,0,3,2] row_mask:0xf bank_mask:0xf bound_ctrl:1
	v_add_f32_dpp v220, v220, v220 quad_perm:[1,0,3,2] row_mask:0xf bank_mask:0xf bound_ctrl:1
	v_fma_mix_f32 v26, v177, v26, v26 op_sel:[0,0,0] op_sel_hi:[1,0,0]
	v_fma_mix_f32 v27, v177, v27, v27 op_sel:[1,0,0] op_sel_hi:[1,0,0]
	v_add_f32_dpp v224, v224, v224 quad_perm:[2,3,0,1] row_mask:0xf bank_mask:0xf bound_ctrl:1
	v_add_f32_dpp v220, v220, v220 quad_perm:[2,3,0,1] row_mask:0xf bank_mask:0xf bound_ctrl:1
	v_fma_mix_f32 v24, v188, v172, v24 op_sel:[0,0,0] op_sel_hi:[1,0,0]
	v_fma_mix_f32 v25, v188, v172, v25 op_sel:[1,0,0] op_sel_hi:[1,0,0]
	v_add_f32_dpp v224, v224, v224 row_half_mirror row_mask:0xf bank_mask:0xf bound_ctrl:1
	v_fma_mix_f32 v26, v189, v172, v26 op_sel:[0,0,0] op_sel_hi:[1,0,0]
	v_fma_mix_f32 v27, v189, v172, v27 op_sel:[1,0,0] op_sel_hi:[1,0,0]
	v_add_f32_dpp v224, v224, v224 row_mirror row_mask:0xf bank_mask:0xf bound_ctrl:1
	v_fma_mix_f32 v24, v186, v224, v24 op_sel:[0,0,0] op_sel_hi:[1,0,0]
	v_fma_mix_f32 v25, v186, v224, v25 op_sel:[1,0,0] op_sel_hi:[1,0,0]
	v_fma_mix_f32 v26, v187, v224, v26 op_sel:[0,0,0] op_sel_hi:[1,0,0]
	v_fma_mix_f32 v27, v187, v224, v27 op_sel:[1,0,0] op_sel_hi:[1,0,0]
	v_fma_mix_f32 v226, v24, v192, 0 op_sel:[0,0,0] op_sel_hi:[0,1,0]
	v_fma_mix_f32 v227, v26, v193, 0 op_sel:[0,0,0] op_sel_hi:[0,1,0]
	v_fma_mix_f32 v221, v24, v190, 0 op_sel:[0,0,0] op_sel_hi:[0,1,0]
	v_fma_mix_f32 v226, v25, v192, v226 op_sel:[0,1,0] op_sel_hi:[0,1,0]
	v_fma_mix_f32 v227, v27, v193, v227 op_sel:[0,1,0] op_sel_hi:[0,1,0]
	v_fma_mix_f32 v221, v25, v190, v221 op_sel:[0,1,0] op_sel_hi:[0,1,0]
	v_add_f32 v226, v226, v227
	v_fma_mix_f32 v221, v26, v191, v221 op_sel:[0,0,0] op_sel_hi:[0,1,0]
	v_fma_mix_f32 v221, v27, v191, v221 op_sel:[0,1,0] op_sel_hi:[0,1,0]
	v_fma_mix_f32 v24, v178, v24, v24 op_sel:[0,0,0] op_sel_hi:[1,0,0]
	v_fma_mix_f32 v25, v178, v25, v25 op_sel:[1,0,0] op_sel_hi:[1,0,0]
	v_add_f32_dpp v226, v226, v226 quad_perm:[1,0,3,2] row_mask:0xf bank_mask:0xf bound_ctrl:1
	v_add_f32_dpp v221, v221, v221 quad_perm:[1,0,3,2] row_mask:0xf bank_mask:0xf bound_ctrl:1
	v_fma_mix_f32 v26, v179, v26, v26 op_sel:[0,0,0] op_sel_hi:[1,0,0]
	v_fma_mix_f32 v27, v179, v27, v27 op_sel:[1,0,0] op_sel_hi:[1,0,0]
	v_add_f32_dpp v226, v226, v226 quad_perm:[2,3,0,1] row_mask:0xf bank_mask:0xf bound_ctrl:1
	v_add_f32_dpp v221, v221, v221 quad_perm:[2,3,0,1] row_mask:0xf bank_mask:0xf bound_ctrl:1
; __device__ __forceinline__ void scan_step(f32x4& S, float& ypo, const u32x4& h0, const u32x4& h1, unsigned e01, unsigned e23, unsigned r01, unsigned r23, float vi) {
;     float s0 = S[0], s1 = S[1], s2 = S[2], s3 = S[3], sa, yp, sb;
;     asm volatile(
;         MIX_SH("%[sa]", "%[s0]", "%[n01]", "0", "0") MIX_SH("%[sb]", "%[s2]", "%[n23]", "0", "0") MIX_SH("%[yp]", "%[s0]", "%[r01]", "0", "0")
;         MIX_SH("%[sa]", "%[s1]", "%[n01]", "%[sa]", "1") MIX_SH("%[sb]", "%[s3]", "%[n23]", "%[sb]", "1") MIX_SH("%[yp]", "%[s1]", "%[r01]", "%[yp]", "1")
;         "v_add_f32 %[sa], %[sa], %[sb]\n\t" MIX_SH("%[yp]", "%[s2]", "%[r23]", "%[yp]", "0") MIX_SH("%[yp]", "%[s3]", "%[r23]", "%[yp]", "1")
;         "v_fma_mix_f32 %[s0], %[e01], %[s0], %[s0] op_sel:[0,0,0] op_sel_hi:[1,0,0]\n\t" "v_fma_mix_f32 %[s1], %[e01], %[s1], %[s1] op_sel:[1,0,0] op_sel_hi:[1,0,0]\n\t"
;         DPP_ADD("%[sa]", "quad_perm:[1,0,3,2]") DPP_ADD("%[yp]", "quad_perm:[1,0,3,2]")
;         "v_fma_mix_f32 %[s2], %[e23], %[s2], %[s2] op_sel:[0,0,0] op_sel_hi:[1,0,0]\n\t" "v_fma_mix_f32 %[s3], %[e23], %[s3], %[s3] op_sel:[1,0,0] op_sel_hi:[1,0,0]\n\t"
;         DPP_ADD("%[sa]", "quad_perm:[2,3,0,1]") DPP_ADD("%[yp]", "quad_perm:[2,3,0,1]")
;         MIX_HS("%[s0]", "%[p01]", "%[vi]", "0") MIX_HS("%[s1]", "%[p01]", "%[vi]", "1")
;         DPP_ADD("%[sa]", "row_half_mirror")
;         MIX_HS("%[s2]", "%[p23]", "%[vi]", "0") MIX_HS("%[s3]", "%[p23]", "%[vi]", "1")
;         DPP_ADD("%[sa]", "row_mirror")
;         MIX_HS("%[s0]", "%[b01]", "%[sa]", "0") MIX_HS("%[s1]", "%[b01]", "%[sa]", "1") MIX_HS("%[s2]", "%[b23]", "%[sa]", "0") "v_fma_mix_f32 %[s3], %[b23], %[sa], %[s3] op_sel:[1,0,0] op_sel_hi:[1,0,0]"
;         : [s0] "+v"(s0), [s1] "+v"(s1), [s2] "+v"(s2), [s3] "+v"(s3), [sa] "=&v"(sa), [yp] "=&v"(yp), [sb] "=&v"(sb)
;         : [n01] "v"(h0.x), [n23] "v"(h0.y), [b01] "v"(h0.z), [b23] "v"(h0.w), [p01] "v"(h1.x), [p23] "v"(h1.y), [r01] "v"(r01), [r23] "v"(r23),
;           [e01] "v"(e01), [e23] "v"(e23), [vi] "v"(vi));
;     S[0] = s0; S[1] = s1; S[2] = s2; S[3] = s3; ypo = yp;
; }
; __device__ __forceinline__ float h2f_lo(unsigned u) { return (float)__builtin_bit_cast(__fp16, (unsigned short)(u & 0xffffu)); }
; __device__ __forceinline__ float h2f_hi(unsigned u) { return (float)__builtin_bit_cast(__fp16, (unsigned short)(u >> 16)); }
	v_fma_mix_f32 v24, v196, v173, v24 op_sel:[0,0,0] op_sel_hi:[1,0,0]
	v_fma_mix_f32 v25, v196, v173, v25 op_sel:[1,0,0] op_sel_hi:[1,0,0]
	v_add_f32_dpp v226, v226, v226 row_half_mirror row_mask:0xf bank_mask:0xf bound_ctrl:1
	v_fma_mix_f32 v26, v197, v173, v26 op_sel:[0,0,0] op_sel_hi:[1,0,0]
	v_fma_mix_f32 v27, v197, v173, v27 op_sel:[1,0,0] op_sel_hi:[1,0,0]
	v_add_f32_dpp v226, v226, v226 row_mirror row_mask:0xf bank_mask:0xf bound_ctrl:1
	v_fma_mix_f32 v24, v194, v226, v24 op_sel:[0,0,0] op_sel_hi:[1,0,0]
	v_fma_mix_f32 v25, v194, v226, v25 op_sel:[1,0,0] op_sel_hi:[1,0,0]
	v_fma_mix_f32 v26, v195, v226, v26 op_sel:[0,0,0] op_sel_hi:[1,0,0]
	v_fma_mix_f32 v27, v195, v226, v27 op_sel:[1,0,0] op_sel_hi:[1,0,0]
	v_fma_mix_f32 v224, v24, v200, 0 op_sel:[0,0,0] op_sel_hi:[0,1,0]
	v_fma_mix_f32 v225, v26, v201, 0 op_sel:[0,0,0] op_sel_hi:[0,1,0]
	v_fma_mix_f32 v222, v24, v198, 0 op_sel:[0,0,0] op_sel_hi:[0,1,0]
	v_fma_mix_f32 v224, v25, v200, v224 op_sel:[0,1,0] op_sel_hi:[0,1,0]
	v_fma_mix_f32 v225, v27, v201, v225 op_sel:[0,1,0] op_sel_hi:[0,1,0]
	v_fma_mix_f32 v222, v25, v198, v222 op_sel:[0,1,0] op_sel_hi:[0,1,0]
	v_add_f32 v224, v224, v225
	v_fma_mix_f32 v222, v26, v199, v222 op_sel:[0,0,0] op_sel_hi:[0,1,0]
	v_fma_mix_f32 v222, v27, v199, v222 op_sel:[0,1,0] op_sel_hi:[0,1,0]
	v_fma_mix_f32 v24, v180, v24, v24 op_sel:[0,0,0] op_sel_hi:[1,0,0]
	v_fma_mix_f32 v25, v180, v25, v25 op_sel:[1,0,0] op_sel_hi:[1,0,0]
	v_add_f32_dpp v224, v224, v224 quad_perm:[1,0,3,2] row_mask:0xf bank_mask:0xf bound_ctrl:1
	v_add_f32_dpp v222, v222, v222 quad_perm:[1,0,3,2] row_mask:0xf bank_mask:0xf bound_ctrl:1
	v_fma_mix_f32 v26, v181, v26, v26 op_sel:[0,0,0] op_sel_hi:[1,0,0]
	v_fma_mix_f32 v27, v181, v27, v27 op_sel:[1,0,0] op_sel_hi:[1,0,0]
	v_add_f32_dpp v224, v224, v224 quad_perm:[2,3,0,1] row_mask:0xf bank_mask:0xf bound_ctrl:1
	v_add_f32_dpp v222, v222, v222 quad_perm:[2,3,0,1] row_mask:0xf bank_mask:0xf bound_ctrl:1
	v_fma_mix_f32 v24, v204, v174, v24 op_sel:[0,0,0] op_sel_hi:[1,0,0]
	v_fma_mix_f32 v25, v204, v174, v25 op_sel:[1,0,0] op_sel_hi:[1,0,0]
	v_add_f32_dpp v224, v224, v224 row_half_mirror row_mask:0xf bank_mask:0xf bound_ctrl:1
	v_fma_mix_f32 v26, v205, v174, v26 op_sel:[0,0,0] op_sel_hi:[1,0,0]
	v_fma_mix_f32 v27, v205, v174, v27 op_sel:[1,0,0] op_sel_hi:[1,0,0]
	v_add_f32_dpp v224, v224, v224 row_mirror row_mask:0xf bank_mask:0xf bound_ctrl:1
	v_fma_mix_f32 v24, v202, v224, v24 op_sel:[0,0,0] op_sel_hi:[1,0,0]
	v_fma_mix_f32 v25, v202, v224, v25 op_sel:[1,0,0] op_sel_hi:[1,0,0]
	v_fma_mix_f32 v26, v203, v224, v26 op_sel:[0,0,0] op_sel_hi:[1,0,0]
	v_fma_mix_f32 v27, v203, v224, v27 op_sel:[1,0,0] op_sel_hi:[1,0,0]
	v_fma_mix_f32 v226, v24, v208, 0 op_sel:[0,0,0] op_sel_hi:[0,1,0]
	v_fma_mix_f32 v227, v26, v209, 0 op_sel:[0,0,0] op_sel_hi:[0,1,0]
	v_fma_mix_f32 v223, v24, v206, 0 op_sel:[0,0,0] op_sel_hi:[0,1,0]
	v_fma_mix_f32 v226, v25, v208, v226 op_sel:[0,1,0] op_sel_hi:[0,1,0]
	v_fma_mix_f32 v227, v27, v209, v227 op_sel:[0,1,0] op_sel_hi:[0,1,0]
	v_fma_mix_f32 v223, v25, v206, v223 op_sel:[0,1,0] op_sel_hi:[0,1,0]
	v_add_f32 v226, v226, v227
	v_fma_mix_f32 v223, v26, v207, v223 op_sel:[0,0,0] op_sel_hi:[0,1,0]
	v_fma_mix_f32 v223, v27, v207, v223 op_sel:[0,1,0] op_sel_hi:[0,1,0]
	v_fma_mix_f32 v24, v182, v24, v24 op_sel:[0,0,0] op_sel_hi:[1,0,0]
	v_fma_mix_f32 v25, v182, v25, v25 op_sel:[1,0,0] op_sel_hi:[1,0,0]
	v_add_f32_dpp v226, v226, v226 quad_perm:[1,0,3,2] row_mask:0xf bank_mask:0xf bound_ctrl:1
	v_add_f32_dpp v223, v223, v223 quad_perm:[1,0,3,2] row_mask:0xf bank_mask:0xf bound_ctrl:1
	v_fma_mix_f32 v26, v183, v26, v26 op_sel:[0,0,0] op_sel_hi:[1,0,0]
	v_fma_mix_f32 v27, v183, v27, v27 op_sel:[1,0,0] op_sel_hi:[1,0,0]
	v_add_f32_dpp v226, v226, v226 quad_perm:[2,3,0,1] row_mask:0xf bank_mask:0xf bound_ctrl:1
	v_add_f32_dpp v223, v223, v223 quad_perm:[2,3,0,1] row_mask:0xf bank_mask:0xf bound_ctrl:1
	v_fma_mix_f32 v24, v212, v175, v24 op_sel:[0,0,0] op_sel_hi:[1,0,0]
	v_fma_mix_f32 v25, v212, v175, v25 op_sel:[1,0,0] op_sel_hi:[1,0,0]
	v_add_f32_dpp v226, v226, v226 row_half_mirror row_mask:0xf bank_mask:0xf bound_ctrl:1
	v_fma_mix_f32 v26, v213, v175, v26 op_sel:[0,0,0] op_sel_hi:[1,0,0]
	v_fma_mix_f32 v27, v213, v175, v27 op_sel:[1,0,0] op_sel_hi:[1,0,0]
	v_add_f32_dpp v226, v226, v226 row_mirror row_mask:0xf bank_mask:0xf bound_ctrl:1
	v_fma_mix_f32 v24, v210, v226, v24 op_sel:[0,0,0] op_sel_hi:[1,0,0]
	v_fma_mix_f32 v25, v210, v226, v25 op_sel:[1,0,0] op_sel_hi:[1,0,0]
	v_fma_mix_f32 v26, v211, v226, v26 op_sel:[0,0,0] op_sel_hi:[1,0,0]
	v_fma_mix_f32 v27, v211, v226, v27 op_sel:[1,0,0] op_sel_hi:[1,0,0]
	s_and_saveexec_b64 s[44:45], s[10:11]
	ds_write_b128 v99, v[220:223] offset:112
	s_or_b64 exec, exec, s[44:45]
	v_mov_b32_e32 v58, v214
	v_mov_b32_e32 v59, v215
	v_cvt_f32_f16_e32 v52, v58
	v_mul_f32_e32 v52, v24, v52
	v_fma_mix_f32 v52, v25, v58, v52 op_sel:[0,1,0] op_sel_hi:[0,1,0]
	v_fma_mix_f32 v52, v26, v59, v52 op_sel_hi:[0,1,0]
	v_fma_mix_f32 v52, v27, v59, v52 op_sel:[0,1,0] op_sel_hi:[0,1,0]
	s_nop 1
	v_add_f32_dpp v52, v52, v52 quad_perm:[1,0,3,2] row_mask:0xf bank_mask:0xf bound_ctrl:1
	s_nop 1
	v_mov_b32_dpp v53, v52 quad_perm:[2,3,0,1] row_mask:0xf bank_mask:0xf bound_ctrl:1
	s_and_saveexec_b64 s[44:45], s[10:11]
	v_add_f32_e32 v52, v52, v53
	ds_write_b32 v99, v52 offset:128
	s_or_b64 exec, exec, s[44:45]
	v_mov_b64_e32 v[60:61], v[26:27]
	v_mov_b32_e32 v100, v27
	v_mov_b32_e32 v101, v26
	v_mov_b32_e32 v102, v25
	v_mov_b32_e32 v52, v24
	v_mov_b64_e32 v[58:59], v[24:25]

; #define MFMA16(a, b, c) __builtin_amdgcn_mfma_f32_16x16x32_bf16((a), (b), (c), 0, 0, 0)
; __device__ __forceinline__ void sgemm_resid(int tid, LAS unsigned char* lds, const bf16_t* A, const bf16_t* Bt, int K, float* x, float scale) {
;     ...
;         const bf16_t* bp = Bt + (size_t)(16 * t + fr) * K + kb; const bf16_t* ap = A + (size_t)fr * K + kb;
;         for (int k = 0; k < Kc; k += 128) { bf16x8 bv[4], av[4][8];
; #pragma unroll
;             for (int u = 0; u < 4; ++u) { const int kk = (k + 32 * u) < Kc ? (k + 32 * u) : k; bv[u] = *(const bf16x8*)(bp + kk);
; #pragma unroll
;                 for (int rb = 0; rb < 8; ++rb) av[u][rb] = *(const bf16x8*)(ap + (size_t)(16 * rb) * K + kk); }
; #pragma unroll
;             for (int u = 0; u < 4; ++u) if (k + 32 * u < Kc) {
; #pragma unroll
;                 for (int rb = 0; rb < 8; ++rb) acc[rb] = MFMA16(bv[u], av[u][rb], acc[rb]); } }
.LBB0_1610:
	v_lshl_add_u64 v[132:133], v[112:113], 0, s[26:27]
	v_lshl_add_u64 v[134:135], v[128:129], 0, s[26:27]
	s_waitcnt vmcnt(0)
	v_lshl_add_u64 v[44:45], v[132:133], 0, s[4:5]
	global_load_dwordx4 v[144:147], v[134:135], off
	v_lshl_add_u64 v[40:41], v[44:45], 0, s[4:5]
	v_lshl_add_u64 v[36:37], v[40:41], 0, s[4:5]
	v_lshl_add_u64 v[48:49], v[36:37], 0, s[4:5]
	v_lshl_add_u64 v[52:53], v[48:49], 0, s[4:5]
	v_lshl_add_u64 v[56:57], v[52:53], 0, s[4:5]
	global_load_dwordx4 v[32:35], v[48:49], off
	s_nop 0
	global_load_dwordx4 v[36:39], v[36:37], off
	s_nop 0
	global_load_dwordx4 v[40:43], v[40:41], off
	s_nop 0
	global_load_dwordx4 v[44:47], v[44:45], off
	s_nop 0
	global_load_dwordx4 v[48:51], v[56:57], off
	s_nop 0
	global_load_dwordx4 v[52:55], v[52:53], off
	s_add_i32 s33, s25, 32
	s_add_i32 s30, s25, 64
	s_cmp_lt_u32 s30, s19
	s_cselect_b64 s[38:39], -1, 0
	s_and_b64 s[36:37], s[38:39], exec
	s_cselect_b32 s30, s30, s25
	s_add_i32 s34, s25, 0x60
	s_lshl_b64 s[36:37], s[30:31], 1
	v_lshl_add_u64 v[56:57], v[56:57], 0, s[4:5]
	s_cmp_lt_u32 s34, s19
	global_load_dwordx4 v[148:151], v[56:57], off
	global_load_dwordx4 v[152:155], v[132:133], off
	v_lshl_add_u64 v[56:57], v[130:131], 0, s[36:37]
	v_lshl_add_u64 v[58:59], v[106:107], 0, s[36:37]
	s_cselect_b64 s[36:37], -1, 0
	s_and_b64 s[40:41], s[36:37], exec
	s_cselect_b32 s30, s34, s25
	s_mov_b32 s9, s31
	s_mov_b32 s11, s31
	s_mov_b32 s13, s31
	s_mov_b32 s15, s31
	s_mov_b32 s17, s31
	s_lshl_b64 s[40:41], s[30:31], 1
	s_mov_b32 s21, s31
	s_mov_b32 s23, s31
	global_load_dwordx4 v[68:71], v[56:57], off
	v_lshl_add_u64 v[56:57], v[58:59], 0, s[8:9]
	v_lshl_add_u64 v[60:61], v[58:59], 0, s[10:11]
	v_lshl_add_u64 v[62:63], v[58:59], 0, s[12:13]
	v_lshl_add_u64 v[64:65], v[58:59], 0, s[14:15]
	v_lshl_add_u64 v[66:67], v[58:59], 0, s[16:17]
	global_load_dwordx4 v[92:95], v[58:59], off
	global_load_dwordx4 v[88:91], v[56:57], off
	global_load_dwordx4 v[84:87], v[60:61], off
	global_load_dwordx4 v[80:83], v[62:63], off
	global_load_dwordx4 v[76:79], v[64:65], off
	global_load_dwordx4 v[72:75], v[66:67], off
	v_lshl_add_u64 v[96:97], v[58:59], 0, s[20:21]
	v_lshl_add_u64 v[100:101], v[58:59], 0, s[22:23]
	global_load_dwordx4 v[96:99], v[96:97], off
	s_nop 0
	global_load_dwordx4 v[100:103], v[100:101], off
	global_load_dwordx4 v[204:207], v[134:135], off offset:64
	v_lshl_add_u64 v[160:161], v[110:111], 0, s[26:27]
	global_load_dwordx4 v[172:175], v[160:161], off
	v_lshl_add_u64 v[162:163], v[124:125], 0, s[26:27]
	global_load_dwordx4 v[176:179], v[162:163], off
	v_lshl_add_u64 v[160:161], v[122:123], 0, s[26:27]
	global_load_dwordx4 v[180:183], v[160:161], off
	v_lshl_add_u64 v[162:163], v[120:121], 0, s[26:27]
	global_load_dwordx4 v[184:187], v[162:163], off
	v_lshl_add_u64 v[160:161], v[118:119], 0, s[26:27]
	global_load_dwordx4 v[188:191], v[160:161], off
	v_lshl_add_u64 v[162:163], v[116:117], 0, s[26:27]
	global_load_dwordx4 v[192:195], v[162:163], off
	v_lshl_add_u64 v[160:161], v[114:115], 0, s[26:27]
	global_load_dwordx4 v[196:199], v[160:161], off
	global_load_dwordx4 v[200:203], v[132:133], off offset:64
	s_cmp_ge_u32 s33, s19
	s_waitcnt vmcnt(9)
	v_mfma_f32_16x16x32_bf16 v[16:19], v[144:147], v[36:39], v[16:19]
	v_lshl_add_u64 v[36:37], v[106:107], 0, s[40:41]
	v_lshl_add_u64 v[38:39], v[36:37], 0, s[8:9]
	v_lshl_add_u64 v[156:157], v[36:37], 0, s[20:21]
	v_mfma_f32_16x16x32_bf16 v[20:23], v[144:147], v[32:35], v[20:23]
	v_lshl_add_u64 v[32:33], v[130:131], 0, s[40:41]
	global_load_dwordx4 v[32:35], v[32:33], off
	v_lshl_add_u64 v[158:159], v[36:37], 0, s[22:23]
	v_mfma_f32_16x16x32_bf16 v[12:15], v[144:147], v[40:43], v[12:15]
	v_lshl_add_u64 v[40:41], v[36:37], 0, s[10:11]
	v_lshl_add_u64 v[42:43], v[36:37], 0, s[12:13]
	global_load_dwordx4 v[64:67], v[36:37], off
	global_load_dwordx4 v[60:63], v[38:39], off
	v_mfma_f32_16x16x32_bf16 v[4:7], v[144:147], v[44:47], v[4:7]
	v_lshl_add_u64 v[44:45], v[36:37], 0, s[14:15]
	v_lshl_add_u64 v[46:47], v[36:37], 0, s[16:17]
	v_mfma_f32_16x16x32_bf16 v[24:27], v[144:147], v[52:55], v[24:27]
	global_load_dwordx4 v[56:59], v[40:41], off
	global_load_dwordx4 v[52:55], v[42:43], off
	s_nop 0
	global_load_dwordx4 v[40:43], v[44:45], off
	global_load_dwordx4 v[36:39], v[46:47], off
	v_mfma_f32_16x16x32_bf16 v[28:31], v[144:147], v[48:51], v[28:31]
	global_load_dwordx4 v[48:51], v[156:157], off
	global_load_dwordx4 v[44:47], v[158:159], off
	v_mfma_f32_16x16x32_bf16 v[8:11], v[144:147], v[148:151], v[8:11]
	v_mfma_f32_16x16x32_bf16 v[0:3], v[144:147], v[152:155], v[0:3]
	s_cbranch_scc1 .LBB0_1613
	s_waitcnt vmcnt(16)
	v_mfma_f32_16x16x32_bf16 v[8:11], v[204:207], v[172:175], v[8:11]
	s_waitcnt vmcnt(15)
	v_mfma_f32_16x16x32_bf16 v[28:31], v[204:207], v[176:179], v[28:31]
	s_waitcnt vmcnt(14)
	v_mfma_f32_16x16x32_bf16 v[24:27], v[204:207], v[180:183], v[24:27]
	s_waitcnt vmcnt(13)
	v_mfma_f32_16x16x32_bf16 v[20:23], v[204:207], v[184:187], v[20:23]
	s_waitcnt vmcnt(12)
	v_mfma_f32_16x16x32_bf16 v[16:19], v[204:207], v[188:191], v[16:19]
	s_waitcnt vmcnt(11)
	v_mfma_f32_16x16x32_bf16 v[12:15], v[204:207], v[192:195], v[12:15]
	s_waitcnt vmcnt(10)
	v_mfma_f32_16x16x32_bf16 v[4:7], v[204:207], v[196:199], v[4:7]
	s_waitcnt vmcnt(9)
	v_mfma_f32_16x16x32_bf16 v[0:3], v[204:207], v[200:203], v[0:3]
	s_andn2_b64 vcc, exec, s[38:39]
	s_cbranch_vccz .LBB0_1614
